# GEMM loops: LDS-DMA loads use SGPR base + 32-bit VGPR offset form (drops 12 of 16 v_lshl_add_u64 per iteration), on top of no-setprio
# speedup vs baseline: 1.0242x; 1.0130x over previous
.LBB0_87:
	s_add_u32 s16, s14, 0xfff80080
	s_addc_u32 s17, s15, -1
	s_add_i32 s43, 0, 0x10000
	v_add_u32_e32 v140, s43, v183
	ds_read_b128 v[128:131], v140
	ds_read_b128 v[132:135], v140 offset:1024
	ds_read_b128 v[136:139], v140 offset:2048
	ds_read_b128 v[140:143], v140 offset:3072
	s_cmp_eq_u32 s42, 28
	s_cselect_b32 s19, s7, s17
	s_cselect_b32 s18, s38, s16
	s_cselect_b32 s17, s5, s41
	s_cselect_b32 s16, s39, s40
	s_add_i32 m0, s28, 0xc000
	ds_read_b128 v[144:147], v185
	ds_read_b128 v[148:151], v185 offset:1024
	ds_read_b128 v[152:155], v185 offset:2048
	ds_read_b128 v[156:159], v185 offset:3072
	ds_read_b128 v[170:173], v185 offset:4096
	ds_read_b128 v[174:177], v185 offset:5120
	ds_read_b128 v[178:181], v185 offset:6144
	ds_read_b128 v[186:189], v185 offset:7168
	global_load_lds_dwordx4 v166, s[14:15]
	s_add_i32 m0, s28, 0xe000
	s_nop 0
	global_load_lds_dwordx4 v168, s[14:15]
	s_waitcnt lgkmcnt(8)
	s_barrier
	s_waitcnt lgkmcnt(0)
	s_waitcnt lgkmcnt(0)
	v_mfma_f32_16x16x32_bf16 v[124:127], v[128:131], v[144:147], v[124:127]
	v_mfma_f32_16x16x32_bf16 v[120:123], v[136:139], v[144:147], v[120:123]
	v_mfma_f32_16x16x32_bf16 v[108:111], v[128:131], v[152:155], v[108:111]
	v_mfma_f32_16x16x32_bf16 v[104:107], v[136:139], v[152:155], v[104:107]
	v_mfma_f32_16x16x32_bf16 v[92:95], v[128:131], v[170:173], v[92:95]
	v_mfma_f32_16x16x32_bf16 v[88:91], v[136:139], v[170:173], v[88:91]
	v_mfma_f32_16x16x32_bf16 v[76:79], v[128:131], v[178:181], v[76:79]
	v_mfma_f32_16x16x32_bf16 v[72:75], v[136:139], v[178:181], v[72:75]
	v_mfma_f32_16x16x32_bf16 v[124:127], v[132:135], v[148:151], v[124:127]
	v_mfma_f32_16x16x32_bf16 v[120:123], v[140:143], v[148:151], v[120:123]
	v_mfma_f32_16x16x32_bf16 v[108:111], v[132:135], v[156:159], v[108:111]
	v_mfma_f32_16x16x32_bf16 v[104:107], v[140:143], v[156:159], v[104:107]
	v_mfma_f32_16x16x32_bf16 v[92:95], v[132:135], v[174:177], v[92:95]
	v_mfma_f32_16x16x32_bf16 v[88:91], v[140:143], v[174:177], v[88:91]
	v_mfma_f32_16x16x32_bf16 v[76:79], v[132:135], v[186:189], v[76:79]
	v_mfma_f32_16x16x32_bf16 v[72:75], v[140:143], v[186:189], v[72:75]
	s_barrier
	s_add_i32 s46, 0, 0x14000
	v_add_u32_e32 v190, s46, v183
	s_add_i32 s43, s43, s27
	ds_read_b128 v[196:199], v190
	ds_read_b128 v[204:207], v190 offset:1024
	ds_read_b128 v[208:211], v190 offset:2048
	ds_read_b128 v[214:217], v190 offset:3072
	s_mov_b32 m0, s43
	s_nop 0
	global_load_lds_dwordx4 v192, s[16:17]
	s_add_i32 m0, s43, 0x2000
	s_nop 0
	global_load_lds_dwordx4 v164, s[16:17]
	s_barrier
	s_waitcnt lgkmcnt(0)
	s_waitcnt lgkmcnt(0)
	v_mfma_f32_16x16x32_bf16 v[116:119], v[196:199], v[144:147], v[116:119]
	v_mfma_f32_16x16x32_bf16 v[112:115], v[208:211], v[144:147], v[112:115]
	v_mfma_f32_16x16x32_bf16 v[100:103], v[196:199], v[152:155], v[100:103]
	v_mfma_f32_16x16x32_bf16 v[96:99], v[208:211], v[152:155], v[96:99]
	v_mfma_f32_16x16x32_bf16 v[84:87], v[196:199], v[170:173], v[84:87]
	v_mfma_f32_16x16x32_bf16 v[80:83], v[208:211], v[170:173], v[80:83]
	v_mfma_f32_16x16x32_bf16 v[68:71], v[196:199], v[178:181], v[68:71]
	v_mfma_f32_16x16x32_bf16 v[64:67], v[208:211], v[178:181], v[64:67]
	v_mfma_f32_16x16x32_bf16 v[116:119], v[204:207], v[148:151], v[116:119]
	v_mfma_f32_16x16x32_bf16 v[112:115], v[214:217], v[148:151], v[112:115]
	v_mfma_f32_16x16x32_bf16 v[100:103], v[204:207], v[156:159], v[100:103]
	v_mfma_f32_16x16x32_bf16 v[96:99], v[214:217], v[156:159], v[96:99]
	v_mfma_f32_16x16x32_bf16 v[84:87], v[204:207], v[174:177], v[84:87]
	v_mfma_f32_16x16x32_bf16 v[80:83], v[214:217], v[174:177], v[80:83]
	v_mfma_f32_16x16x32_bf16 v[68:71], v[204:207], v[186:189], v[68:71]
	v_mfma_f32_16x16x32_bf16 v[64:67], v[214:217], v[186:189], v[64:67]
	s_mov_b32 m0, s28
	v_lshl_add_u64 v[220:221], s[18:19], 0, v[160:161]
	s_barrier
	ds_read_b128 v[144:147], v185 offset:16384
	ds_read_b128 v[148:151], v185 offset:17408
	ds_read_b128 v[152:155], v185 offset:18432
	ds_read_b128 v[156:159], v185 offset:19456
	ds_read_b128 v[170:173], v185 offset:20480
	ds_read_b128 v[174:177], v185 offset:21504
	ds_read_b128 v[178:181], v185 offset:22528
	ds_read_b128 v[186:189], v185 offset:23552
	global_load_lds_dwordx4 v160, s[18:19]
	v_lshl_add_u64 v[222:223], s[18:19], 0, v[162:163]
	s_mov_b32 m0, s29
	s_nop 0
	global_load_lds_dwordx4 v162, s[18:19]
	s_barrier
	s_waitcnt lgkmcnt(0)
	s_waitcnt lgkmcnt(0)
	v_mfma_f32_16x16x32_bf16 v[60:63], v[128:131], v[144:147], v[60:63]
	v_mfma_f32_16x16x32_bf16 v[56:59], v[136:139], v[144:147], v[56:59]
	v_mfma_f32_16x16x32_bf16 v[44:47], v[128:131], v[152:155], v[44:47]
	v_mfma_f32_16x16x32_bf16 v[40:43], v[136:139], v[152:155], v[40:43]
	v_mfma_f32_16x16x32_bf16 v[28:31], v[128:131], v[170:173], v[28:31]
	v_mfma_f32_16x16x32_bf16 v[24:27], v[136:139], v[170:173], v[24:27]
	v_mfma_f32_16x16x32_bf16 v[12:15], v[128:131], v[178:181], v[12:15]
	v_mfma_f32_16x16x32_bf16 v[8:11], v[136:139], v[178:181], v[8:11]
	v_mfma_f32_16x16x32_bf16 v[60:63], v[132:135], v[148:151], v[60:63]
	v_mfma_f32_16x16x32_bf16 v[56:59], v[140:143], v[148:151], v[56:59]
	v_mfma_f32_16x16x32_bf16 v[44:47], v[132:135], v[156:159], v[44:47]
	v_mfma_f32_16x16x32_bf16 v[40:43], v[140:143], v[156:159], v[40:43]
	v_mfma_f32_16x16x32_bf16 v[28:31], v[132:135], v[174:177], v[28:31]
	v_mfma_f32_16x16x32_bf16 v[24:27], v[140:143], v[174:177], v[24:27]
	v_mfma_f32_16x16x32_bf16 v[12:15], v[132:135], v[186:189], v[12:15]
	v_mfma_f32_16x16x32_bf16 v[8:11], v[140:143], v[186:189], v[8:11]
	s_barrier
	s_add_u32 s44, s16, 0x80000
	s_addc_u32 s45, s17, 0
	s_add_i32 s43, s46, s27
	s_mov_b32 m0, s43
	s_nop 0
	global_load_lds_dwordx4 v192, s[44:45]
	s_add_i32 m0, s43, 0x2000
	s_nop 0
	global_load_lds_dwordx4 v164, s[44:45]
	s_waitcnt vmcnt(6)
	s_barrier
	v_mfma_f32_16x16x32_bf16 v[52:55], v[196:199], v[144:147], v[52:55]
	v_mfma_f32_16x16x32_bf16 v[48:51], v[208:211], v[144:147], v[48:51]
	v_mfma_f32_16x16x32_bf16 v[36:39], v[196:199], v[152:155], v[36:39]
	v_mfma_f32_16x16x32_bf16 v[32:35], v[208:211], v[152:155], v[32:35]
	v_mfma_f32_16x16x32_bf16 v[20:23], v[196:199], v[170:173], v[20:23]
	v_mfma_f32_16x16x32_bf16 v[16:19], v[208:211], v[170:173], v[16:19]
	v_mfma_f32_16x16x32_bf16 v[4:7], v[196:199], v[178:181], v[4:7]
	v_mfma_f32_16x16x32_bf16 v[0:3], v[208:211], v[178:181], v[0:3]
	v_mfma_f32_16x16x32_bf16 v[52:55], v[204:207], v[148:151], v[52:55]
	v_mfma_f32_16x16x32_bf16 v[48:51], v[214:217], v[148:151], v[48:51]
	v_mfma_f32_16x16x32_bf16 v[36:39], v[204:207], v[156:159], v[36:39]
	v_mfma_f32_16x16x32_bf16 v[32:35], v[214:217], v[156:159], v[32:35]
	v_mfma_f32_16x16x32_bf16 v[20:23], v[204:207], v[174:177], v[20:23]
	v_mfma_f32_16x16x32_bf16 v[16:19], v[214:217], v[174:177], v[16:19]
	v_mfma_f32_16x16x32_bf16 v[4:7], v[204:207], v[186:189], v[4:7]
	v_mfma_f32_16x16x32_bf16 v[0:3], v[214:217], v[186:189], v[0:3]
	s_add_i32 s43, 0, 0x18000
	v_add_u32_e32 v140, s43, v183
	s_barrier
	ds_read_b128 v[128:131], v140
	ds_read_b128 v[132:135], v140 offset:1024
	ds_read_b128 v[136:139], v140 offset:2048
	ds_read_b128 v[140:143], v140 offset:3072
	s_add_u32 s18, s18, 0x80000
	s_addc_u32 s19, s19, 0
	s_mov_b32 m0, s30
	ds_read_b128 v[144:147], v185 offset:32768
	ds_read_b128 v[148:151], v185 offset:33792
	ds_read_b128 v[152:155], v185 offset:34816
	ds_read_b128 v[156:159], v185 offset:35840
	ds_read_b128 v[170:173], v185 offset:36864
	ds_read_b128 v[174:177], v185 offset:37888
	ds_read_b128 v[178:181], v185 offset:38912
	ds_read_b128 v[186:189], v185 offset:39936
	global_load_lds_dwordx4 v160, s[18:19]
	s_mov_b32 m0, s31
	s_nop 0
	global_load_lds_dwordx4 v162, s[18:19]
	s_waitcnt lgkmcnt(8)
	s_barrier
	s_waitcnt lgkmcnt(0)
	s_waitcnt lgkmcnt(0)
	v_mfma_f32_16x16x32_bf16 v[124:127], v[128:131], v[144:147], v[124:127]
	v_mfma_f32_16x16x32_bf16 v[120:123], v[136:139], v[144:147], v[120:123]
	v_mfma_f32_16x16x32_bf16 v[108:111], v[128:131], v[152:155], v[108:111]
	v_mfma_f32_16x16x32_bf16 v[104:107], v[136:139], v[152:155], v[104:107]
	v_mfma_f32_16x16x32_bf16 v[92:95], v[128:131], v[170:173], v[92:95]
	v_mfma_f32_16x16x32_bf16 v[88:91], v[136:139], v[170:173], v[88:91]
	v_mfma_f32_16x16x32_bf16 v[76:79], v[128:131], v[178:181], v[76:79]
	v_mfma_f32_16x16x32_bf16 v[72:75], v[136:139], v[178:181], v[72:75]
	v_mfma_f32_16x16x32_bf16 v[124:127], v[132:135], v[148:151], v[124:127]
	v_mfma_f32_16x16x32_bf16 v[120:123], v[140:143], v[148:151], v[120:123]
	v_mfma_f32_16x16x32_bf16 v[108:111], v[132:135], v[156:159], v[108:111]
	v_mfma_f32_16x16x32_bf16 v[104:107], v[140:143], v[156:159], v[104:107]
	v_mfma_f32_16x16x32_bf16 v[92:95], v[132:135], v[174:177], v[92:95]
	v_mfma_f32_16x16x32_bf16 v[88:91], v[140:143], v[174:177], v[88:91]
	v_mfma_f32_16x16x32_bf16 v[76:79], v[132:135], v[186:189], v[76:79]
	v_mfma_f32_16x16x32_bf16 v[72:75], v[140:143], v[186:189], v[72:75]
	s_barrier
	s_add_i32 s18, 0, 0x1c000
	s_add_i32 s19, s43, s27
	v_add_u32_e32 v212, s18, v183
	s_add_i32 m0, s19, 0xffffff80
	ds_read_b128 v[196:199], v212
	ds_read_b128 v[204:207], v212 offset:1024
	ds_read_b128 v[208:211], v212 offset:2048
	ds_read_b128 v[214:217], v212 offset:3072
	global_load_lds_dwordx4 v192, s[16:17] offset:128
	s_add_i32 m0, s19, 0x1f80
	s_nop 0
	global_load_lds_dwordx4 v164, s[16:17] offset:128
	s_barrier
	s_waitcnt lgkmcnt(0)
	s_waitcnt lgkmcnt(0)
	v_mfma_f32_16x16x32_bf16 v[116:119], v[196:199], v[144:147], v[116:119]
	v_mfma_f32_16x16x32_bf16 v[112:115], v[208:211], v[144:147], v[112:115]
	v_mfma_f32_16x16x32_bf16 v[100:103], v[196:199], v[152:155], v[100:103]
	v_mfma_f32_16x16x32_bf16 v[96:99], v[208:211], v[152:155], v[96:99]
	v_mfma_f32_16x16x32_bf16 v[84:87], v[196:199], v[170:173], v[84:87]
	v_mfma_f32_16x16x32_bf16 v[80:83], v[208:211], v[170:173], v[80:83]
	v_mfma_f32_16x16x32_bf16 v[68:71], v[196:199], v[178:181], v[68:71]
	v_mfma_f32_16x16x32_bf16 v[64:67], v[208:211], v[178:181], v[64:67]
	v_mfma_f32_16x16x32_bf16 v[116:119], v[204:207], v[148:151], v[116:119]
	v_mfma_f32_16x16x32_bf16 v[112:115], v[214:217], v[148:151], v[112:115]
	v_mfma_f32_16x16x32_bf16 v[100:103], v[204:207], v[156:159], v[100:103]
	v_mfma_f32_16x16x32_bf16 v[96:99], v[214:217], v[156:159], v[96:99]
	v_mfma_f32_16x16x32_bf16 v[84:87], v[204:207], v[174:177], v[84:87]
	v_mfma_f32_16x16x32_bf16 v[80:83], v[214:217], v[174:177], v[80:83]
	v_mfma_f32_16x16x32_bf16 v[68:71], v[204:207], v[186:189], v[68:71]
	v_mfma_f32_16x16x32_bf16 v[64:67], v[214:217], v[186:189], v[64:67]
	s_mov_b32 m0, s35
	v_lshl_add_u64 v[190:191], v[220:221], 0, s[48:49]
	s_barrier
	ds_read_b128 v[144:147], v185 offset:49152
	ds_read_b128 v[148:151], v185 offset:50176
	ds_read_b128 v[152:155], v185 offset:51200
	ds_read_b128 v[156:159], v185 offset:52224
	ds_read_b128 v[170:173], v185 offset:53248
	ds_read_b128 v[174:177], v185 offset:54272
	ds_read_b128 v[178:181], v185 offset:55296
	ds_read_b128 v[186:189], v185 offset:56320
	global_load_lds_dwordx4 v[190:191], off
	v_lshl_add_u64 v[190:191], v[222:223], 0, s[48:49]
	s_mov_b32 m0, s36
	s_nop 0
	global_load_lds_dwordx4 v[190:191], off
	s_barrier
	s_waitcnt lgkmcnt(0)
	s_waitcnt lgkmcnt(0)
	v_mfma_f32_16x16x32_bf16 v[60:63], v[128:131], v[144:147], v[60:63]
	v_mfma_f32_16x16x32_bf16 v[56:59], v[136:139], v[144:147], v[56:59]
	v_mfma_f32_16x16x32_bf16 v[44:47], v[128:131], v[152:155], v[44:47]
	v_mfma_f32_16x16x32_bf16 v[40:43], v[136:139], v[152:155], v[40:43]
	v_mfma_f32_16x16x32_bf16 v[28:31], v[128:131], v[170:173], v[28:31]
	v_mfma_f32_16x16x32_bf16 v[24:27], v[136:139], v[170:173], v[24:27]
	v_mfma_f32_16x16x32_bf16 v[12:15], v[128:131], v[178:181], v[12:15]
	v_mfma_f32_16x16x32_bf16 v[8:11], v[136:139], v[178:181], v[8:11]
	v_mfma_f32_16x16x32_bf16 v[60:63], v[132:135], v[148:151], v[60:63]
	v_mfma_f32_16x16x32_bf16 v[56:59], v[140:143], v[148:151], v[56:59]
	v_mfma_f32_16x16x32_bf16 v[44:47], v[132:135], v[156:159], v[44:47]
	v_mfma_f32_16x16x32_bf16 v[40:43], v[140:143], v[156:159], v[40:43]
	v_mfma_f32_16x16x32_bf16 v[28:31], v[132:135], v[174:177], v[28:31]
	v_mfma_f32_16x16x32_bf16 v[24:27], v[140:143], v[174:177], v[24:27]
	v_mfma_f32_16x16x32_bf16 v[12:15], v[132:135], v[186:189], v[12:15]
	v_mfma_f32_16x16x32_bf16 v[8:11], v[140:143], v[186:189], v[8:11]
	s_barrier
	s_add_u32 s16, s16, 0x80080
	s_addc_u32 s17, s17, 0
	s_add_i32 s18, s18, s27
	s_mov_b32 m0, s18
	s_nop 0
	global_load_lds_dwordx4 v192, s[16:17]
	s_add_i32 m0, s18, 0x2000
	s_nop 0
	global_load_lds_dwordx4 v164, s[16:17]
	s_waitcnt vmcnt(6)
	s_barrier
	v_mfma_f32_16x16x32_bf16 v[52:55], v[196:199], v[144:147], v[52:55]
	v_mfma_f32_16x16x32_bf16 v[48:51], v[208:211], v[144:147], v[48:51]
	v_mfma_f32_16x16x32_bf16 v[36:39], v[196:199], v[152:155], v[36:39]
	v_mfma_f32_16x16x32_bf16 v[32:35], v[208:211], v[152:155], v[32:35]
	v_mfma_f32_16x16x32_bf16 v[20:23], v[196:199], v[170:173], v[20:23]
	v_mfma_f32_16x16x32_bf16 v[16:19], v[208:211], v[170:173], v[16:19]
	v_mfma_f32_16x16x32_bf16 v[4:7], v[196:199], v[178:181], v[4:7]
	v_mfma_f32_16x16x32_bf16 v[0:3], v[208:211], v[178:181], v[0:3]
	v_mfma_f32_16x16x32_bf16 v[52:55], v[204:207], v[148:151], v[52:55]
	v_mfma_f32_16x16x32_bf16 v[48:51], v[214:217], v[148:151], v[48:51]
	v_mfma_f32_16x16x32_bf16 v[36:39], v[204:207], v[156:159], v[36:39]
	v_mfma_f32_16x16x32_bf16 v[32:35], v[214:217], v[156:159], v[32:35]
	v_mfma_f32_16x16x32_bf16 v[20:23], v[204:207], v[174:177], v[20:23]
	v_mfma_f32_16x16x32_bf16 v[16:19], v[214:217], v[174:177], v[16:19]
	v_mfma_f32_16x16x32_bf16 v[4:7], v[204:207], v[186:189], v[4:7]
	v_mfma_f32_16x16x32_bf16 v[0:3], v[214:217], v[186:189], v[0:3]
	s_add_i32 s42, s42, 2
	s_add_u32 s14, s14, 0x100
	s_addc_u32 s15, s15, 0
	s_add_u32 s40, s40, 0x100
	s_addc_u32 s41, s41, 0
	s_cmp_gt_u32 s42, 29
	s_barrier
	s_cbranch_scc0 .LBB0_87
	v_lshl_or_b32 v128, s13, 8, v184
	v_lshl_add_u32 v172, s12, 8, v182
	v_ashrrev_i32_e32 v129, 31, v128
	v_lshlrev_b64 v[170:171], 1, v[128:129]
	v_ashrrev_i32_e32 v173, 31, v172
	v_lshl_add_u64 v[174:175], s[2:3], 0, v[170:171]
	v_lshlrev_b64 v[128:129], 13, v[172:173]
	v_lshl_add_u64 v[130:131], v[174:175], 0, v[128:129]
	global_load_dwordx4 v[186:189], v[130:131], off
	global_load_dwordx4 v[196:199], v[130:131], off offset:256
	s_lshl_b32 s5, s13, 1
	v_mul_f32_e32 v133, 0xbfb8aa3b, v124
	v_mul_f32_e32 v135, 0xbfb8aa3b, v125
	v_mul_f32_e32 v137, 0xbfb8aa3b, v126
	v_mul_f32_e32 v138, 0xbfb8aa3b, v127
	v_mul_f32_e32 v139, 0xbfb8aa3b, v120
	v_mul_f32_e32 v140, 0xbfb8aa3b, v121
	s_and_b32 s12, s5, -4
	v_or_b32_e32 v132, 16, v172
	v_or_b32_e32 v136, 48, v172
	v_exp_f32_e32 v148, v133
	v_exp_f32_e32 v149, v135
	v_exp_f32_e32 v150, v137
	v_exp_f32_e32 v151, v138
	v_exp_f32_e32 v204, v139
	v_exp_f32_e32 v205, v140
	s_ashr_i32 s13, s12, 31
	v_or_b32_e32 v134, 32, v172
	v_ashrrev_i32_e32 v133, 31, v132
	v_ashrrev_i32_e32 v137, 31, v136
	s_lshl_b64 s[12:13], s[12:13], 2
	v_mul_f32_e32 v141, 0xbfb8aa3b, v122
	v_ashrrev_i32_e32 v135, 31, v134
	v_lshlrev_b64 v[180:181], 13, v[132:133]
	v_lshlrev_b64 v[176:177], 13, v[136:137]
	s_add_u32 s12, s33, s12
	v_exp_f32_e32 v212, v141
	v_lshlrev_b64 v[138:139], 7, v[172:173]
	v_lshlrev_b64 v[140:141], 7, v[132:133]
	v_lshlrev_b64 v[142:143], 7, v[134:135]
	v_lshlrev_b64 v[178:179], 13, v[134:135]
	v_lshlrev_b64 v[144:145], 7, v[136:137]
	v_lshl_add_u64 v[128:129], s[2:3], 0, v[128:129]
	v_lshl_add_u64 v[130:131], v[174:175], 0, v[180:181]
	v_lshl_add_u64 v[136:137], v[174:175], 0, v[176:177]
	s_addc_u32 s13, s34, s13
	v_lshl_add_u64 v[146:147], v[174:175], 0, v[178:179]
	v_lshl_add_u64 v[190:191], v[128:129], 0, v[170:171]
	global_load_dwordx4 v[156:159], v[130:131], off
	global_load_dwordx4 v[152:155], v[130:131], off offset:256
	global_load_dwordx4 v[132:135], v[136:137], off
	s_nop 0
	global_load_dwordx4 v[128:131], v[136:137], off offset:256
	v_add_f32_e32 v148, 1.0, v148
	v_add_f32_e32 v149, 1.0, v149
	v_add_f32_e32 v150, 1.0, v150
	v_add_f32_e32 v151, 1.0, v151
	v_add_f32_e32 v173, 1.0, v204
	v_add_f32_e32 v204, 1.0, v205
	v_lshl_add_u64 v[136:137], s[12:13], 0, v[138:139]
	v_lshl_add_u64 v[138:139], s[12:13], 0, v[140:141]
	v_lshl_add_u64 v[140:141], s[12:13], 0, v[142:143]
	v_lshl_add_u64 v[144:145], s[12:13], 0, v[144:145]
	v_rcp_f32_e32 v214, v148
	v_rcp_f32_e32 v215, v149
	v_rcp_f32_e32 v216, v150
	v_rcp_f32_e32 v217, v151
	v_rcp_f32_e32 v218, v204
	global_load_dwordx4 v[204:207], v[136:137], off
	global_load_dwordx4 v[208:211], v[138:139], off
	s_nop 0
	global_load_dwordx4 v[136:139], v[140:141], off
	global_load_dwordx4 v[148:151], v[146:147], off
	s_nop 0
	global_load_dwordx4 v[140:143], v[146:147], off offset:256
	s_nop 0
	global_load_dwordx4 v[144:147], v[144:145], off
	v_rcp_f32_e32 v173, v173
	v_mul_f32_e32 v124, v124, v214
	v_mul_f32_e32 v125, v125, v215
	v_mul_f32_e32 v127, v127, v217
	v_mul_f32_e32 v120, v120, v173
	v_mul_f32_e32 v121, v121, v218
	s_mov_b32 s14, 0x358637bd
	s_mov_b32 s5, 0x800000
	v_mul_f32_e32 v126, v126, v216
	s_mov_b64 s[16:17], s[10:11]
	s_mov_b32 s11, 0xc000
	s_waitcnt vmcnt(0)
	v_lshlrev_b32_e32 v173, 16, v186
	v_and_b32_e32 v186, 0xffff0000, v186
	v_lshlrev_b32_e32 v214, 16, v187
	v_and_b32_e32 v187, 0xffff0000, v187
	v_mul_f32_e32 v125, v125, v186
	v_mul_f32_e32 v127, v127, v187
	v_add_f32_e32 v186, 1.0, v212
	v_mul_f32_e32 v187, 0xbfb8aa3b, v123
	v_rcp_f32_e32 v186, v186
	v_exp_f32_e32 v187, v187
	v_mul_f32_e32 v124, v124, v173
	v_and_b32_e32 v173, 0xffff0000, v188
	v_mul_f32_e32 v122, v122, v186
	v_add_f32_e32 v186, 1.0, v187
	v_mul_f32_e32 v187, 0xbfb8aa3b, v116
	v_rcp_f32_e32 v186, v186
	v_exp_f32_e32 v187, v187
	v_mul_f32_e32 v121, v121, v173
	v_lshlrev_b32_e32 v173, 16, v189
	v_mul_f32_e32 v123, v123, v186
	v_add_f32_e32 v186, 1.0, v187
	v_mul_f32_e32 v187, 0xbfb8aa3b, v117
	v_rcp_f32_e32 v186, v186
	v_exp_f32_e32 v187, v187
	v_mul_f32_e32 v122, v122, v173
	v_and_b32_e32 v173, 0xffff0000, v189
	v_mul_f32_e32 v116, v116, v186
	v_add_f32_e32 v186, 1.0, v187
	v_mul_f32_e32 v187, 0xbfb8aa3b, v118
	v_rcp_f32_e32 v186, v186
	v_exp_f32_e32 v187, v187
	v_mul_f32_e32 v123, v123, v173
	v_lshlrev_b32_e32 v173, 16, v196
	v_mul_f32_e32 v173, v116, v173
	v_mul_f32_e32 v116, v117, v186
	v_add_f32_e32 v186, 1.0, v187
	v_mul_f32_e32 v187, 0xbfb8aa3b, v119
	v_rcp_f32_e32 v186, v186
	v_exp_f32_e32 v187, v187
	v_and_b32_e32 v117, 0xffff0000, v196
	v_lshlrev_b32_e32 v215, 16, v188
	v_mul_f32_e32 v188, v116, v117
	v_mul_f32_e32 v116, v118, v186
	v_add_f32_e32 v118, 1.0, v187
	v_rcp_f32_e32 v118, v118
	v_mul_f32_e32 v186, 0xbfb8aa3b, v112
	v_exp_f32_e32 v186, v186
	v_lshlrev_b32_e32 v117, 16, v197
	v_mul_f32_e32 v187, v116, v117
	v_mul_f32_e32 v116, v119, v118
	v_mul_f32_e32 v119, 0xbfb8aa3b, v113
	v_add_f32_e32 v118, 1.0, v186
	v_exp_f32_e32 v119, v119
	v_rcp_f32_e32 v118, v118
	v_and_b32_e32 v117, 0xffff0000, v197
	v_mul_f32_e32 v186, v116, v117
	v_add_f32_e32 v117, 1.0, v119
	v_mul_f32_e32 v112, v112, v118
	v_rcp_f32_e32 v117, v117
	v_mul_f32_e32 v118, 0xbfb8aa3b, v114
	v_exp_f32_e32 v118, v118
	v_lshlrev_b32_e32 v116, 16, v198
	v_mul_f32_e32 v189, v112, v116
	v_mul_f32_e32 v112, v113, v117
	v_and_b32_e32 v113, 0xffff0000, v198
	v_add_f32_e32 v116, 1.0, v118
	v_mul_f32_e32 v196, v112, v113
	v_mul_f32_e32 v112, 0xbfb8aa3b, v115
	v_rcp_f32_e32 v116, v116
	v_exp_f32_e32 v112, v112
	v_mov_b32_e32 v117, v206
	v_mov_b32_e32 v206, v211
	v_mul_f32_e32 v113, v114, v116
	v_lshlrev_b32_e32 v114, 16, v199
	v_add_f32_e32 v112, 1.0, v112
	v_mul_f32_e32 v197, v113, v114
	v_rcp_f32_e32 v114, v112
	v_mov_b32_e32 v112, v208
	v_mov_b32_e32 v113, v204
	v_mov_b32_e32 v204, v209
	v_pk_add_f32 v[112:113], v[112:113], v[204:205]
	v_mov_b32_e32 v116, v210
	v_pk_add_f32 v[112:113], v[116:117], v[112:113]
	v_mul_f32_e32 v114, v115, v114
	v_pk_add_f32 v[116:117], v[206:207], v[112:113]
	v_mov_b64_e32 v[112:113], s[14:15]
	s_mov_b32 s14, 0x3b000000
	v_pk_fma_f32 v[118:119], v[116:117], s[14:15], v[112:113] op_sel_hi:[1,0,0]
	v_and_b32_e32 v115, 0xffff0000, v199
	v_mul_f32_e32 v116, 0x4b800000, v119
	v_cmp_gt_f32_e32 vcc, s5, v119
	v_mul_f32_e32 v126, v126, v214
	v_mul_f32_e32 v120, v120, v215
	v_cndmask_b32_e32 v116, v119, v116, vcc
	v_rsq_f32_e32 v116, v116
	v_mul_f32_e32 v119, v114, v115
	v_mul_f32_e32 v114, 0x45800000, v116
	v_cndmask_b32_e32 v198, v116, v114, vcc
	v_mul_f32_e32 v114, v124, v198
	v_mul_f32_e32 v115, v125, v198
	v_cvt_pk_bf16_f32 v114, v114, v115
	v_mul_f32_e32 v115, v126, v198
	v_mul_f32_e32 v116, v127, v198
	v_cvt_pk_bf16_f32 v115, v115, v116
	v_mul_f32_e32 v116, v120, v198
	v_mul_f32_e32 v117, v121, v198
	v_cvt_pk_bf16_f32 v116, v116, v117
	v_mul_f32_e32 v117, v122, v198
	v_mul_f32_e32 v120, v123, v198
	v_cvt_pk_bf16_f32 v117, v117, v120
	global_store_dwordx4 v[190:191], v[114:117], off
	v_mul_f32_e32 v119, v119, v198
	v_cmp_gt_f32_e32 vcc, s5, v118
	v_mul_f32_e32 v114, v173, v198
	v_mul_f32_e32 v115, v188, v198
	v_cvt_pk_bf16_f32 v114, v114, v115
	v_mul_f32_e32 v115, v187, v198
	v_mul_f32_e32 v116, v186, v198
	v_cvt_pk_bf16_f32 v115, v115, v116
	v_mul_f32_e32 v116, v189, v198
	v_mul_f32_e32 v117, v196, v198
	v_cvt_pk_bf16_f32 v116, v116, v117
	v_mul_f32_e32 v117, v197, v198
	v_cvt_pk_bf16_f32 v117, v117, v119
	v_mul_f32_e32 v119, 0x4b800000, v118
	v_cndmask_b32_e32 v118, v118, v119, vcc
	global_store_dwordx4 v[190:191], v[114:117], off offset:256
	v_rsq_f32_e32 v118, v118
	v_mul_f32_e32 v123, 0xbfb8aa3b, v61
	v_mul_f32_e32 v114, 0xbfb8aa3b, v108
	v_exp_f32_e32 v116, v114
	v_mul_f32_e32 v114, 0x45800000, v118
	v_cndmask_b32_e32 v117, v118, v114, vcc
	v_mul_f32_e32 v118, 0xbfb8aa3b, v109
	v_add_f32_e32 v116, 1.0, v116
	v_rcp_f32_e32 v116, v116
	v_exp_f32_e32 v118, v118
	v_lshl_add_u64 v[114:115], s[2:3], 0, v[180:181]
	v_lshl_add_u64 v[114:115], v[114:115], 0, v[170:171]
	v_mul_f32_e32 v108, v108, v116
	v_lshlrev_b32_e32 v116, 16, v156
	v_mul_f32_e32 v108, v108, v116
	v_add_f32_e32 v116, 1.0, v118
	v_rcp_f32_e32 v116, v116
	v_mul_f32_e32 v118, 0xbfb8aa3b, v110
	v_exp_f32_e32 v118, v118
	v_mul_f32_e32 v108, v108, v117
	v_mul_f32_e32 v109, v109, v116
	v_and_b32_e32 v116, 0xffff0000, v156
	v_mul_f32_e32 v109, v109, v116
	v_add_f32_e32 v116, 1.0, v118
	v_mul_f32_e32 v118, 0xbfb8aa3b, v111
	v_rcp_f32_e32 v116, v116
	v_exp_f32_e32 v118, v118
	v_mul_f32_e32 v109, v109, v117
	v_cvt_pk_bf16_f32 v108, v108, v109
	v_mul_f32_e32 v109, v110, v116
	v_add_f32_e32 v110, 1.0, v118
	v_rcp_f32_e32 v110, v110
	v_lshlrev_b32_e32 v116, 16, v157
	v_mul_f32_e32 v109, v109, v116
	v_and_b32_e32 v116, 0xffff0000, v157
	v_mul_f32_e32 v110, v111, v110
	v_mul_f32_e32 v111, 0xbfb8aa3b, v104
	v_exp_f32_e32 v111, v111
	v_mul_f32_e32 v110, v110, v116
	v_mul_f32_e32 v109, v109, v117
	v_mul_f32_e32 v110, v110, v117
	v_add_f32_e32 v111, 1.0, v111
	v_cvt_pk_bf16_f32 v109, v109, v110
	v_mul_f32_e32 v110, 0xbfb8aa3b, v105
	v_rcp_f32_e32 v111, v111
	v_exp_f32_e32 v110, v110
	v_exp_f32_e32 v123, v123
	v_mul_f32_e32 v124, 0xbfb8aa3b, v62
	v_mul_f32_e32 v104, v104, v111
	v_lshlrev_b32_e32 v111, 16, v158
	v_add_f32_e32 v110, 1.0, v110
	v_mul_f32_e32 v104, v104, v111
	v_rcp_f32_e32 v110, v110
	v_mul_f32_e32 v111, 0xbfb8aa3b, v106
	v_exp_f32_e32 v111, v111
	v_mul_f32_e32 v104, v104, v117
	v_mul_f32_e32 v105, v105, v110
	v_and_b32_e32 v110, 0xffff0000, v158
	v_mul_f32_e32 v105, v105, v110
	v_add_f32_e32 v110, 1.0, v111
	v_rcp_f32_e32 v111, v110
	v_mul_f32_e32 v110, 0xbfb8aa3b, v107
	v_exp_f32_e32 v116, v110
	v_mul_f32_e32 v105, v105, v117
	v_cvt_pk_bf16_f32 v110, v104, v105
	v_mul_f32_e32 v104, v106, v111
	v_add_f32_e32 v105, 1.0, v116
	v_rcp_f32_e32 v105, v105
	v_lshlrev_b32_e32 v106, 16, v159
	v_mul_f32_e32 v104, v104, v106
	v_and_b32_e32 v106, 0xffff0000, v159
	v_mul_f32_e32 v105, v107, v105
	v_mul_f32_e32 v107, 0xbfb8aa3b, v100
	v_exp_f32_e32 v107, v107
	v_mul_f32_e32 v104, v104, v117
	v_mul_f32_e32 v105, v105, v106
	v_mul_f32_e32 v105, v105, v117
	v_cvt_pk_bf16_f32 v111, v104, v105
	v_add_f32_e32 v104, 1.0, v107
	v_rcp_f32_e32 v104, v104
	v_mul_f32_e32 v105, 0xbfb8aa3b, v101
	v_exp_f32_e32 v105, v105
	global_store_dwordx4 v[114:115], v[108:111], off
	v_mul_f32_e32 v100, v100, v104
	v_lshlrev_b32_e32 v104, 16, v152
	v_mul_f32_e32 v100, v100, v104
	v_add_f32_e32 v104, 1.0, v105
	v_rcp_f32_e32 v104, v104
	v_mul_f32_e32 v105, 0xbfb8aa3b, v102
	v_exp_f32_e32 v105, v105
	v_mul_f32_e32 v100, v100, v117
	v_mul_f32_e32 v101, v101, v104
	v_and_b32_e32 v104, 0xffff0000, v152
	v_mul_f32_e32 v101, v101, v104
	v_add_f32_e32 v104, 1.0, v105
	v_mul_f32_e32 v105, 0xbfb8aa3b, v103
	v_rcp_f32_e32 v104, v104
	v_exp_f32_e32 v105, v105
	v_mul_f32_e32 v101, v101, v117
	v_cvt_pk_bf16_f32 v100, v100, v101
	v_mul_f32_e32 v101, v102, v104
	v_add_f32_e32 v102, 1.0, v105
	v_rcp_f32_e32 v102, v102
	v_lshlrev_b32_e32 v104, 16, v153
	v_mul_f32_e32 v101, v101, v104
	v_and_b32_e32 v104, 0xffff0000, v153
	v_mul_f32_e32 v102, v103, v102
	v_mul_f32_e32 v103, 0xbfb8aa3b, v96
	v_exp_f32_e32 v103, v103
	v_mul_f32_e32 v102, v102, v104
	v_mul_f32_e32 v101, v101, v117
	v_mul_f32_e32 v102, v102, v117
	v_add_f32_e32 v103, 1.0, v103
	v_cvt_pk_bf16_f32 v101, v101, v102
	v_mul_f32_e32 v102, 0xbfb8aa3b, v97
	v_rcp_f32_e32 v103, v103
	v_exp_f32_e32 v102, v102
	v_add_f32_e32 v123, 1.0, v123
	v_rcp_f32_e32 v123, v123
	v_mul_f32_e32 v96, v96, v103
	v_lshlrev_b32_e32 v103, 16, v154
	v_add_f32_e32 v102, 1.0, v102
	v_mul_f32_e32 v96, v96, v103
	v_rcp_f32_e32 v102, v102
	v_mul_f32_e32 v103, 0xbfb8aa3b, v98
	v_exp_f32_e32 v103, v103
	v_mul_f32_e32 v96, v96, v117
	v_mul_f32_e32 v97, v97, v102
	v_and_b32_e32 v102, 0xffff0000, v154
	v_mul_f32_e32 v97, v97, v102
	v_add_f32_e32 v102, 1.0, v103
	v_rcp_f32_e32 v103, v102
	v_mul_f32_e32 v102, 0xbfb8aa3b, v99
	v_exp_f32_e32 v104, v102
	v_mul_f32_e32 v97, v97, v117
	v_cvt_pk_bf16_f32 v102, v96, v97
	v_mul_f32_e32 v96, v98, v103
	v_add_f32_e32 v97, 1.0, v104
	v_rcp_f32_e32 v97, v97
	v_lshlrev_b32_e32 v98, 16, v155
	v_mul_f32_e32 v96, v96, v98
	v_and_b32_e32 v98, 0xffff0000, v155
	v_mul_f32_e32 v97, v99, v97
	v_mul_f32_e32 v99, 0xbfb8aa3b, v93
	v_exp_f32_e32 v99, v99
	v_mul_f32_e32 v97, v97, v98
	v_mul_f32_e32 v96, v96, v117
	v_mul_f32_e32 v97, v97, v117
	v_cvt_pk_bf16_f32 v103, v96, v97
	global_store_dwordx4 v[114:115], v[100:103], off offset:256
	v_add_f32_e32 v99, 1.0, v99
	v_rcp_f32_e32 v99, v99
	v_mul_f32_e32 v100, 0xbfb8aa3b, v94
	v_exp_f32_e32 v100, v100
	v_mul_f32_e32 v98, 0xbfb8aa3b, v92
	v_mul_f32_e32 v93, v93, v99
	v_exp_f32_e32 v98, v98
	v_add_f32_e32 v99, 1.0, v100
	v_mul_f32_e32 v100, 0xbfb8aa3b, v95
	v_rcp_f32_e32 v99, v99
	v_exp_f32_e32 v100, v100
	v_add_f32_e32 v98, 1.0, v98
	v_rcp_f32_e32 v98, v98
	v_mul_f32_e32 v94, v94, v99
	v_add_f32_e32 v99, 1.0, v100
	v_mul_f32_e32 v100, 0xbfb8aa3b, v88
	v_rcp_f32_e32 v99, v99
	v_exp_f32_e32 v100, v100
	v_mul_f32_e32 v92, v92, v98
	v_lshlrev_b32_e32 v98, 16, v148
	v_mul_f32_e32 v95, v95, v99
	v_add_f32_e32 v99, 1.0, v100
	v_mul_f32_e32 v100, 0xbfb8aa3b, v89
	v_rcp_f32_e32 v99, v99
	v_exp_f32_e32 v100, v100
	v_mul_f32_e32 v92, v92, v98
	v_and_b32_e32 v98, 0xffff0000, v148
	v_mul_f32_e32 v88, v88, v99
	v_add_f32_e32 v99, 1.0, v100
	v_mul_f32_e32 v100, 0xbfb8aa3b, v90
	v_rcp_f32_e32 v99, v99
	v_exp_f32_e32 v100, v100
	v_mul_f32_e32 v93, v93, v98
	v_lshlrev_b32_e32 v98, 16, v149
	v_mul_f32_e32 v89, v89, v99
	v_add_f32_e32 v99, 1.0, v100
	v_mul_f32_e32 v100, 0xbfb8aa3b, v91
	v_rcp_f32_e32 v99, v99
	v_exp_f32_e32 v100, v100
	v_mul_f32_e32 v94, v94, v98
	v_and_b32_e32 v98, 0xffff0000, v149
	v_mul_f32_e32 v90, v90, v99
	v_add_f32_e32 v99, 1.0, v100
	v_mul_f32_e32 v100, 0xbfb8aa3b, v84
	v_rcp_f32_e32 v99, v99
	v_exp_f32_e32 v100, v100
	v_mul_f32_e32 v95, v95, v98
	v_lshlrev_b32_e32 v98, 16, v150
	v_mul_f32_e32 v91, v91, v99
	v_add_f32_e32 v99, 1.0, v100
	v_mul_f32_e32 v100, 0xbfb8aa3b, v85
	v_rcp_f32_e32 v99, v99
	v_exp_f32_e32 v100, v100
	v_mul_f32_e32 v88, v88, v98
	v_and_b32_e32 v98, 0xffff0000, v150
	v_mul_f32_e32 v84, v84, v99
	v_add_f32_e32 v99, 1.0, v100
	v_mul_f32_e32 v100, 0xbfb8aa3b, v86
	v_rcp_f32_e32 v99, v99
	v_exp_f32_e32 v100, v100
	v_mul_f32_e32 v89, v89, v98
	v_lshlrev_b32_e32 v98, 16, v151
	v_mul_f32_e32 v90, v90, v98
	v_and_b32_e32 v98, 0xffff0000, v151
	v_mul_f32_e32 v91, v91, v98
	v_lshlrev_b32_e32 v98, 16, v140
	v_mul_f32_e32 v98, v84, v98
	v_mul_f32_e32 v84, v85, v99
	v_add_f32_e32 v99, 1.0, v100
	v_mul_f32_e32 v100, 0xbfb8aa3b, v87
	v_rcp_f32_e32 v99, v99
	v_exp_f32_e32 v100, v100
	v_and_b32_e32 v85, 0xffff0000, v140
	v_mul_f32_e32 v101, v84, v85
	v_mul_f32_e32 v84, v86, v99
	v_add_f32_e32 v86, 1.0, v100
	v_rcp_f32_e32 v86, v86
	v_mul_f32_e32 v99, 0xbfb8aa3b, v80
	v_exp_f32_e32 v99, v99
	v_lshlrev_b32_e32 v85, 16, v141
	v_mul_f32_e32 v100, v84, v85
	v_mul_f32_e32 v84, v87, v86
	v_mul_f32_e32 v87, 0xbfb8aa3b, v81
	v_add_f32_e32 v86, 1.0, v99
	v_exp_f32_e32 v87, v87
	v_rcp_f32_e32 v86, v86
	v_and_b32_e32 v85, 0xffff0000, v141
	v_mul_f32_e32 v99, v84, v85
	v_add_f32_e32 v85, 1.0, v87
	v_mul_f32_e32 v80, v80, v86
	v_rcp_f32_e32 v85, v85
	v_mul_f32_e32 v86, 0xbfb8aa3b, v82
	v_exp_f32_e32 v86, v86
	v_lshlrev_b32_e32 v84, 16, v142
	v_mul_f32_e32 v87, v80, v84
	v_mul_f32_e32 v80, v81, v85
	v_and_b32_e32 v81, 0xffff0000, v142
	v_add_f32_e32 v84, 1.0, v86
	v_mul_f32_e32 v86, v80, v81
	v_mul_f32_e32 v80, 0xbfb8aa3b, v83
	v_rcp_f32_e32 v84, v84
	v_exp_f32_e32 v80, v80
	v_mov_b32_e32 v85, v138
	v_mov_b32_e32 v138, v147
	v_mul_f32_e32 v81, v82, v84
	v_lshlrev_b32_e32 v82, 16, v143
	v_add_f32_e32 v80, 1.0, v80
	v_mul_f32_e32 v102, v81, v82
	v_rcp_f32_e32 v82, v80
	v_mov_b32_e32 v80, v144
	v_mov_b32_e32 v81, v136
	v_mov_b32_e32 v136, v145
	v_pk_add_f32 v[80:81], v[80:81], v[136:137]
	v_mov_b32_e32 v84, v146
	v_pk_add_f32 v[80:81], v[84:85], v[80:81]
	v_lshl_add_u64 v[96:97], s[2:3], 0, v[178:179]
	v_pk_add_f32 v[80:81], v[138:139], v[80:81]
	v_lshl_add_u64 v[96:97], v[96:97], 0, v[170:171]
	v_pk_fma_f32 v[84:85], v[80:81], s[14:15], v[112:113] op_sel_hi:[1,0,0]
	v_mul_f32_e32 v81, v83, v82
	v_mul_f32_e32 v80, 0x4b800000, v85
	v_cmp_gt_f32_e32 vcc, s5, v85
	v_and_b32_e32 v82, 0xffff0000, v143
	v_exp_f32_e32 v124, v124
	v_cndmask_b32_e32 v80, v85, v80, vcc
	v_rsq_f32_e32 v80, v80
	v_mul_f32_e32 v85, v81, v82
	v_mul_f32_e32 v61, v61, v123
	v_mul_f32_e32 v123, 0xbfb8aa3b, v63
	v_mul_f32_e32 v81, 0x45800000, v80
	v_cndmask_b32_e32 v103, v80, v81, vcc
	v_mul_f32_e32 v80, v92, v103
	v_mul_f32_e32 v81, v93, v103
	v_cvt_pk_bf16_f32 v80, v80, v81
	v_mul_f32_e32 v81, v94, v103
	v_mul_f32_e32 v82, v95, v103
	v_cvt_pk_bf16_f32 v81, v81, v82
	v_mul_f32_e32 v82, v88, v103
	v_mul_f32_e32 v83, v89, v103
	v_cvt_pk_bf16_f32 v82, v82, v83
	v_mul_f32_e32 v83, v90, v103
	v_mul_f32_e32 v88, v91, v103
	v_cvt_pk_bf16_f32 v83, v83, v88
	global_store_dwordx4 v[96:97], v[80:83], off
	v_mul_f32_e32 v85, v85, v103
	v_cmp_gt_f32_e32 vcc, s5, v84
	v_mul_f32_e32 v80, v98, v103
	v_mul_f32_e32 v81, v101, v103
	v_cvt_pk_bf16_f32 v80, v80, v81
	v_mul_f32_e32 v81, v100, v103
	v_mul_f32_e32 v82, v99, v103
	v_cvt_pk_bf16_f32 v81, v81, v82
	v_mul_f32_e32 v82, v87, v103
	v_mul_f32_e32 v83, v86, v103
	v_cvt_pk_bf16_f32 v82, v82, v83
	v_mul_f32_e32 v83, v102, v103
	v_cvt_pk_bf16_f32 v83, v83, v85
	v_mul_f32_e32 v85, 0x4b800000, v84
	v_cndmask_b32_e32 v84, v84, v85, vcc
	global_store_dwordx4 v[96:97], v[80:83], off offset:256
	v_rsq_f32_e32 v84, v84
	v_exp_f32_e32 v123, v123
	v_mul_f32_e32 v80, 0xbfb8aa3b, v76
	v_exp_f32_e32 v82, v80
	v_mul_f32_e32 v80, 0x45800000, v84
	v_cndmask_b32_e32 v83, v84, v80, vcc
	v_mul_f32_e32 v84, 0xbfb8aa3b, v77
	v_add_f32_e32 v82, 1.0, v82
	v_rcp_f32_e32 v82, v82
	v_exp_f32_e32 v84, v84
	v_lshl_add_u64 v[80:81], s[2:3], 0, v[176:177]
	v_lshl_add_u64 v[80:81], v[80:81], 0, v[170:171]
	v_mul_f32_e32 v76, v76, v82
	v_lshlrev_b32_e32 v82, 16, v132
	v_mul_f32_e32 v76, v76, v82
	v_add_f32_e32 v82, 1.0, v84
	v_rcp_f32_e32 v82, v82
	v_mul_f32_e32 v84, 0xbfb8aa3b, v78
	v_exp_f32_e32 v84, v84
	v_mul_f32_e32 v76, v76, v83
	v_mul_f32_e32 v77, v77, v82
	v_and_b32_e32 v82, 0xffff0000, v132
	v_mul_f32_e32 v77, v77, v82
	v_add_f32_e32 v82, 1.0, v84
	v_mul_f32_e32 v84, 0xbfb8aa3b, v79
	v_rcp_f32_e32 v82, v82
	v_exp_f32_e32 v84, v84
	v_mul_f32_e32 v77, v77, v83
	v_cvt_pk_bf16_f32 v76, v76, v77
	v_mul_f32_e32 v77, v78, v82
	v_add_f32_e32 v78, 1.0, v84
	v_rcp_f32_e32 v78, v78
	v_lshlrev_b32_e32 v82, 16, v133
	v_mul_f32_e32 v77, v77, v82
	v_and_b32_e32 v82, 0xffff0000, v133
	v_mul_f32_e32 v78, v79, v78
	v_mul_f32_e32 v79, 0xbfb8aa3b, v72
	v_exp_f32_e32 v79, v79
	v_mul_f32_e32 v78, v78, v82
	v_mul_f32_e32 v77, v77, v83
	v_mul_f32_e32 v78, v78, v83
	v_add_f32_e32 v79, 1.0, v79
	v_cvt_pk_bf16_f32 v77, v77, v78
	v_mul_f32_e32 v78, 0xbfb8aa3b, v73
	v_rcp_f32_e32 v79, v79
	v_exp_f32_e32 v78, v78
	v_mul_f32_e32 v72, v72, v79
	v_lshlrev_b32_e32 v79, 16, v134
	v_add_f32_e32 v78, 1.0, v78
	v_mul_f32_e32 v72, v72, v79
	v_rcp_f32_e32 v78, v78
	v_mul_f32_e32 v79, 0xbfb8aa3b, v74
	v_exp_f32_e32 v79, v79
	v_mul_f32_e32 v72, v72, v83
	v_mul_f32_e32 v73, v73, v78
	v_and_b32_e32 v78, 0xffff0000, v134
	v_mul_f32_e32 v73, v73, v78
	v_add_f32_e32 v78, 1.0, v79
	v_rcp_f32_e32 v79, v78
	v_mul_f32_e32 v78, 0xbfb8aa3b, v75
	v_exp_f32_e32 v82, v78
	v_mul_f32_e32 v73, v73, v83
	v_cvt_pk_bf16_f32 v78, v72, v73
	v_mul_f32_e32 v72, v74, v79
	v_add_f32_e32 v73, 1.0, v82
	v_rcp_f32_e32 v73, v73
	v_lshlrev_b32_e32 v74, 16, v135
	v_mul_f32_e32 v72, v72, v74
	v_and_b32_e32 v74, 0xffff0000, v135
	v_mul_f32_e32 v73, v75, v73
	v_mul_f32_e32 v75, 0xbfb8aa3b, v68
	v_exp_f32_e32 v75, v75
	v_mul_f32_e32 v72, v72, v83
	v_mul_f32_e32 v73, v73, v74
	v_mul_f32_e32 v73, v73, v83
	v_cvt_pk_bf16_f32 v79, v72, v73
	v_add_f32_e32 v72, 1.0, v75
	v_rcp_f32_e32 v72, v72
	v_mul_f32_e32 v73, 0xbfb8aa3b, v69
	v_exp_f32_e32 v73, v73
	global_store_dwordx4 v[80:81], v[76:79], off
	v_mul_f32_e32 v68, v68, v72
	v_lshlrev_b32_e32 v72, 16, v128
	v_mul_f32_e32 v68, v68, v72
	v_add_f32_e32 v72, 1.0, v73
	v_rcp_f32_e32 v72, v72
	v_mul_f32_e32 v73, 0xbfb8aa3b, v70
	v_exp_f32_e32 v73, v73
	v_mul_f32_e32 v68, v68, v83
	v_mul_f32_e32 v69, v69, v72
	v_and_b32_e32 v72, 0xffff0000, v128
	v_mul_f32_e32 v69, v69, v72
	v_add_f32_e32 v72, 1.0, v73
	v_mul_f32_e32 v73, 0xbfb8aa3b, v71
	v_rcp_f32_e32 v72, v72
	v_exp_f32_e32 v73, v73
	v_mul_f32_e32 v69, v69, v83
	v_cvt_pk_bf16_f32 v68, v68, v69
	v_mul_f32_e32 v69, v70, v72
	v_add_f32_e32 v70, 1.0, v73
	v_rcp_f32_e32 v70, v70
	v_lshlrev_b32_e32 v72, 16, v129
	v_mul_f32_e32 v69, v69, v72
	v_and_b32_e32 v72, 0xffff0000, v129
	v_mul_f32_e32 v70, v71, v70
	v_mul_f32_e32 v71, 0xbfb8aa3b, v64
	v_exp_f32_e32 v71, v71
	v_mul_f32_e32 v70, v70, v72
	v_mul_f32_e32 v69, v69, v83
	v_mul_f32_e32 v70, v70, v83
	v_add_f32_e32 v71, 1.0, v71
	v_cvt_pk_bf16_f32 v69, v69, v70
	v_mul_f32_e32 v70, 0xbfb8aa3b, v65
	v_rcp_f32_e32 v71, v71
	v_exp_f32_e32 v70, v70
	v_mul_f32_e32 v64, v64, v71
	v_lshlrev_b32_e32 v71, 16, v130
	v_add_f32_e32 v70, 1.0, v70
	v_mul_f32_e32 v64, v64, v71
	v_rcp_f32_e32 v70, v70
	v_mul_f32_e32 v71, 0xbfb8aa3b, v66
	v_exp_f32_e32 v71, v71
	v_mul_f32_e32 v64, v64, v83
	v_mul_f32_e32 v65, v65, v70
	v_and_b32_e32 v70, 0xffff0000, v130
	v_mul_f32_e32 v65, v65, v70
	v_add_f32_e32 v70, 1.0, v71
	v_rcp_f32_e32 v71, v70
	v_mul_f32_e32 v70, 0xbfb8aa3b, v67
	v_exp_f32_e32 v72, v70
	v_mul_f32_e32 v65, v65, v83
	v_cvt_pk_bf16_f32 v70, v64, v65
	v_mul_f32_e32 v64, v66, v71
	v_add_f32_e32 v65, 1.0, v72
	v_rcp_f32_e32 v65, v65
	v_lshlrev_b32_e32 v66, 16, v131
	v_mul_f32_e32 v64, v64, v66
	v_and_b32_e32 v66, 0xffff0000, v131
	v_mul_f32_e32 v65, v67, v65
	v_mul_f32_e32 v64, v64, v83
	v_mul_f32_e32 v65, v65, v66
	v_mul_f32_e32 v65, v65, v83
	v_cvt_pk_bf16_f32 v71, v64, v65
	v_add_u32_e32 v64, 0x80, v172
	v_ashrrev_i32_e32 v65, 31, v64
	v_lshlrev_b64 v[110:111], 13, v[64:65]
	v_lshl_add_u64 v[66:67], v[174:175], 0, v[110:111]
	global_load_dwordx4 v[102:105], v[66:67], off
	v_lshlrev_b64 v[64:65], 7, v[64:65]
	global_store_dwordx4 v[80:81], v[68:71], off offset:256
	v_lshl_add_u64 v[64:65], s[12:13], 0, v[64:65]
	global_load_dwordx4 v[106:109], v[64:65], off
	v_add_u32_e32 v64, 0x90, v172
	v_ashrrev_i32_e32 v65, 31, v64
	v_lshlrev_b64 v[68:69], 7, v[64:65]
	v_lshl_add_u64 v[68:69], s[12:13], 0, v[68:69]
	global_load_dwordx4 v[114:117], v[66:67], off offset:256
	global_load_dwordx4 v[118:121], v[68:69], off
	v_lshlrev_b64 v[100:101], 13, v[64:65]
	v_lshl_add_u64 v[64:65], v[174:175], 0, v[100:101]
	global_load_dwordx4 v[92:95], v[64:65], off
	global_load_dwordx4 v[88:91], v[64:65], off offset:256
	v_add_u32_e32 v64, 0xa0, v172
	v_ashrrev_i32_e32 v65, 31, v64
	v_lshlrev_b64 v[66:67], 7, v[64:65]
	v_lshl_add_u64 v[66:67], s[12:13], 0, v[66:67]
	v_lshlrev_b64 v[98:99], 13, v[64:65]
	v_lshl_add_u64 v[64:65], v[174:175], 0, v[98:99]
	global_load_dwordx4 v[72:75], v[66:67], off
	global_load_dwordx4 v[84:87], v[64:65], off
	v_add_u32_e32 v66, 0xb0, v172
	v_ashrrev_i32_e32 v67, 31, v66
	v_lshlrev_b64 v[68:69], 7, v[66:67]
	v_lshlrev_b64 v[96:97], 13, v[66:67]
	v_mul_f32_e32 v66, 0xbfb8aa3b, v60
	v_exp_f32_e32 v122, v66
	v_lshl_add_u64 v[68:69], s[12:13], 0, v[68:69]
	global_load_dwordx4 v[76:79], v[64:65], off offset:256
	global_load_dwordx4 v[80:83], v[68:69], off
	v_lshl_add_u64 v[64:65], v[174:175], 0, v[96:97]
	v_add_f32_e32 v122, 1.0, v122
	v_rcp_f32_e32 v122, v122
	global_load_dwordx4 v[68:71], v[64:65], off
	s_nop 0
	global_load_dwordx4 v[64:67], v[64:65], off offset:256
	v_lshl_add_u64 v[110:111], s[2:3], 0, v[110:111]
	v_lshl_add_u64 v[110:111], v[110:111], 0, v[170:171]
	v_mul_f32_e32 v60, v60, v122
	s_mov_b32 s13, s4
	s_mov_b32 s12, s6
	s_waitcnt vmcnt(0)
	v_lshlrev_b32_e32 v122, 16, v102
	v_mul_f32_e32 v60, v60, v122
	v_add_f32_e32 v122, 1.0, v124
	v_rcp_f32_e32 v122, v122
	v_and_b32_e32 v102, 0xffff0000, v102
	v_mul_f32_e32 v61, v61, v102
	v_lshlrev_b32_e32 v102, 16, v103
	v_mul_f32_e32 v62, v62, v122
	v_add_f32_e32 v122, 1.0, v123
	v_mul_f32_e32 v123, 0xbfb8aa3b, v56
	v_rcp_f32_e32 v122, v122
	v_exp_f32_e32 v123, v123
	v_mul_f32_e32 v62, v62, v102
	v_and_b32_e32 v102, 0xffff0000, v103
	v_mul_f32_e32 v63, v63, v122
	v_add_f32_e32 v103, 1.0, v123
	v_mul_f32_e32 v122, 0xbfb8aa3b, v57
	v_rcp_f32_e32 v103, v103
	v_exp_f32_e32 v122, v122
	v_mul_f32_e32 v63, v63, v102
	v_lshlrev_b32_e32 v102, 16, v104
	v_mul_f32_e32 v56, v56, v103
	v_add_f32_e32 v103, 1.0, v122
	v_mul_f32_e32 v122, 0xbfb8aa3b, v58
	v_rcp_f32_e32 v103, v103
	v_exp_f32_e32 v122, v122
	v_mul_f32_e32 v56, v56, v102
	v_and_b32_e32 v102, 0xffff0000, v104
	v_mul_f32_e32 v57, v57, v103
	v_add_f32_e32 v103, 1.0, v122
	v_mul_f32_e32 v104, 0xbfb8aa3b, v59
	v_rcp_f32_e32 v103, v103
	v_exp_f32_e32 v104, v104
	v_mul_f32_e32 v57, v57, v102
	v_lshlrev_b32_e32 v102, 16, v105
	v_mul_f32_e32 v58, v58, v103
	v_add_f32_e32 v103, 1.0, v104
	v_mul_f32_e32 v104, 0xbfb8aa3b, v52
	v_rcp_f32_e32 v103, v103
	v_exp_f32_e32 v104, v104
	v_mul_f32_e32 v58, v58, v102
	v_and_b32_e32 v102, 0xffff0000, v105
	v_mul_f32_e32 v59, v59, v103
	v_add_f32_e32 v103, 1.0, v104
	v_mul_f32_e32 v104, 0xbfb8aa3b, v53
	v_rcp_f32_e32 v103, v103
	v_exp_f32_e32 v104, v104
	v_mul_f32_e32 v59, v59, v102
	v_lshlrev_b32_e32 v102, 16, v114
	v_mul_f32_e32 v52, v52, v103
	v_add_f32_e32 v103, 1.0, v104
	v_mul_f32_e32 v104, 0xbfb8aa3b, v54
	v_rcp_f32_e32 v103, v103
	v_exp_f32_e32 v104, v104
	v_mul_f32_e32 v102, v52, v102
	v_mul_f32_e32 v52, v53, v103
	v_add_f32_e32 v103, 1.0, v104
	v_mul_f32_e32 v104, 0xbfb8aa3b, v55
	v_rcp_f32_e32 v103, v103
	v_exp_f32_e32 v104, v104
	v_and_b32_e32 v53, 0xffff0000, v114
	v_mul_f32_e32 v105, v52, v53
	v_mul_f32_e32 v52, v54, v103
	v_add_f32_e32 v54, 1.0, v104
	v_rcp_f32_e32 v54, v54
	v_mul_f32_e32 v103, 0xbfb8aa3b, v48
	v_exp_f32_e32 v103, v103
	v_lshlrev_b32_e32 v53, 16, v115
	v_mul_f32_e32 v104, v52, v53
	v_mul_f32_e32 v52, v55, v54
	v_mul_f32_e32 v55, 0xbfb8aa3b, v49
	v_add_f32_e32 v54, 1.0, v103
	v_exp_f32_e32 v55, v55
	v_rcp_f32_e32 v54, v54
	v_and_b32_e32 v53, 0xffff0000, v115
	v_mul_f32_e32 v103, v52, v53
	v_add_f32_e32 v53, 1.0, v55
	v_mul_f32_e32 v48, v48, v54
	v_rcp_f32_e32 v53, v53
	v_mul_f32_e32 v54, 0xbfb8aa3b, v50
	v_exp_f32_e32 v54, v54
	v_lshlrev_b32_e32 v52, 16, v116
	v_mul_f32_e32 v55, v48, v52
	v_mul_f32_e32 v48, v49, v53
	v_and_b32_e32 v49, 0xffff0000, v116
	v_add_f32_e32 v52, 1.0, v54
	v_mul_f32_e32 v54, v48, v49
	v_mul_f32_e32 v48, 0xbfb8aa3b, v51
	v_rcp_f32_e32 v52, v52
	v_exp_f32_e32 v48, v48
	v_mov_b32_e32 v53, v108
	v_mov_b32_e32 v108, v121
	v_mul_f32_e32 v49, v50, v52
	v_lshlrev_b32_e32 v50, 16, v117
	v_add_f32_e32 v48, 1.0, v48
	v_mul_f32_e32 v114, v49, v50
	v_rcp_f32_e32 v50, v48
	v_mov_b32_e32 v48, v118
	v_mov_b32_e32 v49, v106
	v_mov_b32_e32 v106, v119
	v_pk_add_f32 v[48:49], v[48:49], v[106:107]
	v_mov_b32_e32 v52, v120
	v_pk_add_f32 v[48:49], v[52:53], v[48:49]
	s_nop 0
	v_pk_add_f32 v[48:49], v[108:109], v[48:49]
	s_nop 0
	v_pk_fma_f32 v[52:53], v[48:49], s[14:15], v[112:113] op_sel_hi:[1,0,0]
	v_mul_f32_e32 v49, v51, v50
	v_mul_f32_e32 v48, 0x4b800000, v53
	v_cmp_gt_f32_e32 vcc, s5, v53
	v_and_b32_e32 v50, 0xffff0000, v117
	s_nop 0
	v_cndmask_b32_e32 v48, v53, v48, vcc
	v_rsq_f32_e32 v48, v48
	v_mul_f32_e32 v53, v49, v50
	v_mul_f32_e32 v49, 0x45800000, v48
	v_cndmask_b32_e32 v106, v48, v49, vcc
	v_mul_f32_e32 v48, v60, v106
	v_mul_f32_e32 v49, v61, v106
	v_cvt_pk_bf16_f32 v48, v48, v49
	v_mul_f32_e32 v49, v62, v106
	v_mul_f32_e32 v50, v63, v106
	v_cvt_pk_bf16_f32 v49, v49, v50
	v_mul_f32_e32 v50, v56, v106
	v_mul_f32_e32 v51, v57, v106
	v_cvt_pk_bf16_f32 v50, v50, v51
	v_mul_f32_e32 v51, v58, v106
	v_mul_f32_e32 v56, v59, v106
	v_cvt_pk_bf16_f32 v51, v51, v56
	global_store_dwordx4 v[110:111], v[48:51], off
	v_mul_f32_e32 v53, v53, v106
	v_cmp_gt_f32_e32 vcc, s5, v52
	v_mul_f32_e32 v48, v102, v106
	v_mul_f32_e32 v49, v105, v106
	v_cvt_pk_bf16_f32 v48, v48, v49
	v_mul_f32_e32 v49, v104, v106
	v_mul_f32_e32 v50, v103, v106
	v_cvt_pk_bf16_f32 v49, v49, v50
	v_mul_f32_e32 v50, v55, v106
	v_mul_f32_e32 v51, v54, v106
	v_cvt_pk_bf16_f32 v50, v50, v51
	v_mul_f32_e32 v51, v114, v106
	v_cvt_pk_bf16_f32 v51, v51, v53
	v_mul_f32_e32 v53, 0x4b800000, v52
	v_cndmask_b32_e32 v52, v52, v53, vcc
	global_store_dwordx4 v[110:111], v[48:51], off offset:256
	v_rsq_f32_e32 v52, v52
	s_nop 0
	v_mul_f32_e32 v48, 0xbfb8aa3b, v44
	v_exp_f32_e32 v50, v48
	v_mul_f32_e32 v48, 0x45800000, v52
	v_cndmask_b32_e32 v51, v52, v48, vcc
	v_mul_f32_e32 v52, 0xbfb8aa3b, v45
	v_add_f32_e32 v50, 1.0, v50
	v_rcp_f32_e32 v50, v50
	v_exp_f32_e32 v52, v52
	v_lshl_add_u64 v[48:49], s[2:3], 0, v[100:101]
	v_lshl_add_u64 v[48:49], v[48:49], 0, v[170:171]
	v_mul_f32_e32 v44, v44, v50
	v_lshlrev_b32_e32 v50, 16, v92
	v_mul_f32_e32 v44, v44, v50
	v_add_f32_e32 v50, 1.0, v52
	v_rcp_f32_e32 v50, v50
	v_mul_f32_e32 v52, 0xbfb8aa3b, v46
	v_exp_f32_e32 v52, v52
	v_mul_f32_e32 v44, v44, v51
	v_mul_f32_e32 v45, v45, v50
	v_and_b32_e32 v50, 0xffff0000, v92
	v_mul_f32_e32 v45, v45, v50
	v_add_f32_e32 v50, 1.0, v52
	v_mul_f32_e32 v52, 0xbfb8aa3b, v47
	v_rcp_f32_e32 v50, v50
	v_exp_f32_e32 v52, v52
	v_mul_f32_e32 v45, v45, v51
	v_cvt_pk_bf16_f32 v44, v44, v45
	v_mul_f32_e32 v45, v46, v50
	v_add_f32_e32 v46, 1.0, v52
	v_rcp_f32_e32 v46, v46
	v_lshlrev_b32_e32 v50, 16, v93
	v_mul_f32_e32 v45, v45, v50
	v_and_b32_e32 v50, 0xffff0000, v93
	v_mul_f32_e32 v46, v47, v46
	v_mul_f32_e32 v47, 0xbfb8aa3b, v40
	v_exp_f32_e32 v47, v47
	v_mul_f32_e32 v46, v46, v50
	v_mul_f32_e32 v45, v45, v51
	v_mul_f32_e32 v46, v46, v51
	v_add_f32_e32 v47, 1.0, v47
	v_cvt_pk_bf16_f32 v45, v45, v46
	v_mul_f32_e32 v46, 0xbfb8aa3b, v41
	v_rcp_f32_e32 v47, v47
	v_exp_f32_e32 v46, v46
	v_mul_f32_e32 v40, v40, v47
	v_lshlrev_b32_e32 v47, 16, v94
	v_add_f32_e32 v46, 1.0, v46
	v_mul_f32_e32 v40, v40, v47
	v_rcp_f32_e32 v46, v46
	v_mul_f32_e32 v47, 0xbfb8aa3b, v42
	v_exp_f32_e32 v47, v47
	v_mul_f32_e32 v40, v40, v51
	v_mul_f32_e32 v41, v41, v46
	v_and_b32_e32 v46, 0xffff0000, v94
	v_mul_f32_e32 v41, v41, v46
	v_add_f32_e32 v46, 1.0, v47
	v_rcp_f32_e32 v47, v46
	v_mul_f32_e32 v46, 0xbfb8aa3b, v43
	v_exp_f32_e32 v50, v46
	v_mul_f32_e32 v41, v41, v51
	v_cvt_pk_bf16_f32 v46, v40, v41
	v_mul_f32_e32 v40, v42, v47
	v_add_f32_e32 v41, 1.0, v50
	v_rcp_f32_e32 v41, v41
	v_lshlrev_b32_e32 v42, 16, v95
	v_mul_f32_e32 v40, v40, v42
	v_and_b32_e32 v42, 0xffff0000, v95
	v_mul_f32_e32 v41, v43, v41
	v_mul_f32_e32 v43, 0xbfb8aa3b, v36
	v_exp_f32_e32 v43, v43
	v_mul_f32_e32 v40, v40, v51
	v_mul_f32_e32 v41, v41, v42
	v_mul_f32_e32 v41, v41, v51
	v_cvt_pk_bf16_f32 v47, v40, v41
	v_add_f32_e32 v40, 1.0, v43
	v_rcp_f32_e32 v40, v40
	v_mul_f32_e32 v41, 0xbfb8aa3b, v37
	v_exp_f32_e32 v41, v41
	global_store_dwordx4 v[48:49], v[44:47], off
	v_mul_f32_e32 v36, v36, v40
	v_lshlrev_b32_e32 v40, 16, v88
	v_mul_f32_e32 v36, v36, v40
	v_add_f32_e32 v40, 1.0, v41
	v_rcp_f32_e32 v40, v40
	v_mul_f32_e32 v41, 0xbfb8aa3b, v38
	v_exp_f32_e32 v41, v41
	v_mul_f32_e32 v36, v36, v51
	v_mul_f32_e32 v37, v37, v40
	v_and_b32_e32 v40, 0xffff0000, v88
	v_mul_f32_e32 v37, v37, v40
	v_add_f32_e32 v40, 1.0, v41
	v_mul_f32_e32 v41, 0xbfb8aa3b, v39
	v_rcp_f32_e32 v40, v40
	v_exp_f32_e32 v41, v41
	v_mul_f32_e32 v37, v37, v51
	v_cvt_pk_bf16_f32 v36, v36, v37
	v_mul_f32_e32 v37, v38, v40
	v_add_f32_e32 v38, 1.0, v41
	v_rcp_f32_e32 v38, v38
	v_lshlrev_b32_e32 v40, 16, v89
	v_mul_f32_e32 v37, v37, v40
	v_and_b32_e32 v40, 0xffff0000, v89
	v_mul_f32_e32 v38, v39, v38
	v_mul_f32_e32 v39, 0xbfb8aa3b, v32
	v_exp_f32_e32 v39, v39
	v_mul_f32_e32 v38, v38, v40
	v_mul_f32_e32 v37, v37, v51
	v_mul_f32_e32 v38, v38, v51
	v_add_f32_e32 v39, 1.0, v39
	v_cvt_pk_bf16_f32 v37, v37, v38
	v_mul_f32_e32 v38, 0xbfb8aa3b, v33
	v_rcp_f32_e32 v39, v39
	v_exp_f32_e32 v38, v38
	v_mul_f32_e32 v32, v32, v39
	v_lshlrev_b32_e32 v39, 16, v90
	v_add_f32_e32 v38, 1.0, v38
	v_mul_f32_e32 v32, v32, v39
	v_rcp_f32_e32 v38, v38
	v_mul_f32_e32 v39, 0xbfb8aa3b, v34
	v_exp_f32_e32 v39, v39
	v_mul_f32_e32 v32, v32, v51
	v_mul_f32_e32 v33, v33, v38
	v_and_b32_e32 v38, 0xffff0000, v90
	v_mul_f32_e32 v33, v33, v38
	v_add_f32_e32 v38, 1.0, v39
	v_rcp_f32_e32 v39, v38
	v_mul_f32_e32 v38, 0xbfb8aa3b, v35
	v_exp_f32_e32 v40, v38
	v_mul_f32_e32 v33, v33, v51
	v_cvt_pk_bf16_f32 v38, v32, v33
	v_mul_f32_e32 v32, v34, v39
	v_add_f32_e32 v33, 1.0, v40
	v_rcp_f32_e32 v33, v33
	v_lshlrev_b32_e32 v34, 16, v91
	v_mul_f32_e32 v32, v32, v34
	v_and_b32_e32 v34, 0xffff0000, v91
	v_mul_f32_e32 v33, v35, v33
	v_mul_f32_e32 v35, 0xbfb8aa3b, v29
	v_exp_f32_e32 v35, v35
	v_mul_f32_e32 v33, v33, v34
	v_mul_f32_e32 v32, v32, v51
	v_mul_f32_e32 v33, v33, v51
	v_cvt_pk_bf16_f32 v39, v32, v33
	global_store_dwordx4 v[48:49], v[36:39], off offset:256
	v_add_f32_e32 v35, 1.0, v35
	v_rcp_f32_e32 v35, v35
	v_mul_f32_e32 v36, 0xbfb8aa3b, v30
	v_exp_f32_e32 v36, v36
	v_mul_f32_e32 v34, 0xbfb8aa3b, v28
	v_mul_f32_e32 v29, v29, v35
	v_exp_f32_e32 v34, v34
	v_add_f32_e32 v35, 1.0, v36
	v_mul_f32_e32 v36, 0xbfb8aa3b, v31
	v_rcp_f32_e32 v35, v35
	v_exp_f32_e32 v36, v36
	v_add_f32_e32 v34, 1.0, v34
	v_rcp_f32_e32 v34, v34
	v_mul_f32_e32 v30, v30, v35
	v_add_f32_e32 v35, 1.0, v36
	v_mul_f32_e32 v36, 0xbfb8aa3b, v24
	v_rcp_f32_e32 v35, v35
	v_exp_f32_e32 v36, v36
	v_mul_f32_e32 v28, v28, v34
	v_lshlrev_b32_e32 v34, 16, v84
	v_mul_f32_e32 v31, v31, v35
	v_add_f32_e32 v35, 1.0, v36
	v_mul_f32_e32 v36, 0xbfb8aa3b, v25
	v_rcp_f32_e32 v35, v35
	v_exp_f32_e32 v36, v36
	v_mul_f32_e32 v28, v28, v34
	v_and_b32_e32 v34, 0xffff0000, v84
	v_mul_f32_e32 v24, v24, v35
	v_add_f32_e32 v35, 1.0, v36
	v_mul_f32_e32 v36, 0xbfb8aa3b, v26
	v_rcp_f32_e32 v35, v35
	v_exp_f32_e32 v36, v36
	v_mul_f32_e32 v29, v29, v34
	v_lshlrev_b32_e32 v34, 16, v85
	v_mul_f32_e32 v25, v25, v35
	v_add_f32_e32 v35, 1.0, v36
	v_mul_f32_e32 v36, 0xbfb8aa3b, v27
	v_rcp_f32_e32 v35, v35
	v_exp_f32_e32 v36, v36
	v_mul_f32_e32 v30, v30, v34
	v_and_b32_e32 v34, 0xffff0000, v85
	v_mul_f32_e32 v26, v26, v35
	v_add_f32_e32 v35, 1.0, v36
	v_mul_f32_e32 v36, 0xbfb8aa3b, v20
	v_rcp_f32_e32 v35, v35
	v_exp_f32_e32 v36, v36
	v_mul_f32_e32 v31, v31, v34
	v_lshlrev_b32_e32 v34, 16, v86
	v_mul_f32_e32 v27, v27, v35
	v_add_f32_e32 v35, 1.0, v36
	v_mul_f32_e32 v36, 0xbfb8aa3b, v21
	v_rcp_f32_e32 v35, v35
	v_exp_f32_e32 v36, v36
	v_mul_f32_e32 v24, v24, v34
	v_and_b32_e32 v34, 0xffff0000, v86
	v_mul_f32_e32 v20, v20, v35
	v_add_f32_e32 v35, 1.0, v36
	v_mul_f32_e32 v36, 0xbfb8aa3b, v22
	v_rcp_f32_e32 v35, v35
	v_exp_f32_e32 v36, v36
	v_mul_f32_e32 v25, v25, v34
	v_lshlrev_b32_e32 v34, 16, v87
	v_mul_f32_e32 v26, v26, v34
	v_and_b32_e32 v34, 0xffff0000, v87
	v_mul_f32_e32 v27, v27, v34
	v_lshlrev_b32_e32 v34, 16, v76
	v_mul_f32_e32 v34, v20, v34
	v_mul_f32_e32 v20, v21, v35
	v_add_f32_e32 v35, 1.0, v36
	v_mul_f32_e32 v36, 0xbfb8aa3b, v23
	v_rcp_f32_e32 v35, v35
	v_exp_f32_e32 v36, v36
	v_and_b32_e32 v21, 0xffff0000, v76
	v_mul_f32_e32 v37, v20, v21
	v_mul_f32_e32 v20, v22, v35
	v_add_f32_e32 v22, 1.0, v36
	v_rcp_f32_e32 v22, v22
	v_mul_f32_e32 v35, 0xbfb8aa3b, v16
	v_exp_f32_e32 v35, v35
	v_lshlrev_b32_e32 v21, 16, v77
	v_mul_f32_e32 v36, v20, v21
	v_mul_f32_e32 v20, v23, v22
	v_mul_f32_e32 v23, 0xbfb8aa3b, v17
	v_add_f32_e32 v22, 1.0, v35
	v_exp_f32_e32 v23, v23
	v_rcp_f32_e32 v22, v22
	v_and_b32_e32 v21, 0xffff0000, v77
	v_mul_f32_e32 v35, v20, v21
	v_add_f32_e32 v21, 1.0, v23
	v_mul_f32_e32 v16, v16, v22
	v_rcp_f32_e32 v21, v21
	v_mul_f32_e32 v22, 0xbfb8aa3b, v18
	v_exp_f32_e32 v22, v22
	v_lshlrev_b32_e32 v20, 16, v78
	v_mul_f32_e32 v23, v16, v20
	v_mul_f32_e32 v16, v17, v21
	v_and_b32_e32 v17, 0xffff0000, v78
	v_add_f32_e32 v20, 1.0, v22
	v_mul_f32_e32 v22, v16, v17
	v_mul_f32_e32 v16, 0xbfb8aa3b, v19
	v_rcp_f32_e32 v20, v20
	v_exp_f32_e32 v16, v16
	v_mov_b32_e32 v21, v74
	v_mov_b32_e32 v74, v83
	v_mul_f32_e32 v17, v18, v20
	v_lshlrev_b32_e32 v18, 16, v79
	v_add_f32_e32 v16, 1.0, v16
	v_mul_f32_e32 v38, v17, v18
	v_rcp_f32_e32 v18, v16
	v_mov_b32_e32 v16, v80
	v_mov_b32_e32 v17, v72
	v_mov_b32_e32 v72, v81
	v_pk_add_f32 v[16:17], v[16:17], v[72:73]
	v_mov_b32_e32 v20, v82
	v_pk_add_f32 v[16:17], v[20:21], v[16:17]
	v_lshl_add_u64 v[32:33], s[2:3], 0, v[98:99]
	v_pk_add_f32 v[16:17], v[74:75], v[16:17]
	v_lshl_add_u64 v[32:33], v[32:33], 0, v[170:171]
	v_pk_fma_f32 v[20:21], v[16:17], s[14:15], v[112:113] op_sel_hi:[1,0,0]
	v_mul_f32_e32 v17, v19, v18
	v_mul_f32_e32 v16, 0x4b800000, v21
	v_cmp_gt_f32_e32 vcc, s5, v21
	v_and_b32_e32 v18, 0xffff0000, v79
	s_mov_b64 s[14:15], s[8:9]
	v_cndmask_b32_e32 v16, v21, v16, vcc
	v_rsq_f32_e32 v16, v16
	v_mul_f32_e32 v21, v17, v18
	v_mul_f32_e32 v17, 0x45800000, v16
	v_cndmask_b32_e32 v39, v16, v17, vcc
	v_mul_f32_e32 v16, v28, v39
	v_mul_f32_e32 v17, v29, v39
	v_cvt_pk_bf16_f32 v16, v16, v17
	v_mul_f32_e32 v17, v30, v39
	v_mul_f32_e32 v18, v31, v39
	v_cvt_pk_bf16_f32 v17, v17, v18
	v_mul_f32_e32 v18, v24, v39
	v_mul_f32_e32 v19, v25, v39
	v_cvt_pk_bf16_f32 v18, v18, v19
	v_mul_f32_e32 v19, v26, v39
	v_mul_f32_e32 v24, v27, v39
	v_cvt_pk_bf16_f32 v19, v19, v24
	global_store_dwordx4 v[32:33], v[16:19], off
	v_mul_f32_e32 v21, v21, v39
	v_cmp_gt_f32_e32 vcc, s5, v20
	v_mul_f32_e32 v16, v34, v39
	v_mul_f32_e32 v17, v37, v39
	v_cvt_pk_bf16_f32 v16, v16, v17
	v_mul_f32_e32 v17, v36, v39
	v_mul_f32_e32 v18, v35, v39
	v_cvt_pk_bf16_f32 v17, v17, v18
	v_mul_f32_e32 v18, v23, v39
	v_mul_f32_e32 v19, v22, v39
	v_cvt_pk_bf16_f32 v18, v18, v19
	v_mul_f32_e32 v19, v38, v39
	v_cvt_pk_bf16_f32 v19, v19, v21
	v_mul_f32_e32 v21, 0x4b800000, v20
	v_cndmask_b32_e32 v20, v20, v21, vcc
	global_store_dwordx4 v[32:33], v[16:19], off offset:256
	v_rsq_f32_e32 v20, v20
	s_nop 0
	v_mul_f32_e32 v16, 0xbfb8aa3b, v12
	v_exp_f32_e32 v18, v16
	v_mul_f32_e32 v16, 0x45800000, v20
	v_cndmask_b32_e32 v19, v20, v16, vcc
	v_mul_f32_e32 v20, 0xbfb8aa3b, v13
	v_add_f32_e32 v18, 1.0, v18
	v_rcp_f32_e32 v18, v18
	v_exp_f32_e32 v20, v20
	v_lshl_add_u64 v[16:17], s[2:3], 0, v[96:97]
	v_lshl_add_u64 v[16:17], v[16:17], 0, v[170:171]
	v_mul_f32_e32 v12, v12, v18
	v_lshlrev_b32_e32 v18, 16, v68
	v_mul_f32_e32 v12, v12, v18
	v_add_f32_e32 v18, 1.0, v20
	v_rcp_f32_e32 v18, v18
	v_mul_f32_e32 v20, 0xbfb8aa3b, v14
	v_exp_f32_e32 v20, v20
	v_mul_f32_e32 v12, v12, v19
	v_mul_f32_e32 v13, v13, v18
	v_and_b32_e32 v18, 0xffff0000, v68
	v_mul_f32_e32 v13, v13, v18
	v_add_f32_e32 v18, 1.0, v20
	v_mul_f32_e32 v20, 0xbfb8aa3b, v15
	v_rcp_f32_e32 v18, v18
	v_exp_f32_e32 v20, v20
	v_mul_f32_e32 v13, v13, v19
	v_cvt_pk_bf16_f32 v12, v12, v13
	v_mul_f32_e32 v13, v14, v18
	v_add_f32_e32 v14, 1.0, v20
	v_rcp_f32_e32 v14, v14
	v_lshlrev_b32_e32 v18, 16, v69
	v_mul_f32_e32 v13, v13, v18
	v_and_b32_e32 v18, 0xffff0000, v69
	v_mul_f32_e32 v14, v15, v14
	v_mul_f32_e32 v15, 0xbfb8aa3b, v8
	v_exp_f32_e32 v15, v15
	v_mul_f32_e32 v14, v14, v18
	v_mul_f32_e32 v13, v13, v19
	v_mul_f32_e32 v14, v14, v19
	v_add_f32_e32 v15, 1.0, v15
	v_cvt_pk_bf16_f32 v13, v13, v14
	v_mul_f32_e32 v14, 0xbfb8aa3b, v9
	v_rcp_f32_e32 v15, v15
	v_exp_f32_e32 v14, v14
	s_and_b64 vcc, exec, s[0:1]
	v_mul_f32_e32 v8, v8, v15
	v_lshlrev_b32_e32 v15, 16, v70
	v_add_f32_e32 v14, 1.0, v14
	v_mul_f32_e32 v8, v8, v15
	v_rcp_f32_e32 v14, v14
	v_mul_f32_e32 v15, 0xbfb8aa3b, v10
	v_exp_f32_e32 v15, v15
	v_mul_f32_e32 v8, v8, v19
	v_mul_f32_e32 v9, v9, v14
	v_and_b32_e32 v14, 0xffff0000, v70
	v_mul_f32_e32 v9, v9, v14
	v_add_f32_e32 v14, 1.0, v15
	v_rcp_f32_e32 v15, v14
	v_mul_f32_e32 v14, 0xbfb8aa3b, v11
	v_exp_f32_e32 v18, v14
	v_mul_f32_e32 v9, v9, v19
	v_cvt_pk_bf16_f32 v14, v8, v9
	v_mul_f32_e32 v8, v10, v15
	v_add_f32_e32 v9, 1.0, v18
	v_rcp_f32_e32 v9, v9
	v_lshlrev_b32_e32 v10, 16, v71
	v_mul_f32_e32 v8, v8, v10
	v_and_b32_e32 v10, 0xffff0000, v71
	v_mul_f32_e32 v9, v11, v9
	v_mul_f32_e32 v11, 0xbfb8aa3b, v4
	v_exp_f32_e32 v11, v11
	v_mul_f32_e32 v8, v8, v19
	v_mul_f32_e32 v9, v9, v10
	v_mul_f32_e32 v9, v9, v19
	v_cvt_pk_bf16_f32 v15, v8, v9
	v_add_f32_e32 v8, 1.0, v11
	v_rcp_f32_e32 v8, v8
	v_mul_f32_e32 v9, 0xbfb8aa3b, v5
	v_exp_f32_e32 v9, v9
	global_store_dwordx4 v[16:17], v[12:15], off
	v_mul_f32_e32 v4, v4, v8
	v_lshlrev_b32_e32 v8, 16, v64
	v_mul_f32_e32 v4, v4, v8
	v_add_f32_e32 v8, 1.0, v9
	v_rcp_f32_e32 v8, v8
	v_mul_f32_e32 v9, 0xbfb8aa3b, v6
	v_exp_f32_e32 v9, v9
	v_mul_f32_e32 v4, v4, v19
	v_mul_f32_e32 v5, v5, v8
	v_and_b32_e32 v8, 0xffff0000, v64
	v_mul_f32_e32 v5, v5, v8
	v_add_f32_e32 v8, 1.0, v9
	v_mul_f32_e32 v9, 0xbfb8aa3b, v7
	v_rcp_f32_e32 v8, v8
	v_exp_f32_e32 v9, v9
	v_mul_f32_e32 v5, v5, v19
	v_cvt_pk_bf16_f32 v4, v4, v5
	v_mul_f32_e32 v5, v6, v8
	v_add_f32_e32 v6, 1.0, v9
	v_rcp_f32_e32 v6, v6
	v_lshlrev_b32_e32 v8, 16, v65
	v_mul_f32_e32 v5, v5, v8
	v_and_b32_e32 v8, 0xffff0000, v65
	v_mul_f32_e32 v6, v7, v6
	v_mul_f32_e32 v7, 0xbfb8aa3b, v0
	v_exp_f32_e32 v7, v7
	v_mul_f32_e32 v6, v6, v8
	v_mul_f32_e32 v5, v5, v19
	v_mul_f32_e32 v6, v6, v19
	v_add_f32_e32 v7, 1.0, v7
	v_cvt_pk_bf16_f32 v5, v5, v6
	v_mul_f32_e32 v6, 0xbfb8aa3b, v1
	v_rcp_f32_e32 v7, v7
	v_exp_f32_e32 v6, v6
	v_mul_f32_e32 v0, v0, v7
	v_lshlrev_b32_e32 v7, 16, v66
	v_add_f32_e32 v6, 1.0, v6
	v_mul_f32_e32 v0, v0, v7
	v_rcp_f32_e32 v6, v6
	v_mul_f32_e32 v7, 0xbfb8aa3b, v2
	v_exp_f32_e32 v7, v7
	v_mul_f32_e32 v0, v0, v19
	v_mul_f32_e32 v1, v1, v6
	v_and_b32_e32 v6, 0xffff0000, v66
	v_mul_f32_e32 v1, v1, v6
	v_add_f32_e32 v6, 1.0, v7
	v_rcp_f32_e32 v7, v6
	v_mul_f32_e32 v6, 0xbfb8aa3b, v3
	v_exp_f32_e32 v8, v6
	v_mul_f32_e32 v1, v1, v19
	v_cvt_pk_bf16_f32 v6, v0, v1
	v_mul_f32_e32 v0, v2, v7
	v_add_f32_e32 v1, 1.0, v8
	v_rcp_f32_e32 v1, v1
	v_lshlrev_b32_e32 v2, 16, v67
	v_mul_f32_e32 v0, v0, v2
	v_and_b32_e32 v2, 0xffff0000, v67
	v_mul_f32_e32 v1, v3, v1
	v_mul_f32_e32 v1, v1, v2
	v_mul_f32_e32 v0, v0, v19
	v_mul_f32_e32 v1, v1, v19
	v_cvt_pk_bf16_f32 v7, v0, v1
	global_store_dwordx4 v[16:17], v[4:7], off offset:256
	s_cbranch_vccz .LBB0_80
	s_waitcnt vmcnt(0)
	s_cmpk_gt_u32 s21, 0xff
	s_cbranch_scc1 .LBB0_91
	s_barrier

.LBB0_200:
	s_add_u32 s16, s14, 0xfff80080
	s_addc_u32 s17, s15, -1
	s_add_i32 s41, 0, 0x10000
	v_add_u32_e32 v140, s41, v238
	ds_read_b128 v[128:131], v140
	ds_read_b128 v[132:135], v140 offset:1024
	ds_read_b128 v[136:139], v140 offset:2048
	ds_read_b128 v[140:143], v140 offset:3072
	s_cmp_eq_u32 s40, 28
	s_cselect_b32 s19, s5, s17
	s_cselect_b32 s18, s9, s16
	s_cselect_b32 s17, s7, s39
	s_cselect_b32 s16, s37, s38
	s_add_i32 m0, s28, 0xc000
	ds_read_b128 v[144:147], v240
	ds_read_b128 v[148:151], v240 offset:1024
	ds_read_b128 v[152:155], v240 offset:2048
	ds_read_b128 v[156:159], v240 offset:3072
	ds_read_b128 v[160:163], v240 offset:4096
	ds_read_b128 v[164:167], v240 offset:5120
	ds_read_b128 v[168:171], v240 offset:6144
	ds_read_b128 v[172:175], v240 offset:7168
	global_load_lds_dwordx4 v218, s[14:15]
	s_add_i32 m0, s28, 0xe000
	s_nop 0
	global_load_lds_dwordx4 v220, s[14:15]
	s_waitcnt lgkmcnt(8)
	s_barrier
	s_waitcnt lgkmcnt(0)
	s_waitcnt lgkmcnt(0)
	v_mfma_f32_16x16x32_bf16 v[124:127], v[128:131], v[144:147], v[124:127]
	v_mfma_f32_16x16x32_bf16 v[120:123], v[136:139], v[144:147], v[120:123]
	v_mfma_f32_16x16x32_bf16 v[116:119], v[128:131], v[152:155], v[116:119]
	v_mfma_f32_16x16x32_bf16 v[108:111], v[136:139], v[152:155], v[108:111]
	v_mfma_f32_16x16x32_bf16 v[100:103], v[128:131], v[160:163], v[100:103]
	v_mfma_f32_16x16x32_bf16 v[92:95], v[136:139], v[160:163], v[92:95]
	v_mfma_f32_16x16x32_bf16 v[84:87], v[128:131], v[168:171], v[84:87]
	v_mfma_f32_16x16x32_bf16 v[76:79], v[136:139], v[168:171], v[76:79]
	v_mfma_f32_16x16x32_bf16 v[124:127], v[132:135], v[148:151], v[124:127]
	v_mfma_f32_16x16x32_bf16 v[120:123], v[140:143], v[148:151], v[120:123]
	v_mfma_f32_16x16x32_bf16 v[116:119], v[132:135], v[156:159], v[116:119]
	v_mfma_f32_16x16x32_bf16 v[108:111], v[140:143], v[156:159], v[108:111]
	v_mfma_f32_16x16x32_bf16 v[100:103], v[132:135], v[164:167], v[100:103]
	v_mfma_f32_16x16x32_bf16 v[92:95], v[140:143], v[164:167], v[92:95]
	v_mfma_f32_16x16x32_bf16 v[84:87], v[132:135], v[172:175], v[84:87]
	v_mfma_f32_16x16x32_bf16 v[76:79], v[140:143], v[172:175], v[76:79]
	s_barrier
	s_add_i32 s44, 0, 0x14000
	s_add_i32 s41, s41, s27
	v_add_u32_e32 v188, s44, v238
	s_mov_b32 m0, s41
	ds_read_b128 v[176:179], v188
	ds_read_b128 v[180:183], v188 offset:1024
	ds_read_b128 v[184:187], v188 offset:2048
	ds_read_b128 v[188:191], v188 offset:3072
	global_load_lds_dwordx4 v206, s[16:17]
	s_add_i32 m0, s41, 0x2000
	s_nop 0
	global_load_lds_dwordx4 v210, s[16:17]
	s_barrier
	s_waitcnt lgkmcnt(0)
	s_waitcnt lgkmcnt(0)
	v_mfma_f32_16x16x32_bf16 v[112:115], v[176:179], v[144:147], v[112:115]
	v_mfma_f32_16x16x32_bf16 v[104:107], v[184:187], v[144:147], v[104:107]
	v_mfma_f32_16x16x32_bf16 v[96:99], v[176:179], v[152:155], v[96:99]
	v_mfma_f32_16x16x32_bf16 v[88:91], v[184:187], v[152:155], v[88:91]
	v_mfma_f32_16x16x32_bf16 v[80:83], v[176:179], v[160:163], v[80:83]
	v_mfma_f32_16x16x32_bf16 v[72:75], v[184:187], v[160:163], v[72:75]
	v_mfma_f32_16x16x32_bf16 v[68:71], v[176:179], v[168:171], v[68:71]
	v_mfma_f32_16x16x32_bf16 v[64:67], v[184:187], v[168:171], v[64:67]
	v_mfma_f32_16x16x32_bf16 v[112:115], v[180:183], v[148:151], v[112:115]
	v_mfma_f32_16x16x32_bf16 v[104:107], v[188:191], v[148:151], v[104:107]
	v_mfma_f32_16x16x32_bf16 v[96:99], v[180:183], v[156:159], v[96:99]
	v_mfma_f32_16x16x32_bf16 v[88:91], v[188:191], v[156:159], v[88:91]
	v_mfma_f32_16x16x32_bf16 v[80:83], v[180:183], v[164:167], v[80:83]
	v_mfma_f32_16x16x32_bf16 v[72:75], v[188:191], v[164:167], v[72:75]
	v_mfma_f32_16x16x32_bf16 v[68:71], v[180:183], v[172:175], v[68:71]
	v_mfma_f32_16x16x32_bf16 v[64:67], v[188:191], v[172:175], v[64:67]
	s_mov_b32 m0, s28
	v_lshl_add_u64 v[222:223], s[18:19], 0, v[204:205]
	s_barrier
	ds_read_b128 v[144:147], v240 offset:16384
	ds_read_b128 v[148:151], v240 offset:17408
	ds_read_b128 v[152:155], v240 offset:18432
	ds_read_b128 v[156:159], v240 offset:19456
	ds_read_b128 v[160:163], v240 offset:20480
	ds_read_b128 v[164:167], v240 offset:21504
	ds_read_b128 v[168:171], v240 offset:22528
	ds_read_b128 v[172:175], v240 offset:23552
	global_load_lds_dwordx4 v204, s[18:19]
	v_lshl_add_u64 v[224:225], s[18:19], 0, v[208:209]
	s_mov_b32 m0, s29
	s_nop 0
	global_load_lds_dwordx4 v208, s[18:19]
	s_barrier
	s_waitcnt lgkmcnt(0)
	s_waitcnt lgkmcnt(0)
	v_mfma_f32_16x16x32_bf16 v[60:63], v[128:131], v[144:147], v[60:63]
	v_mfma_f32_16x16x32_bf16 v[56:59], v[136:139], v[144:147], v[56:59]
	v_mfma_f32_16x16x32_bf16 v[52:55], v[128:131], v[152:155], v[52:55]
	v_mfma_f32_16x16x32_bf16 v[44:47], v[136:139], v[152:155], v[44:47]
	v_mfma_f32_16x16x32_bf16 v[36:39], v[128:131], v[160:163], v[36:39]
	v_mfma_f32_16x16x32_bf16 v[28:31], v[136:139], v[160:163], v[28:31]
	v_mfma_f32_16x16x32_bf16 v[20:23], v[128:131], v[168:171], v[20:23]
	v_mfma_f32_16x16x32_bf16 v[12:15], v[136:139], v[168:171], v[12:15]
	v_mfma_f32_16x16x32_bf16 v[60:63], v[132:135], v[148:151], v[60:63]
	v_mfma_f32_16x16x32_bf16 v[56:59], v[140:143], v[148:151], v[56:59]
	v_mfma_f32_16x16x32_bf16 v[52:55], v[132:135], v[156:159], v[52:55]
	v_mfma_f32_16x16x32_bf16 v[44:47], v[140:143], v[156:159], v[44:47]
	v_mfma_f32_16x16x32_bf16 v[36:39], v[132:135], v[164:167], v[36:39]
	v_mfma_f32_16x16x32_bf16 v[28:31], v[140:143], v[164:167], v[28:31]
	v_mfma_f32_16x16x32_bf16 v[20:23], v[132:135], v[172:175], v[20:23]
	v_mfma_f32_16x16x32_bf16 v[12:15], v[140:143], v[172:175], v[12:15]
	s_barrier
	s_add_u32 s42, s16, 0x80000
	s_addc_u32 s43, s17, 0
	s_add_i32 s41, s44, s27
	s_mov_b32 m0, s41
	s_nop 0
	global_load_lds_dwordx4 v206, s[42:43]
	s_add_i32 m0, s41, 0x2000
	s_nop 0
	global_load_lds_dwordx4 v210, s[42:43]
	s_waitcnt vmcnt(6)
	s_barrier
	v_mfma_f32_16x16x32_bf16 v[48:51], v[176:179], v[144:147], v[48:51]
	v_mfma_f32_16x16x32_bf16 v[40:43], v[184:187], v[144:147], v[40:43]
	v_mfma_f32_16x16x32_bf16 v[32:35], v[176:179], v[152:155], v[32:35]
	v_mfma_f32_16x16x32_bf16 v[24:27], v[184:187], v[152:155], v[24:27]
	v_mfma_f32_16x16x32_bf16 v[16:19], v[176:179], v[160:163], v[16:19]
	v_mfma_f32_16x16x32_bf16 v[8:11], v[184:187], v[160:163], v[8:11]
	v_mfma_f32_16x16x32_bf16 v[4:7], v[176:179], v[168:171], v[4:7]
	v_mfma_f32_16x16x32_bf16 v[0:3], v[184:187], v[168:171], v[0:3]
	v_mfma_f32_16x16x32_bf16 v[48:51], v[180:183], v[148:151], v[48:51]
	v_mfma_f32_16x16x32_bf16 v[40:43], v[188:191], v[148:151], v[40:43]
	v_mfma_f32_16x16x32_bf16 v[32:35], v[180:183], v[156:159], v[32:35]
	v_mfma_f32_16x16x32_bf16 v[24:27], v[188:191], v[156:159], v[24:27]
	v_mfma_f32_16x16x32_bf16 v[16:19], v[180:183], v[164:167], v[16:19]
	v_mfma_f32_16x16x32_bf16 v[8:11], v[188:191], v[164:167], v[8:11]
	v_mfma_f32_16x16x32_bf16 v[4:7], v[180:183], v[172:175], v[4:7]
	v_mfma_f32_16x16x32_bf16 v[0:3], v[188:191], v[172:175], v[0:3]
	s_add_i32 s41, 0, 0x18000
	v_add_u32_e32 v140, s41, v238
	s_barrier
	ds_read_b128 v[128:131], v140
	ds_read_b128 v[132:135], v140 offset:1024
	ds_read_b128 v[136:139], v140 offset:2048
	ds_read_b128 v[140:143], v140 offset:3072
	s_add_u32 s18, s18, 0x80000
	s_addc_u32 s19, s19, 0
	s_mov_b32 m0, s30
	ds_read_b128 v[144:147], v240 offset:32768
	ds_read_b128 v[148:151], v240 offset:33792
	ds_read_b128 v[152:155], v240 offset:34816
	ds_read_b128 v[156:159], v240 offset:35840
	ds_read_b128 v[160:163], v240 offset:36864
	ds_read_b128 v[164:167], v240 offset:37888
	ds_read_b128 v[168:171], v240 offset:38912
	ds_read_b128 v[172:175], v240 offset:39936
	global_load_lds_dwordx4 v204, s[18:19]
	s_mov_b32 m0, s31
	s_nop 0
	global_load_lds_dwordx4 v208, s[18:19]
	s_waitcnt lgkmcnt(8)
	s_barrier
	s_waitcnt lgkmcnt(0)
	s_waitcnt lgkmcnt(0)
	v_mfma_f32_16x16x32_bf16 v[124:127], v[128:131], v[144:147], v[124:127]
	v_mfma_f32_16x16x32_bf16 v[120:123], v[136:139], v[144:147], v[120:123]
	v_mfma_f32_16x16x32_bf16 v[116:119], v[128:131], v[152:155], v[116:119]
	v_mfma_f32_16x16x32_bf16 v[108:111], v[136:139], v[152:155], v[108:111]
	v_mfma_f32_16x16x32_bf16 v[100:103], v[128:131], v[160:163], v[100:103]
	v_mfma_f32_16x16x32_bf16 v[92:95], v[136:139], v[160:163], v[92:95]
	v_mfma_f32_16x16x32_bf16 v[84:87], v[128:131], v[168:171], v[84:87]
	v_mfma_f32_16x16x32_bf16 v[76:79], v[136:139], v[168:171], v[76:79]
	v_mfma_f32_16x16x32_bf16 v[124:127], v[132:135], v[148:151], v[124:127]
	v_mfma_f32_16x16x32_bf16 v[120:123], v[140:143], v[148:151], v[120:123]
	v_mfma_f32_16x16x32_bf16 v[116:119], v[132:135], v[156:159], v[116:119]
	v_mfma_f32_16x16x32_bf16 v[108:111], v[140:143], v[156:159], v[108:111]
	v_mfma_f32_16x16x32_bf16 v[100:103], v[132:135], v[164:167], v[100:103]
	v_mfma_f32_16x16x32_bf16 v[92:95], v[140:143], v[164:167], v[92:95]
	v_mfma_f32_16x16x32_bf16 v[84:87], v[132:135], v[172:175], v[84:87]
	v_mfma_f32_16x16x32_bf16 v[76:79], v[140:143], v[172:175], v[76:79]
	s_barrier
	s_add_i32 s18, 0, 0x1c000
	s_add_i32 s19, s41, s27
	v_add_u32_e32 v188, s18, v238
	s_add_i32 m0, s19, 0xffffff80
	ds_read_b128 v[176:179], v188
	ds_read_b128 v[180:183], v188 offset:1024
	ds_read_b128 v[184:187], v188 offset:2048
	ds_read_b128 v[188:191], v188 offset:3072
	global_load_lds_dwordx4 v206, s[16:17] offset:128
	s_add_i32 m0, s19, 0x1f80
	s_nop 0
	global_load_lds_dwordx4 v210, s[16:17] offset:128
	s_barrier
	s_waitcnt lgkmcnt(0)
	s_waitcnt lgkmcnt(0)
	v_mfma_f32_16x16x32_bf16 v[112:115], v[176:179], v[144:147], v[112:115]
	v_mfma_f32_16x16x32_bf16 v[104:107], v[184:187], v[144:147], v[104:107]
	v_mfma_f32_16x16x32_bf16 v[96:99], v[176:179], v[152:155], v[96:99]
	v_mfma_f32_16x16x32_bf16 v[88:91], v[184:187], v[152:155], v[88:91]
	v_mfma_f32_16x16x32_bf16 v[80:83], v[176:179], v[160:163], v[80:83]
	v_mfma_f32_16x16x32_bf16 v[72:75], v[184:187], v[160:163], v[72:75]
	v_mfma_f32_16x16x32_bf16 v[68:71], v[176:179], v[168:171], v[68:71]
	v_mfma_f32_16x16x32_bf16 v[64:67], v[184:187], v[168:171], v[64:67]
	v_mfma_f32_16x16x32_bf16 v[112:115], v[180:183], v[148:151], v[112:115]
	v_mfma_f32_16x16x32_bf16 v[104:107], v[188:191], v[148:151], v[104:107]
	v_mfma_f32_16x16x32_bf16 v[96:99], v[180:183], v[156:159], v[96:99]
	v_mfma_f32_16x16x32_bf16 v[88:91], v[188:191], v[156:159], v[88:91]
	v_mfma_f32_16x16x32_bf16 v[80:83], v[180:183], v[164:167], v[80:83]
	v_mfma_f32_16x16x32_bf16 v[72:75], v[188:191], v[164:167], v[72:75]
	v_mfma_f32_16x16x32_bf16 v[68:71], v[180:183], v[172:175], v[68:71]
	v_mfma_f32_16x16x32_bf16 v[64:67], v[188:191], v[172:175], v[64:67]
	s_mov_b32 m0, s33
	v_lshl_add_u64 v[196:197], v[222:223], 0, s[48:49]
	s_barrier
	ds_read_b128 v[144:147], v240 offset:49152
	ds_read_b128 v[148:151], v240 offset:50176
	ds_read_b128 v[152:155], v240 offset:51200
	ds_read_b128 v[156:159], v240 offset:52224
	ds_read_b128 v[160:163], v240 offset:53248
	ds_read_b128 v[164:167], v240 offset:54272
	ds_read_b128 v[168:171], v240 offset:55296
	ds_read_b128 v[172:175], v240 offset:56320
	global_load_lds_dwordx4 v[196:197], off
	v_lshl_add_u64 v[196:197], v[224:225], 0, s[48:49]
	s_mov_b32 m0, s34
	s_nop 0
	global_load_lds_dwordx4 v[196:197], off
	s_barrier
	s_waitcnt lgkmcnt(0)
	s_waitcnt lgkmcnt(0)
	v_mfma_f32_16x16x32_bf16 v[60:63], v[128:131], v[144:147], v[60:63]
	v_mfma_f32_16x16x32_bf16 v[56:59], v[136:139], v[144:147], v[56:59]
	v_mfma_f32_16x16x32_bf16 v[52:55], v[128:131], v[152:155], v[52:55]
	v_mfma_f32_16x16x32_bf16 v[44:47], v[136:139], v[152:155], v[44:47]
	v_mfma_f32_16x16x32_bf16 v[36:39], v[128:131], v[160:163], v[36:39]
	v_mfma_f32_16x16x32_bf16 v[28:31], v[136:139], v[160:163], v[28:31]
	v_mfma_f32_16x16x32_bf16 v[20:23], v[128:131], v[168:171], v[20:23]
	v_mfma_f32_16x16x32_bf16 v[12:15], v[136:139], v[168:171], v[12:15]
	v_mfma_f32_16x16x32_bf16 v[60:63], v[132:135], v[148:151], v[60:63]
	v_mfma_f32_16x16x32_bf16 v[56:59], v[140:143], v[148:151], v[56:59]
	v_mfma_f32_16x16x32_bf16 v[52:55], v[132:135], v[156:159], v[52:55]
	v_mfma_f32_16x16x32_bf16 v[44:47], v[140:143], v[156:159], v[44:47]
	v_mfma_f32_16x16x32_bf16 v[36:39], v[132:135], v[164:167], v[36:39]
	v_mfma_f32_16x16x32_bf16 v[28:31], v[140:143], v[164:167], v[28:31]
	v_mfma_f32_16x16x32_bf16 v[20:23], v[132:135], v[172:175], v[20:23]
	v_mfma_f32_16x16x32_bf16 v[12:15], v[140:143], v[172:175], v[12:15]
	s_barrier
	s_add_u32 s16, s16, 0x80080
	s_addc_u32 s17, s17, 0
	s_add_i32 s18, s18, s27
	s_mov_b32 m0, s18
	s_nop 0
	global_load_lds_dwordx4 v206, s[16:17]
	s_add_i32 m0, s18, 0x2000
	s_nop 0
	global_load_lds_dwordx4 v210, s[16:17]
	s_waitcnt vmcnt(6)
	s_barrier
	v_mfma_f32_16x16x32_bf16 v[48:51], v[176:179], v[144:147], v[48:51]
	v_mfma_f32_16x16x32_bf16 v[40:43], v[184:187], v[144:147], v[40:43]
	v_mfma_f32_16x16x32_bf16 v[32:35], v[176:179], v[152:155], v[32:35]
	v_mfma_f32_16x16x32_bf16 v[24:27], v[184:187], v[152:155], v[24:27]
	v_mfma_f32_16x16x32_bf16 v[16:19], v[176:179], v[160:163], v[16:19]
	v_mfma_f32_16x16x32_bf16 v[8:11], v[184:187], v[160:163], v[8:11]
	v_mfma_f32_16x16x32_bf16 v[4:7], v[176:179], v[168:171], v[4:7]
	v_mfma_f32_16x16x32_bf16 v[0:3], v[184:187], v[168:171], v[0:3]
	v_mfma_f32_16x16x32_bf16 v[48:51], v[180:183], v[148:151], v[48:51]
	v_mfma_f32_16x16x32_bf16 v[40:43], v[188:191], v[148:151], v[40:43]
	v_mfma_f32_16x16x32_bf16 v[32:35], v[180:183], v[156:159], v[32:35]
	v_mfma_f32_16x16x32_bf16 v[24:27], v[188:191], v[156:159], v[24:27]
	v_mfma_f32_16x16x32_bf16 v[16:19], v[180:183], v[164:167], v[16:19]
	v_mfma_f32_16x16x32_bf16 v[8:11], v[188:191], v[164:167], v[8:11]
	v_mfma_f32_16x16x32_bf16 v[4:7], v[180:183], v[172:175], v[4:7]
	v_mfma_f32_16x16x32_bf16 v[0:3], v[188:191], v[172:175], v[0:3]
	s_add_i32 s40, s40, 2
	s_add_u32 s14, s14, 0x100
	s_addc_u32 s15, s15, 0
	s_add_u32 s38, s38, 0x100
	s_addc_u32 s39, s39, 0
	s_cmp_gt_u32 s40, 29
	s_barrier
	s_cbranch_scc0 .LBB0_200
	v_lshl_add_u32 v228, s4, 8, v237
	v_or_b32_e32 v226, 16, v228
	s_mov_b64 s[4:5], -1
	s_cmp_lt_i32 s36, 16
	v_ashrrev_i32_e32 v229, 31, v228
	v_lshlrev_b32_e32 v192, 1, v212
	v_ashrrev_i32_e32 v227, 31, v226
	v_or_b32_e32 v224, 32, v228
	v_or_b32_e32 v222, 48, v228
	s_cbranch_scc0 .LBB0_203
	s_and_b32 s7, s36, 7
	s_cmp_gt_i32 s36, 7
	s_cselect_b64 vcc, -1, 0
	s_and_b64 s[4:5], vcc, exec
	s_mov_b32 s4, 0x15000000
	s_cselect_b32 s4, s4, 0xd000000
	s_add_u32 s4, s50, s4
	s_addc_u32 s5, s51, 0
	s_lshl_b32 s9, s7, 9
	s_add_u32 s4, s4, s9
	v_cvt_f32_ubyte0_e32 v128, s7
	s_addc_u32 s5, s5, 0
	v_sub_f32_e32 v128, 0xc0a00000, v128
	s_mov_b32 s7, 0xc2fc0000
	v_lshl_add_u64 v[230:231], s[4:5], 0, v[192:193]
	v_cmp_gt_f32_e64 s[4:5], s7, v128
	v_ashrrev_i32_e32 v225, 31, v224
	s_nop 0
	v_cndmask_b32_e64 v129, 0, v234, s[4:5]
	v_add_f32_e32 v128, v128, v129
	v_exp_f32_e32 v128, v128
	s_and_b64 s[4:5], s[4:5], exec
	s_cselect_b32 s4, 0xffffffc0, 0
	v_mov_b32_e32 v129, v193
	v_ldexp_f32 v128, v128, s4
	v_sub_f32_e32 v128, 1.0, v128
	v_log_f32_e32 v241, v128
	v_lshlrev_b32_e32 v128, 9, v228
	v_and_b32_e32 v128, 0x1f9e00, v128
	v_lshl_add_u64 v[130:131], v[214:215], 0, v[128:129]
	v_lshl_add_u64 v[132:133], v[216:217], 0, v[128:129]
	global_load_dwordx4 v[180:183], v[130:131], off offset:16
	global_load_dwordx4 v[188:191], v[130:131], off
	global_load_dwordx4 v[176:179], v[132:133], off offset:16
	global_load_dwordx4 v[184:187], v[132:133], off
	v_or_b32_e32 v130, 0x2000, v128
	v_mov_b32_e32 v131, v193
	v_lshl_add_u64 v[132:133], v[214:215], 0, v[130:131]
	v_lshl_add_u64 v[130:131], v[216:217], 0, v[130:131]
	global_load_dwordx4 v[164:167], v[132:133], off offset:16
	global_load_dwordx4 v[172:175], v[132:133], off
	global_load_dwordx4 v[160:163], v[130:131], off offset:16
	global_load_dwordx4 v[168:171], v[130:131], off
	v_mul_f32_e64 v196, v241, -v239
	v_cmp_gt_f32_e64 s[4:5], s7, v196
	v_or_b32_e32 v130, 0x4000, v128
	v_mov_b32_e32 v131, v193
	v_cndmask_b32_e64 v196, 0, v234, s[4:5]
	v_fma_f32 v196, v241, -v239, v196
	v_exp_f32_e32 v196, v196
	v_cndmask_b32_e64 v197, 0, v235, s[4:5]
	v_lshl_add_u64 v[132:133], v[214:215], 0, v[130:131]
	v_lshl_add_u64 v[130:131], v[216:217], 0, v[130:131]
	v_ldexp_f32 v196, v196, v197
	v_mul_f32_e32 v196, 0x3d800000, v196
	v_cndmask_b32_e32 v242, 1.0, v196, vcc
	v_mov_b32_e32 v196, v124
	v_mov_b32_e32 v197, v112
	global_load_dwordx4 v[148:151], v[132:133], off offset:16
	global_load_dwordx4 v[156:159], v[132:133], off
	global_load_dwordx4 v[144:147], v[130:131], off offset:16
	global_load_dwordx4 v[152:155], v[130:131], off
	v_or_b32_e32 v128, 0x6000, v128
	v_lshl_add_u64 v[130:131], v[214:215], 0, v[128:129]
	v_lshl_add_u64 v[136:137], v[216:217], 0, v[128:129]
	global_load_dwordx4 v[132:135], v[130:131], off offset:16
	global_load_dwordx4 v[140:143], v[130:131], off
	s_nop 0
	global_load_dwordx4 v[128:131], v[136:137], off offset:16
	s_nop 0
	global_load_dwordx4 v[136:139], v[136:137], off
	s_movk_i32 s4, 0x5f
	s_waitcnt vmcnt(0)
	v_mov_b32_e32 v198, v188
	v_mov_b32_e32 v199, v184
	v_pk_mul_f32 v[196:197], v[196:197], v[198:199]
	s_nop 0
	v_sub_f32_e32 v184, v196, v197
	v_mov_b32_e32 v196, v112
	v_mov_b32_e32 v197, v124
	v_pk_mul_f32 v[196:197], v[196:197], v[198:199]
	v_mul_f32_e32 v223, v242, v184
	v_add_f32_e32 v184, v196, v197
	v_mul_f32_e32 v198, v242, v184
	v_mov_b32_e32 v196, v125
	v_mov_b32_e32 v197, v113
	v_mov_b32_e32 v184, v189
	v_pk_mul_f32 v[188:189], v[196:197], v[184:185]
	s_nop 0
	v_sub_f32_e32 v188, v188, v189
	v_mul_f32_e32 v196, v242, v188
	v_mov_b32_e32 v188, v113
	v_mov_b32_e32 v189, v125
	v_pk_mul_f32 v[184:185], v[188:189], v[184:185]
	v_mov_b32_e32 v188, v190
	v_add_f32_e32 v184, v184, v185
	v_mul_f32_e32 v197, v242, v184
	v_mov_b32_e32 v184, v126
	v_mov_b32_e32 v185, v114
	v_mov_b32_e32 v189, v186
	v_pk_mul_f32 v[184:185], v[184:185], v[188:189]
	v_mov_b32_e32 v186, v191
	v_sub_f32_e32 v184, v184, v185
	v_mul_f32_e32 v190, v242, v184
	v_mov_b32_e32 v184, v114
	v_mov_b32_e32 v185, v126
	v_pk_mul_f32 v[184:185], v[184:185], v[188:189]
	s_nop 0
	v_add_f32_e32 v184, v184, v185
	v_mul_f32_e32 v188, v242, v184
	v_mov_b32_e32 v184, v127
	v_mov_b32_e32 v185, v115
	v_pk_mul_f32 v[184:185], v[184:185], v[186:187]
	s_nop 0
	v_sub_f32_e32 v184, v184, v185
	v_mul_f32_e32 v189, v242, v184
	v_mov_b32_e32 v184, v115
	v_mov_b32_e32 v185, v127
	v_pk_mul_f32 v[184:185], v[184:185], v[186:187]
	v_mov_b32_e32 v186, v180
	v_add_f32_e32 v184, v184, v185
	v_mul_f32_e32 v191, v242, v184
	v_mov_b32_e32 v184, v120
	v_mov_b32_e32 v185, v104
	v_mov_b32_e32 v187, v176
	v_pk_mul_f32 v[184:185], v[184:185], v[186:187]
	s_nop 0
	v_sub_f32_e32 v176, v184, v185
	v_mov_b32_e32 v184, v104
	v_mov_b32_e32 v185, v120
	v_pk_mul_f32 v[184:185], v[184:185], v[186:187]
	v_mul_f32_e32 v199, v242, v176
	v_add_f32_e32 v176, v184, v185
	v_mul_f32_e32 v186, v242, v176
	v_mov_b32_e32 v184, v121
	v_mov_b32_e32 v185, v105
	v_mov_b32_e32 v176, v181
	v_pk_mul_f32 v[180:181], v[184:185], v[176:177]
	s_nop 0
	v_sub_f32_e32 v180, v180, v181
	v_mul_f32_e32 v184, v242, v180
	v_mov_b32_e32 v180, v105
	v_mov_b32_e32 v181, v121
	v_pk_mul_f32 v[176:177], v[180:181], v[176:177]
	v_mov_b32_e32 v180, v182
	v_add_f32_e32 v176, v176, v177
	v_mul_f32_e32 v185, v242, v176
	v_mov_b32_e32 v176, v122
	v_mov_b32_e32 v177, v106
	v_mov_b32_e32 v181, v178
	v_pk_mul_f32 v[176:177], v[176:177], v[180:181]
	v_mov_b32_e32 v178, v183
	v_sub_f32_e32 v176, v176, v177
	v_mul_f32_e32 v182, v242, v176
	v_mov_b32_e32 v176, v106
	v_mov_b32_e32 v177, v122
	v_pk_mul_f32 v[176:177], v[176:177], v[180:181]
	s_nop 0
	v_add_f32_e32 v176, v176, v177
	v_mul_f32_e32 v187, v242, v176
	v_mov_b32_e32 v176, v123
	v_mov_b32_e32 v177, v107
	v_pk_mul_f32 v[176:177], v[176:177], v[178:179]
	s_nop 0
	v_sub_f32_e32 v176, v176, v177
	v_mul_f32_e32 v181, v242, v176
	v_mov_b32_e32 v176, v107
	v_mov_b32_e32 v177, v123
	v_pk_mul_f32 v[176:177], v[176:177], v[178:179]
	v_cvt_pk_bf16_f32 v178, v223, v196
	v_cvt_pk_bf16_f32 v179, v190, v189
	v_cvt_pk_bf16_f32 v180, v199, v184
	v_cvt_pk_bf16_f32 v181, v182, v181
	v_cvt_pk_bf16_f32 v182, v198, v197
	s_nop 0
	v_add_f32_e32 v176, v176, v177
	v_mul_f32_e32 v176, v242, v176
	v_cvt_pk_bf16_f32 v183, v188, v191
	v_cvt_pk_bf16_f32 v184, v186, v185
	v_cvt_pk_bf16_f32 v185, v187, v176
	v_lshlrev_b64 v[176:177], 12, v[228:229]
	v_lshl_add_u64 v[176:177], v[230:231], 0, v[176:177]
	global_store_dwordx4 v[176:177], v[178:181], off
	global_store_dwordx4 v[176:177], v[182:185], off offset:256
	v_ashrrev_i32_e32 v223, 31, v222
	v_bitop3_b32 v178, v228, s4, 16 bitop3:0xc8
	v_add_u32_e32 v178, 1, v178
	v_cvt_f32_ubyte0_e32 v178, v178
	v_mul_f32_e64 v179, v241, -v178
	v_cmp_gt_f32_e64 s[4:5], s7, v179
	v_mov_b32_e32 v181, v168
	v_mov_b32_e32 v190, v60
	v_cndmask_b32_e64 v180, 0, v234, s[4:5]
	v_fma_f32 v178, v241, -v178, v180
	v_exp_f32_e32 v178, v178
	v_cndmask_b32_e64 v179, 0, v235, s[4:5]
	v_mov_b32_e32 v180, v172
	s_movk_i32 s4, 0x6f
	v_ldexp_f32 v178, v178, v179
	v_mul_f32_e32 v178, 0x3d800000, v178
	v_cndmask_b32_e32 v182, 1.0, v178, vcc
	v_mov_b32_e32 v178, v116
	v_mov_b32_e32 v179, v96
	v_pk_mul_f32 v[178:179], v[178:179], v[180:181]
	v_mov_b32_e32 v191, v48
	v_sub_f32_e32 v168, v178, v179
	v_mov_b32_e32 v178, v96
	v_mov_b32_e32 v179, v116
	v_pk_mul_f32 v[178:179], v[178:179], v[180:181]
	v_mul_f32_e32 v183, v182, v168
	v_add_f32_e32 v168, v178, v179
	v_mul_f32_e32 v180, v182, v168
	v_mov_b32_e32 v178, v117
	v_mov_b32_e32 v179, v97
	v_mov_b32_e32 v168, v173
	v_pk_mul_f32 v[172:173], v[178:179], v[168:169]
	s_nop 0
	v_sub_f32_e32 v172, v172, v173
	v_mul_f32_e32 v178, v182, v172
	v_mov_b32_e32 v172, v97
	v_mov_b32_e32 v173, v117
	v_pk_mul_f32 v[168:169], v[172:173], v[168:169]
	v_mov_b32_e32 v172, v174
	v_add_f32_e32 v168, v168, v169
	v_mul_f32_e32 v179, v182, v168
	v_mov_b32_e32 v168, v118
	v_mov_b32_e32 v169, v98
	v_mov_b32_e32 v173, v170
	v_pk_mul_f32 v[168:169], v[168:169], v[172:173]
	v_mov_b32_e32 v170, v175
	v_sub_f32_e32 v168, v168, v169
	v_mul_f32_e32 v174, v182, v168
	v_mov_b32_e32 v168, v98
	v_mov_b32_e32 v169, v118
	v_pk_mul_f32 v[168:169], v[168:169], v[172:173]
	s_nop 0
	v_add_f32_e32 v168, v168, v169
	v_mul_f32_e32 v172, v182, v168
	v_mov_b32_e32 v168, v119
	v_mov_b32_e32 v169, v99
	v_pk_mul_f32 v[168:169], v[168:169], v[170:171]
	s_nop 0
	v_sub_f32_e32 v168, v168, v169
	v_mul_f32_e32 v173, v182, v168
	v_mov_b32_e32 v168, v99
	v_mov_b32_e32 v169, v119
	v_pk_mul_f32 v[168:169], v[168:169], v[170:171]
	v_mov_b32_e32 v170, v164
	v_add_f32_e32 v168, v168, v169
	v_mul_f32_e32 v175, v182, v168
	v_mov_b32_e32 v168, v108
	v_mov_b32_e32 v169, v88
	v_mov_b32_e32 v171, v160
	v_pk_mul_f32 v[168:169], v[168:169], v[170:171]
	s_nop 0
	v_sub_f32_e32 v160, v168, v169
	v_mov_b32_e32 v168, v88
	v_mov_b32_e32 v169, v108
	v_pk_mul_f32 v[168:169], v[168:169], v[170:171]
	v_mul_f32_e32 v181, v182, v160
	v_add_f32_e32 v160, v168, v169
	v_mul_f32_e32 v170, v182, v160
	v_mov_b32_e32 v168, v109
	v_mov_b32_e32 v169, v89
	v_mov_b32_e32 v160, v165
	v_pk_mul_f32 v[164:165], v[168:169], v[160:161]
	s_nop 0
	v_sub_f32_e32 v164, v164, v165
	v_mul_f32_e32 v168, v182, v164
	v_mov_b32_e32 v164, v89
	v_mov_b32_e32 v165, v109
	v_pk_mul_f32 v[160:161], v[164:165], v[160:161]
	v_mov_b32_e32 v164, v166
	v_add_f32_e32 v160, v160, v161
	v_mul_f32_e32 v169, v182, v160
	v_mov_b32_e32 v160, v110
	v_mov_b32_e32 v161, v90
	v_mov_b32_e32 v165, v162
	v_pk_mul_f32 v[160:161], v[160:161], v[164:165]
	v_mov_b32_e32 v162, v167
	v_sub_f32_e32 v160, v160, v161
	v_mul_f32_e32 v166, v182, v160
	v_mov_b32_e32 v160, v90
	v_mov_b32_e32 v161, v110
	v_pk_mul_f32 v[160:161], v[160:161], v[164:165]
	s_nop 0
	v_add_f32_e32 v160, v160, v161
	v_mul_f32_e32 v171, v182, v160
	v_mov_b32_e32 v160, v111
	v_mov_b32_e32 v161, v91
	v_pk_mul_f32 v[160:161], v[160:161], v[162:163]
	s_nop 0
	v_sub_f32_e32 v160, v160, v161
	v_mul_f32_e32 v164, v182, v160
	v_mov_b32_e32 v160, v91
	v_mov_b32_e32 v161, v111
	v_pk_mul_f32 v[160:161], v[160:161], v[162:163]
	s_nop 0
	v_add_f32_e32 v160, v160, v161
	v_mul_f32_e32 v167, v182, v160
	v_cvt_pk_bf16_f32 v160, v183, v178
	v_cvt_pk_bf16_f32 v161, v174, v173
	v_cvt_pk_bf16_f32 v162, v181, v168
	v_cvt_pk_bf16_f32 v163, v166, v164
	v_cvt_pk_bf16_f32 v164, v180, v179
	v_cvt_pk_bf16_f32 v165, v172, v175
	v_cvt_pk_bf16_f32 v166, v170, v169
	v_lshlrev_b64 v[168:169], 12, v[226:227]
	v_lshl_add_u64 v[168:169], v[230:231], 0, v[168:169]
	v_cvt_pk_bf16_f32 v167, v171, v167
	global_store_dwordx4 v[168:169], v[160:163], off
	global_store_dwordx4 v[168:169], v[164:167], off offset:256
	s_nop 0
	v_bitop3_b32 v160, v228, s4, 32 bitop3:0xc8
	v_add_u32_e32 v160, 1, v160
	v_cvt_f32_ubyte0_e32 v160, v160
	v_mul_f32_e64 v161, v241, -v160
	v_cmp_gt_f32_e64 s[4:5], s7, v161
	v_mov_b32_e32 v163, v152
	s_nop 0
	v_cndmask_b32_e64 v162, 0, v234, s[4:5]
	v_fma_f32 v160, v241, -v160, v162
	v_exp_f32_e32 v160, v160
	v_cndmask_b32_e64 v161, 0, v235, s[4:5]
	v_mov_b32_e32 v162, v156
	s_movk_i32 s4, 0x7f
	v_ldexp_f32 v160, v160, v161
	v_mul_f32_e32 v160, 0x3d800000, v160
	v_cndmask_b32_e32 v164, 1.0, v160, vcc
	v_mov_b32_e32 v160, v100
	v_mov_b32_e32 v161, v80
	v_pk_mul_f32 v[160:161], v[160:161], v[162:163]
	s_nop 0
	v_sub_f32_e32 v152, v160, v161
	v_mov_b32_e32 v160, v80
	v_mov_b32_e32 v161, v100
	v_pk_mul_f32 v[160:161], v[160:161], v[162:163]
	v_mul_f32_e32 v165, v164, v152
	v_add_f32_e32 v152, v160, v161
	v_mul_f32_e32 v162, v164, v152
	v_mov_b32_e32 v160, v101
	v_mov_b32_e32 v161, v81
	v_mov_b32_e32 v152, v157
	v_pk_mul_f32 v[156:157], v[160:161], v[152:153]
	s_nop 0
	v_sub_f32_e32 v156, v156, v157
	v_mul_f32_e32 v160, v164, v156
	v_mov_b32_e32 v156, v81
	v_mov_b32_e32 v157, v101
	v_pk_mul_f32 v[152:153], v[156:157], v[152:153]
	v_mov_b32_e32 v156, v158
	v_add_f32_e32 v152, v152, v153
	v_mul_f32_e32 v161, v164, v152
	v_mov_b32_e32 v152, v102
	v_mov_b32_e32 v153, v82
	v_mov_b32_e32 v157, v154
	v_pk_mul_f32 v[152:153], v[152:153], v[156:157]
	v_mov_b32_e32 v154, v159
	v_sub_f32_e32 v152, v152, v153
	v_mul_f32_e32 v158, v164, v152
	v_mov_b32_e32 v152, v82
	v_mov_b32_e32 v153, v102
	v_pk_mul_f32 v[152:153], v[152:153], v[156:157]
	s_nop 0
	v_add_f32_e32 v152, v152, v153
	v_mul_f32_e32 v156, v164, v152
	v_mov_b32_e32 v152, v103
	v_mov_b32_e32 v153, v83
	v_pk_mul_f32 v[152:153], v[152:153], v[154:155]
	s_nop 0
	v_sub_f32_e32 v152, v152, v153
	v_mul_f32_e32 v157, v164, v152
	v_mov_b32_e32 v152, v83
	v_mov_b32_e32 v153, v103
	v_pk_mul_f32 v[152:153], v[152:153], v[154:155]
	v_mov_b32_e32 v154, v148
	v_add_f32_e32 v152, v152, v153
	v_mul_f32_e32 v159, v164, v152
	v_mov_b32_e32 v152, v92
	v_mov_b32_e32 v153, v72
	v_mov_b32_e32 v155, v144
	v_pk_mul_f32 v[152:153], v[152:153], v[154:155]
	s_nop 0
	v_sub_f32_e32 v144, v152, v153
	v_mov_b32_e32 v152, v72
	v_mov_b32_e32 v153, v92
	v_pk_mul_f32 v[152:153], v[152:153], v[154:155]
	v_mul_f32_e32 v163, v164, v144
	v_add_f32_e32 v144, v152, v153
	v_mul_f32_e32 v154, v164, v144
	v_mov_b32_e32 v152, v93
	v_mov_b32_e32 v153, v73
	v_mov_b32_e32 v144, v149
	v_pk_mul_f32 v[148:149], v[152:153], v[144:145]
	s_nop 0
	v_sub_f32_e32 v148, v148, v149
	v_mul_f32_e32 v152, v164, v148
	v_mov_b32_e32 v148, v73
	v_mov_b32_e32 v149, v93
	v_pk_mul_f32 v[144:145], v[148:149], v[144:145]
	v_mov_b32_e32 v148, v150
	v_add_f32_e32 v144, v144, v145
	v_mul_f32_e32 v153, v164, v144
	v_mov_b32_e32 v144, v94
	v_mov_b32_e32 v145, v74
	v_mov_b32_e32 v149, v146
	v_pk_mul_f32 v[144:145], v[144:145], v[148:149]
	v_mov_b32_e32 v146, v151
	v_sub_f32_e32 v144, v144, v145
	v_mul_f32_e32 v150, v164, v144
	v_mov_b32_e32 v144, v74
	v_mov_b32_e32 v145, v94
	v_pk_mul_f32 v[144:145], v[144:145], v[148:149]
	s_nop 0
	v_add_f32_e32 v144, v144, v145
	v_mul_f32_e32 v155, v164, v144
	v_mov_b32_e32 v144, v95
	v_mov_b32_e32 v145, v75
	v_pk_mul_f32 v[144:145], v[144:145], v[146:147]
	s_nop 0
	v_sub_f32_e32 v144, v144, v145
	v_mul_f32_e32 v148, v164, v144
	v_mov_b32_e32 v144, v75
	v_mov_b32_e32 v145, v95
	v_pk_mul_f32 v[144:145], v[144:145], v[146:147]
	s_nop 0
	v_add_f32_e32 v144, v144, v145
	v_mul_f32_e32 v151, v164, v144
	v_cvt_pk_bf16_f32 v144, v165, v160
	v_cvt_pk_bf16_f32 v145, v158, v157
	v_cvt_pk_bf16_f32 v146, v163, v152
	v_cvt_pk_bf16_f32 v147, v150, v148
	v_cvt_pk_bf16_f32 v148, v162, v161
	v_cvt_pk_bf16_f32 v149, v156, v159
	v_cvt_pk_bf16_f32 v150, v154, v153
	v_lshlrev_b64 v[152:153], 12, v[224:225]
	v_lshl_add_u64 v[152:153], v[230:231], 0, v[152:153]
	v_cvt_pk_bf16_f32 v151, v155, v151
	global_store_dwordx4 v[152:153], v[144:147], off
	global_store_dwordx4 v[152:153], v[148:151], off offset:256
	s_nop 0
	v_bitop3_b32 v144, v228, s4, 48 bitop3:0xc8
	v_add_u32_e32 v144, 1, v144
	v_cvt_f32_ubyte0_e32 v144, v144
	v_mul_f32_e64 v145, v241, -v144
	v_cmp_gt_f32_e64 s[4:5], s7, v145
	v_mov_b32_e32 v147, v136
	s_nop 0
	v_cndmask_b32_e64 v146, 0, v234, s[4:5]
	v_fma_f32 v144, v241, -v144, v146
	v_exp_f32_e32 v144, v144
	v_cndmask_b32_e64 v145, 0, v235, s[4:5]
	v_mov_b32_e32 v146, v140
	s_mov_b64 s[4:5], 0x80000
	v_ldexp_f32 v144, v144, v145
	v_mul_f32_e32 v144, 0x3d800000, v144
	v_cndmask_b32_e32 v148, 1.0, v144, vcc
	v_mov_b32_e32 v144, v84
	v_mov_b32_e32 v145, v68
	v_pk_mul_f32 v[144:145], v[144:145], v[146:147]
	s_nop 0
	v_sub_f32_e32 v136, v144, v145
	v_mov_b32_e32 v144, v68
	v_mov_b32_e32 v145, v84
	v_pk_mul_f32 v[144:145], v[144:145], v[146:147]
	v_mul_f32_e32 v149, v148, v136
	v_add_f32_e32 v136, v144, v145
	v_mul_f32_e32 v146, v148, v136
	v_mov_b32_e32 v144, v85
	v_mov_b32_e32 v145, v69
	v_mov_b32_e32 v136, v141
	v_pk_mul_f32 v[140:141], v[144:145], v[136:137]
	s_nop 0
	v_sub_f32_e32 v140, v140, v141
	v_mul_f32_e32 v144, v148, v140
	v_mov_b32_e32 v140, v69
	v_mov_b32_e32 v141, v85
	v_pk_mul_f32 v[136:137], v[140:141], v[136:137]
	v_mov_b32_e32 v140, v142
	v_add_f32_e32 v136, v136, v137
	v_mul_f32_e32 v145, v148, v136
	v_mov_b32_e32 v136, v86
	v_mov_b32_e32 v137, v70
	v_mov_b32_e32 v141, v138
	v_pk_mul_f32 v[136:137], v[136:137], v[140:141]
	v_mov_b32_e32 v138, v143
	v_sub_f32_e32 v136, v136, v137
	v_mul_f32_e32 v142, v148, v136
	v_mov_b32_e32 v136, v70
	v_mov_b32_e32 v137, v86
	v_pk_mul_f32 v[136:137], v[136:137], v[140:141]
	s_nop 0
	v_add_f32_e32 v136, v136, v137
	v_mul_f32_e32 v140, v148, v136
	v_mov_b32_e32 v136, v87
	v_mov_b32_e32 v137, v71
	v_pk_mul_f32 v[136:137], v[136:137], v[138:139]
	s_nop 0
	v_sub_f32_e32 v136, v136, v137
	v_mul_f32_e32 v141, v148, v136
	v_mov_b32_e32 v136, v71
	v_mov_b32_e32 v137, v87
	v_pk_mul_f32 v[136:137], v[136:137], v[138:139]
	v_mov_b32_e32 v138, v132
	v_add_f32_e32 v136, v136, v137
	v_mul_f32_e32 v143, v148, v136
	v_mov_b32_e32 v136, v76
	v_mov_b32_e32 v137, v64
	v_mov_b32_e32 v139, v128
	v_pk_mul_f32 v[136:137], v[136:137], v[138:139]
	s_nop 0
	v_sub_f32_e32 v128, v136, v137
	v_mov_b32_e32 v136, v64
	v_mov_b32_e32 v137, v76
	v_pk_mul_f32 v[136:137], v[136:137], v[138:139]
	v_mul_f32_e32 v147, v148, v128
	v_add_f32_e32 v128, v136, v137
	v_mul_f32_e32 v138, v148, v128
	v_mov_b32_e32 v136, v77
	v_mov_b32_e32 v137, v65
	v_mov_b32_e32 v128, v133
	v_pk_mul_f32 v[132:133], v[136:137], v[128:129]
	s_nop 0
	v_sub_f32_e32 v132, v132, v133
	v_mul_f32_e32 v136, v148, v132
	v_mov_b32_e32 v132, v65
	v_mov_b32_e32 v133, v77
	v_pk_mul_f32 v[128:129], v[132:133], v[128:129]
	v_mov_b32_e32 v132, v134
	v_add_f32_e32 v128, v128, v129
	v_mul_f32_e32 v137, v148, v128
	v_mov_b32_e32 v128, v78
	v_mov_b32_e32 v129, v66
	v_mov_b32_e32 v133, v130
	v_pk_mul_f32 v[128:129], v[128:129], v[132:133]
	v_mov_b32_e32 v130, v135
	v_sub_f32_e32 v128, v128, v129
	v_mul_f32_e32 v134, v148, v128
	v_mov_b32_e32 v128, v66
	v_mov_b32_e32 v129, v78
	v_pk_mul_f32 v[128:129], v[128:129], v[132:133]
	s_nop 0
	v_add_f32_e32 v128, v128, v129
	v_mul_f32_e32 v139, v148, v128
	v_mov_b32_e32 v128, v79
	v_mov_b32_e32 v129, v67
	v_pk_mul_f32 v[128:129], v[128:129], v[130:131]
	s_nop 0
	v_sub_f32_e32 v128, v128, v129
	v_mul_f32_e32 v132, v148, v128
	v_mov_b32_e32 v128, v67
	v_mov_b32_e32 v129, v79
	v_pk_mul_f32 v[128:129], v[128:129], v[130:131]
	s_nop 0
	v_add_f32_e32 v128, v128, v129
	v_mul_f32_e32 v135, v148, v128
	v_cvt_pk_bf16_f32 v128, v149, v144
	v_cvt_pk_bf16_f32 v129, v142, v141
	v_cvt_pk_bf16_f32 v130, v147, v136
	v_cvt_pk_bf16_f32 v131, v134, v132
	v_cvt_pk_bf16_f32 v132, v146, v145
	v_cvt_pk_bf16_f32 v133, v140, v143
	v_cvt_pk_bf16_f32 v134, v138, v137
	v_lshlrev_b64 v[136:137], 12, v[222:223]
	v_lshl_add_u64 v[136:137], v[230:231], 0, v[136:137]
	v_cvt_pk_bf16_f32 v135, v139, v135
	global_store_dwordx4 v[136:137], v[128:131], off
	global_store_dwordx4 v[136:137], v[132:135], off offset:256
	s_nop 0
	v_mov_b32_e32 v128, 0x4000
	v_lshl_add_u32 v128, v228, 7, v128
	v_and_b32_e32 v128, 0x7e780, v128
	v_lshlrev_b32_e32 v128, 2, v128
	v_mov_b32_e32 v129, v193
	v_lshl_add_u64 v[130:131], v[214:215], 0, v[128:129]
	v_lshl_add_u64 v[132:133], v[216:217], 0, v[128:129]
	global_load_dwordx4 v[168:171], v[130:131], off offset:16
	global_load_dwordx4 v[172:175], v[130:131], off
	global_load_dwordx4 v[178:181], v[132:133], off offset:16
	global_load_dwordx4 v[182:185], v[132:133], off
	v_or_b32_e32 v130, 0x2000, v128
	v_mov_b32_e32 v131, v193
	v_lshl_add_u64 v[132:133], v[214:215], 0, v[130:131]
	v_lshl_add_u64 v[130:131], v[216:217], 0, v[130:131]
	global_load_dwordx4 v[164:167], v[132:133], off offset:16
	global_load_dwordx4 v[186:189], v[132:133], off
	global_load_dwordx4 v[160:163], v[130:131], off offset:16
	global_load_dwordx4 v[196:199], v[130:131], off
	v_or_b32_e32 v130, 0x4000, v128
	v_mov_b32_e32 v131, v193
	v_lshl_add_u64 v[132:133], v[214:215], 0, v[130:131]
	v_lshl_add_u64 v[130:131], v[216:217], 0, v[130:131]
	global_load_dwordx4 v[148:151], v[132:133], off offset:16
	global_load_dwordx4 v[156:159], v[132:133], off
	global_load_dwordx4 v[144:147], v[130:131], off offset:16
	global_load_dwordx4 v[152:155], v[130:131], off
	v_or_b32_e32 v128, 0x6000, v128
	v_lshl_add_u64 v[130:131], v[214:215], 0, v[128:129]
	v_lshl_add_u64 v[136:137], v[216:217], 0, v[128:129]
	global_load_dwordx4 v[132:135], v[130:131], off offset:16
	global_load_dwordx4 v[140:143], v[130:131], off
	s_nop 0
	global_load_dwordx4 v[128:131], v[136:137], off offset:16
	s_nop 0
	global_load_dwordx4 v[136:139], v[136:137], off
	s_waitcnt vmcnt(0)
	v_mov_b32_e32 v244, v172
	v_mov_b32_e32 v245, v182
	v_pk_mul_f32 v[190:191], v[190:191], v[244:245]
	v_mov_b32_e32 v182, v173
	v_sub_f32_e32 v172, v190, v191
	v_mov_b32_e32 v190, v48
	v_mov_b32_e32 v191, v60
	v_pk_mul_f32 v[190:191], v[190:191], v[244:245]
	v_mul_f32_e32 v223, v242, v172
	v_add_f32_e32 v172, v190, v191
	v_mov_b32_e32 v190, v61
	v_mov_b32_e32 v191, v49
	v_mul_f32_e32 v225, v242, v172
	v_pk_mul_f32 v[172:173], v[190:191], v[182:183]
	s_nop 0
	v_sub_f32_e32 v172, v172, v173
	v_mul_f32_e32 v190, v242, v172
	v_mov_b32_e32 v172, v49
	v_mov_b32_e32 v173, v61
	v_pk_mul_f32 v[172:173], v[172:173], v[182:183]
	v_mov_b32_e32 v182, v174
	v_add_f32_e32 v172, v172, v173
	v_mul_f32_e32 v191, v242, v172
	v_mov_b32_e32 v172, v62
	v_mov_b32_e32 v173, v50
	v_mov_b32_e32 v183, v184
	v_pk_mul_f32 v[172:173], v[172:173], v[182:183]
	v_mov_b32_e32 v184, v175
	v_sub_f32_e32 v172, v172, v173
	v_mul_f32_e32 v243, v242, v172
	v_mov_b32_e32 v172, v50
	v_mov_b32_e32 v173, v62
	v_pk_mul_f32 v[172:173], v[172:173], v[182:183]
	v_mov_b32_e32 v174, v168
	v_add_f32_e32 v172, v172, v173
	v_mul_f32_e32 v182, v242, v172
	v_mov_b32_e32 v172, v63
	v_mov_b32_e32 v173, v51
	v_pk_mul_f32 v[172:173], v[172:173], v[184:185]
	v_mov_b32_e32 v175, v178
	v_sub_f32_e32 v172, v172, v173
	v_mul_f32_e32 v183, v242, v172
	v_mov_b32_e32 v172, v51
	v_mov_b32_e32 v173, v63
	v_pk_mul_f32 v[172:173], v[172:173], v[184:185]
	v_mov_b32_e32 v178, v169
	v_add_f32_e32 v172, v172, v173
	v_mul_f32_e32 v184, v242, v172
	v_mov_b32_e32 v172, v56
	v_mov_b32_e32 v173, v40
	v_pk_mul_f32 v[172:173], v[172:173], v[174:175]
	s_nop 0
	v_sub_f32_e32 v168, v172, v173
	v_mov_b32_e32 v172, v40
	v_mov_b32_e32 v173, v56
	v_pk_mul_f32 v[172:173], v[172:173], v[174:175]
	v_mul_f32_e32 v185, v242, v168
	v_add_f32_e32 v168, v172, v173
	v_mov_b32_e32 v172, v57
	v_mov_b32_e32 v173, v41
	v_mul_f32_e32 v174, v242, v168
	v_pk_mul_f32 v[168:169], v[172:173], v[178:179]
	v_mov_b32_e32 v172, v170
	v_sub_f32_e32 v168, v168, v169
	v_mul_f32_e32 v175, v242, v168
	v_mov_b32_e32 v168, v41
	v_mov_b32_e32 v169, v57
	v_pk_mul_f32 v[168:169], v[168:169], v[178:179]
	v_mov_b32_e32 v173, v180
	v_add_f32_e32 v168, v168, v169
	v_mul_f32_e32 v178, v242, v168
	v_mov_b32_e32 v168, v58
	v_mov_b32_e32 v169, v42
	v_pk_mul_f32 v[168:169], v[168:169], v[172:173]
	v_mov_b32_e32 v180, v171
	v_sub_f32_e32 v168, v168, v169
	v_mul_f32_e32 v179, v242, v168
	v_mov_b32_e32 v168, v42
	v_mov_b32_e32 v169, v58
	v_pk_mul_f32 v[168:169], v[168:169], v[172:173]
	s_nop 0
	v_add_f32_e32 v168, v168, v169
	v_mul_f32_e32 v244, v242, v168
	v_mov_b32_e32 v168, v59
	v_mov_b32_e32 v169, v43
	v_pk_mul_f32 v[168:169], v[168:169], v[180:181]
	s_nop 0
	v_sub_f32_e32 v168, v168, v169
	v_mul_f32_e32 v171, v242, v168
	v_mov_b32_e32 v168, v43
	v_mov_b32_e32 v169, v59
	v_pk_mul_f32 v[168:169], v[168:169], v[180:181]
	s_nop 0
	v_add_f32_e32 v168, v168, v169
	v_mul_f32_e32 v180, v242, v168
	v_cvt_pk_bf16_f32 v168, v223, v190
	v_cvt_pk_bf16_f32 v169, v243, v183
	v_cvt_pk_bf16_f32 v170, v185, v175
	v_cvt_pk_bf16_f32 v171, v179, v171
	v_cvt_pk_bf16_f32 v172, v225, v191
	v_cvt_pk_bf16_f32 v173, v182, v184
	v_cvt_pk_bf16_f32 v174, v174, v178
	v_lshl_add_u64 v[178:179], v[176:177], 0, s[4:5]
	s_mov_b32 s4, 0x80000
	v_add_co_u32_e64 v176, s[4:5], s4, v176
	v_cvt_pk_bf16_f32 v175, v244, v180
	s_nop 1
	v_addc_co_u32_e64 v177, s[4:5], 0, v177, s[4:5]
	global_store_dwordx4 v[176:177], v[168:171], off
	global_store_dwordx4 v[178:179], v[172:175], off offset:256
	s_nop 0
	v_add_u32_e32 v168, 0x90, v228
	v_and_b32_e32 v169, 0x5f, v168
	v_add_u32_e32 v169, 1, v169
	v_cvt_f32_ubyte0_e32 v169, v169
	v_mul_f32_e64 v170, v241, -v169
	v_cmp_gt_f32_e64 s[4:5], s7, v170
	v_mov_b32_e32 v171, v32
	v_mov_b32_e32 v172, v186
	v_cndmask_b32_e64 v170, 0, v234, s[4:5]
	v_fma_f32 v169, v241, -v169, v170
	v_exp_f32_e32 v169, v169
	v_cndmask_b32_e64 v170, 0, v235, s[4:5]
	v_mov_b32_e32 v173, v196
	v_mov_b32_e32 v196, v187
	v_ldexp_f32 v169, v169, v170
	v_mov_b32_e32 v170, v52
	v_mul_f32_e32 v169, 0x3d800000, v169
	v_pk_mul_f32 v[170:171], v[170:171], v[172:173]
	v_cndmask_b32_e32 v169, 1.0, v169, vcc
	v_sub_f32_e32 v170, v170, v171
	v_mul_f32_e32 v174, v169, v170
	v_mov_b32_e32 v170, v32
	v_mov_b32_e32 v171, v52
	v_pk_mul_f32 v[170:171], v[170:171], v[172:173]
	v_mov_b32_e32 v172, v188
	v_add_f32_e32 v170, v170, v171
	v_mul_f32_e32 v175, v169, v170
	v_mov_b32_e32 v170, v53
	v_mov_b32_e32 v171, v33
	v_pk_mul_f32 v[170:171], v[170:171], v[196:197]
	v_mov_b32_e32 v173, v198
	v_sub_f32_e32 v170, v170, v171
	v_mul_f32_e32 v176, v169, v170
	v_mov_b32_e32 v170, v33
	v_mov_b32_e32 v171, v53
	v_pk_mul_f32 v[170:171], v[170:171], v[196:197]
	v_mov_b32_e32 v198, v189
	v_add_f32_e32 v170, v170, v171
	v_mul_f32_e32 v177, v169, v170
	v_mov_b32_e32 v170, v54
	v_mov_b32_e32 v171, v34
	v_pk_mul_f32 v[170:171], v[170:171], v[172:173]
	s_nop 0
	v_sub_f32_e32 v170, v170, v171
	v_mul_f32_e32 v178, v169, v170
	v_mov_b32_e32 v170, v34
	v_mov_b32_e32 v171, v54
	v_pk_mul_f32 v[170:171], v[170:171], v[172:173]
	v_mov_b32_e32 v172, v164
	v_add_f32_e32 v170, v170, v171
	v_mul_f32_e32 v179, v169, v170
	v_mov_b32_e32 v170, v55
	v_mov_b32_e32 v171, v35
	v_pk_mul_f32 v[170:171], v[170:171], v[198:199]
	v_mov_b32_e32 v173, v160
	v_sub_f32_e32 v170, v170, v171
	v_mul_f32_e32 v180, v169, v170
	v_mov_b32_e32 v170, v35
	v_mov_b32_e32 v171, v55
	v_pk_mul_f32 v[170:171], v[170:171], v[198:199]
	s_nop 0
	v_add_f32_e32 v170, v170, v171
	v_mul_f32_e32 v181, v169, v170
	v_mov_b32_e32 v170, v44
	v_mov_b32_e32 v171, v24
	v_pk_mul_f32 v[170:171], v[170:171], v[172:173]
	s_nop 0
	v_sub_f32_e32 v160, v170, v171
	v_mov_b32_e32 v170, v24
	v_mov_b32_e32 v171, v44
	v_pk_mul_f32 v[170:171], v[170:171], v[172:173]
	v_mul_f32_e32 v182, v169, v160
	v_add_f32_e32 v160, v170, v171
	v_mul_f32_e32 v172, v169, v160
	v_mov_b32_e32 v170, v45
	v_mov_b32_e32 v171, v25
	v_mov_b32_e32 v160, v165
	v_pk_mul_f32 v[164:165], v[170:171], v[160:161]
	s_nop 0
	v_sub_f32_e32 v164, v164, v165
	v_mul_f32_e32 v170, v169, v164
	v_mov_b32_e32 v164, v25
	v_mov_b32_e32 v165, v45
	v_pk_mul_f32 v[160:161], v[164:165], v[160:161]
	v_mov_b32_e32 v164, v166
	v_add_f32_e32 v160, v160, v161
	v_mul_f32_e32 v171, v169, v160
	v_mov_b32_e32 v160, v46
	v_mov_b32_e32 v161, v26
	v_mov_b32_e32 v165, v162
	v_pk_mul_f32 v[160:161], v[160:161], v[164:165]
	v_mov_b32_e32 v162, v167
	v_sub_f32_e32 v160, v160, v161
	v_mul_f32_e32 v166, v169, v160
	v_mov_b32_e32 v160, v26
	v_mov_b32_e32 v161, v46
	v_pk_mul_f32 v[160:161], v[160:161], v[164:165]
	s_nop 0
	v_add_f32_e32 v160, v160, v161
	v_mul_f32_e32 v173, v169, v160
	v_mov_b32_e32 v160, v47
	v_mov_b32_e32 v161, v27
	v_pk_mul_f32 v[160:161], v[160:161], v[162:163]
	s_nop 0
	v_sub_f32_e32 v160, v160, v161
	v_mul_f32_e32 v164, v169, v160
	v_mov_b32_e32 v160, v27
	v_mov_b32_e32 v161, v47
	v_pk_mul_f32 v[160:161], v[160:161], v[162:163]
	s_nop 0
	v_add_f32_e32 v160, v160, v161
	v_mul_f32_e32 v167, v169, v160
	v_ashrrev_i32_e32 v169, 31, v168
	v_lshlrev_b64 v[168:169], 12, v[168:169]
	v_cvt_pk_bf16_f32 v160, v174, v176
	v_cvt_pk_bf16_f32 v161, v178, v180
	v_cvt_pk_bf16_f32 v162, v182, v170
	v_cvt_pk_bf16_f32 v163, v166, v164
	v_lshl_add_u64 v[168:169], v[230:231], 0, v[168:169]
	v_cvt_pk_bf16_f32 v164, v175, v177
	v_cvt_pk_bf16_f32 v165, v179, v181
	v_cvt_pk_bf16_f32 v166, v172, v171
	v_cvt_pk_bf16_f32 v167, v173, v167
	global_store_dwordx4 v[168:169], v[160:163], off
	global_store_dwordx4 v[168:169], v[164:167], off offset:256
	s_nop 0
	v_add_u32_e32 v160, 0xa0, v228
	v_and_b32_e32 v161, 0x6f, v160
	v_add_u32_e32 v161, 1, v161
	v_cvt_f32_ubyte0_e32 v161, v161
	v_mul_f32_e64 v162, v241, -v161
	v_cmp_gt_f32_e64 s[4:5], s7, v162
	v_mov_b32_e32 v163, v16
	v_mov_b32_e32 v164, v156
	v_cndmask_b32_e64 v162, 0, v234, s[4:5]
	v_fma_f32 v161, v241, -v161, v162
	v_exp_f32_e32 v161, v161
	v_cndmask_b32_e64 v162, 0, v235, s[4:5]
	v_mov_b32_e32 v165, v152
	v_ldexp_f32 v161, v161, v162
	v_mov_b32_e32 v162, v36
	v_pk_mul_f32 v[162:163], v[162:163], v[164:165]
	v_mul_f32_e32 v161, 0x3d800000, v161
	v_sub_f32_e32 v152, v162, v163
	v_mov_b32_e32 v162, v16
	v_mov_b32_e32 v163, v36
	v_cndmask_b32_e32 v161, 1.0, v161, vcc
	v_pk_mul_f32 v[162:163], v[162:163], v[164:165]
	v_mul_f32_e32 v166, v161, v152
	v_add_f32_e32 v152, v162, v163
	v_mul_f32_e32 v164, v161, v152
	v_mov_b32_e32 v162, v37
	v_mov_b32_e32 v163, v17
	v_mov_b32_e32 v152, v157
	v_pk_mul_f32 v[156:157], v[162:163], v[152:153]
	s_nop 0
	v_sub_f32_e32 v156, v156, v157
	v_mul_f32_e32 v162, v161, v156
	v_mov_b32_e32 v156, v17
	v_mov_b32_e32 v157, v37
	v_pk_mul_f32 v[152:153], v[156:157], v[152:153]
	v_mov_b32_e32 v156, v158
	v_add_f32_e32 v152, v152, v153
	v_mul_f32_e32 v163, v161, v152
	v_mov_b32_e32 v152, v38
	v_mov_b32_e32 v153, v18
	v_mov_b32_e32 v157, v154
	v_pk_mul_f32 v[152:153], v[152:153], v[156:157]
	v_mov_b32_e32 v154, v159
	v_sub_f32_e32 v152, v152, v153
	v_mul_f32_e32 v158, v161, v152
	v_mov_b32_e32 v152, v18
	v_mov_b32_e32 v153, v38
	v_pk_mul_f32 v[152:153], v[152:153], v[156:157]
	s_nop 0
	v_add_f32_e32 v152, v152, v153
	v_mul_f32_e32 v156, v161, v152
	v_mov_b32_e32 v152, v39
	v_mov_b32_e32 v153, v19
	v_pk_mul_f32 v[152:153], v[152:153], v[154:155]
	s_nop 0
	v_sub_f32_e32 v152, v152, v153
	v_mul_f32_e32 v157, v161, v152
	v_mov_b32_e32 v152, v19
	v_mov_b32_e32 v153, v39
	v_pk_mul_f32 v[152:153], v[152:153], v[154:155]
	v_mov_b32_e32 v154, v148
	v_add_f32_e32 v152, v152, v153
	v_mul_f32_e32 v159, v161, v152
	v_mov_b32_e32 v152, v28
	v_mov_b32_e32 v153, v8
	v_mov_b32_e32 v155, v144
	v_pk_mul_f32 v[152:153], v[152:153], v[154:155]
	s_nop 0
	v_sub_f32_e32 v144, v152, v153
	v_mov_b32_e32 v152, v8
	v_mov_b32_e32 v153, v28
	v_pk_mul_f32 v[152:153], v[152:153], v[154:155]
	v_mul_f32_e32 v165, v161, v144
	v_add_f32_e32 v144, v152, v153
	v_mul_f32_e32 v154, v161, v144
	v_mov_b32_e32 v152, v29
	v_mov_b32_e32 v153, v9
	v_mov_b32_e32 v144, v149
	v_pk_mul_f32 v[148:149], v[152:153], v[144:145]
	s_nop 0
	v_sub_f32_e32 v148, v148, v149
	v_mul_f32_e32 v152, v161, v148
	v_mov_b32_e32 v148, v9
	v_mov_b32_e32 v149, v29
	v_pk_mul_f32 v[144:145], v[148:149], v[144:145]
	v_mov_b32_e32 v148, v150
	v_add_f32_e32 v144, v144, v145
	v_mul_f32_e32 v153, v161, v144
	v_mov_b32_e32 v144, v30
	v_mov_b32_e32 v145, v10
	v_mov_b32_e32 v149, v146
	v_pk_mul_f32 v[144:145], v[144:145], v[148:149]
	v_mov_b32_e32 v146, v151
	v_sub_f32_e32 v144, v144, v145
	v_mul_f32_e32 v150, v161, v144
	v_mov_b32_e32 v144, v10
	v_mov_b32_e32 v145, v30
	v_pk_mul_f32 v[144:145], v[144:145], v[148:149]
	s_nop 0
	v_add_f32_e32 v144, v144, v145
	v_mul_f32_e32 v155, v161, v144
	v_mov_b32_e32 v144, v31
	v_mov_b32_e32 v145, v11
	v_pk_mul_f32 v[144:145], v[144:145], v[146:147]
	s_nop 0
	v_sub_f32_e32 v144, v144, v145
	v_mul_f32_e32 v148, v161, v144
	v_mov_b32_e32 v144, v11
	v_mov_b32_e32 v145, v31
	v_pk_mul_f32 v[144:145], v[144:145], v[146:147]
	s_nop 0
	v_add_f32_e32 v144, v144, v145
	v_mul_f32_e32 v151, v161, v144
	v_ashrrev_i32_e32 v161, 31, v160
	v_cvt_pk_bf16_f32 v144, v166, v162
	v_cvt_pk_bf16_f32 v145, v158, v157
	v_cvt_pk_bf16_f32 v146, v165, v152
	v_cvt_pk_bf16_f32 v147, v150, v148
	v_cvt_pk_bf16_f32 v148, v164, v163
	v_cvt_pk_bf16_f32 v149, v156, v159
	v_cvt_pk_bf16_f32 v150, v154, v153
	v_lshlrev_b64 v[152:153], 12, v[160:161]
	v_lshl_add_u64 v[152:153], v[230:231], 0, v[152:153]
	v_cvt_pk_bf16_f32 v151, v155, v151
	global_store_dwordx4 v[152:153], v[144:147], off
	global_store_dwordx4 v[152:153], v[148:151], off offset:256
	s_nop 0
	v_add_u32_e32 v144, 0xb0, v228
	v_and_b32_e32 v145, 0x7f, v144
	v_add_u32_e32 v145, 1, v145
	v_cvt_f32_ubyte0_e32 v145, v145
	v_mul_f32_e64 v146, v241, -v145
	v_cmp_gt_f32_e64 s[4:5], s7, v146
	v_mov_b32_e32 v147, v4
	v_mov_b32_e32 v148, v140
	v_cndmask_b32_e64 v146, 0, v234, s[4:5]
	v_fma_f32 v145, v241, -v145, v146
	v_exp_f32_e32 v145, v145
	v_cndmask_b32_e64 v146, 0, v235, s[4:5]
	v_mov_b32_e32 v149, v136
	s_mov_b64 s[4:5], 0
	v_ldexp_f32 v145, v145, v146
	v_mov_b32_e32 v146, v20
	v_pk_mul_f32 v[146:147], v[146:147], v[148:149]
	v_mul_f32_e32 v145, 0x3d800000, v145
	v_sub_f32_e32 v136, v146, v147
	v_mov_b32_e32 v146, v4
	v_mov_b32_e32 v147, v20
	v_cndmask_b32_e32 v145, 1.0, v145, vcc
	v_pk_mul_f32 v[146:147], v[146:147], v[148:149]
	v_mul_f32_e32 v150, v145, v136
	v_add_f32_e32 v136, v146, v147
	v_mul_f32_e32 v148, v145, v136
	v_mov_b32_e32 v146, v21
	v_mov_b32_e32 v147, v5
	v_mov_b32_e32 v136, v141
	v_pk_mul_f32 v[140:141], v[146:147], v[136:137]
	s_nop 0
	v_sub_f32_e32 v140, v140, v141
	v_mul_f32_e32 v146, v145, v140
	v_mov_b32_e32 v140, v5
	v_mov_b32_e32 v141, v21
	v_pk_mul_f32 v[136:137], v[140:141], v[136:137]
	v_mov_b32_e32 v140, v142
	v_add_f32_e32 v136, v136, v137
	v_mul_f32_e32 v147, v145, v136
	v_mov_b32_e32 v136, v22
	v_mov_b32_e32 v137, v6
	v_mov_b32_e32 v141, v138
	v_pk_mul_f32 v[136:137], v[136:137], v[140:141]
	v_mov_b32_e32 v138, v143
	v_sub_f32_e32 v136, v136, v137
	v_mul_f32_e32 v142, v145, v136
	v_mov_b32_e32 v136, v6
	v_mov_b32_e32 v137, v22
	v_pk_mul_f32 v[136:137], v[136:137], v[140:141]
	s_nop 0
	v_add_f32_e32 v136, v136, v137
	v_mul_f32_e32 v140, v145, v136
	v_mov_b32_e32 v136, v23
	v_mov_b32_e32 v137, v7
	v_pk_mul_f32 v[136:137], v[136:137], v[138:139]
	s_nop 0
	v_sub_f32_e32 v136, v136, v137
	v_mul_f32_e32 v141, v145, v136
	v_mov_b32_e32 v136, v7
	v_mov_b32_e32 v137, v23
	v_pk_mul_f32 v[136:137], v[136:137], v[138:139]
	v_mov_b32_e32 v138, v132
	v_add_f32_e32 v136, v136, v137
	v_mul_f32_e32 v143, v145, v136
	v_mov_b32_e32 v136, v12
	v_mov_b32_e32 v137, v0
	v_mov_b32_e32 v139, v128
	v_pk_mul_f32 v[136:137], v[136:137], v[138:139]
	s_nop 0
	v_sub_f32_e32 v128, v136, v137
	v_mov_b32_e32 v136, v0
	v_mov_b32_e32 v137, v12
	v_pk_mul_f32 v[136:137], v[136:137], v[138:139]
	v_mul_f32_e32 v149, v145, v128
	v_add_f32_e32 v128, v136, v137
	v_mul_f32_e32 v138, v145, v128
	v_mov_b32_e32 v136, v13
	v_mov_b32_e32 v137, v1
	v_mov_b32_e32 v128, v133
	v_pk_mul_f32 v[132:133], v[136:137], v[128:129]
	s_nop 0
	v_sub_f32_e32 v132, v132, v133
	v_mul_f32_e32 v136, v145, v132
	v_mov_b32_e32 v132, v1
	v_mov_b32_e32 v133, v13
	v_pk_mul_f32 v[128:129], v[132:133], v[128:129]
	v_mov_b32_e32 v132, v134
	v_add_f32_e32 v128, v128, v129
	v_mul_f32_e32 v139, v145, v128
	v_mov_b32_e32 v128, v14
	v_mov_b32_e32 v129, v2
	v_mov_b32_e32 v133, v130
	v_pk_mul_f32 v[128:129], v[128:129], v[132:133]
	v_mov_b32_e32 v130, v135
	v_sub_f32_e32 v128, v128, v129
	v_mul_f32_e32 v137, v145, v128
	v_mov_b32_e32 v128, v2
	v_mov_b32_e32 v129, v14
	v_pk_mul_f32 v[128:129], v[128:129], v[132:133]
	v_cvt_pk_bf16_f32 v134, v150, v146
	v_cvt_pk_bf16_f32 v135, v142, v141
	v_cvt_pk_bf16_f32 v136, v149, v136
	s_nop 0
	v_add_f32_e32 v128, v128, v129
	v_mul_f32_e32 v132, v145, v128
	v_mov_b32_e32 v128, v15
	v_mov_b32_e32 v129, v3
	v_pk_mul_f32 v[128:129], v[128:129], v[130:131]
	s_nop 0
	v_sub_f32_e32 v128, v128, v129
	v_mul_f32_e32 v133, v145, v128
	v_mov_b32_e32 v128, v3
	v_mov_b32_e32 v129, v15
	v_pk_mul_f32 v[128:129], v[128:129], v[130:131]
	v_cvt_pk_bf16_f32 v137, v137, v133
	s_nop 0
	v_add_f32_e32 v128, v128, v129
	v_mul_f32_e32 v131, v145, v128
	v_ashrrev_i32_e32 v145, 31, v144
	v_cvt_pk_bf16_f32 v128, v148, v147
	v_cvt_pk_bf16_f32 v129, v140, v143
	v_cvt_pk_bf16_f32 v130, v138, v139
	v_cvt_pk_bf16_f32 v131, v132, v131
	v_lshlrev_b64 v[132:133], 12, v[144:145]
	v_lshl_add_u64 v[132:133], v[230:231], 0, v[132:133]
	global_store_dwordx4 v[132:133], v[134:137], off

.LBB0_217:
	s_add_u32 s16, s14, 0xfff80080
	s_addc_u32 s17, s15, -1
	s_add_i32 s41, 0, 0x10000
	v_add_u32_e32 v138, s41, v141
	ds_read_b128 v[144:147], v138
	ds_read_b128 v[148:151], v138 offset:1024
	ds_read_b128 v[152:155], v138 offset:2048
	ds_read_b128 v[156:159], v138 offset:3072
	s_cmp_eq_u32 s40, 28
	s_cselect_b32 s19, s7, s17
	s_cselect_b32 s18, s36, s16
	s_cselect_b32 s17, s5, s39
	s_cselect_b32 s16, s37, s38
	s_add_i32 m0, s13, 0xc000
	ds_read_b128 v[160:163], v143
	ds_read_b128 v[164:167], v143 offset:1024
	ds_read_b128 v[168:171], v143 offset:2048
	ds_read_b128 v[172:175], v143 offset:3072
	ds_read_b128 v[176:179], v143 offset:4096
	ds_read_b128 v[180:183], v143 offset:5120
	ds_read_b128 v[184:187], v143 offset:6144
	ds_read_b128 v[188:191], v143 offset:7168
	global_load_lds_dwordx4 v134, s[14:15]
	s_add_i32 m0, s13, 0xe000
	s_nop 0
	global_load_lds_dwordx4 v136, s[14:15]
	s_waitcnt lgkmcnt(8)
	s_barrier
	s_waitcnt lgkmcnt(0)
	s_waitcnt lgkmcnt(0)
	v_mfma_f32_16x16x32_bf16 v[124:127], v[144:147], v[160:163], v[124:127]
	v_mfma_f32_16x16x32_bf16 v[116:119], v[152:155], v[160:163], v[116:119]
	v_mfma_f32_16x16x32_bf16 v[108:111], v[144:147], v[168:171], v[108:111]
	v_mfma_f32_16x16x32_bf16 v[100:103], v[152:155], v[168:171], v[100:103]
	v_mfma_f32_16x16x32_bf16 v[92:95], v[144:147], v[176:179], v[92:95]
	v_mfma_f32_16x16x32_bf16 v[84:87], v[152:155], v[176:179], v[84:87]
	v_mfma_f32_16x16x32_bf16 v[76:79], v[144:147], v[184:187], v[76:79]
	v_mfma_f32_16x16x32_bf16 v[68:71], v[152:155], v[184:187], v[68:71]
	v_mfma_f32_16x16x32_bf16 v[124:127], v[148:151], v[164:167], v[124:127]
	v_mfma_f32_16x16x32_bf16 v[116:119], v[156:159], v[164:167], v[116:119]
	v_mfma_f32_16x16x32_bf16 v[108:111], v[148:151], v[172:175], v[108:111]
	v_mfma_f32_16x16x32_bf16 v[100:103], v[156:159], v[172:175], v[100:103]
	v_mfma_f32_16x16x32_bf16 v[92:95], v[148:151], v[180:183], v[92:95]
	v_mfma_f32_16x16x32_bf16 v[84:87], v[156:159], v[180:183], v[84:87]
	v_mfma_f32_16x16x32_bf16 v[76:79], v[148:151], v[188:191], v[76:79]
	v_mfma_f32_16x16x32_bf16 v[68:71], v[156:159], v[188:191], v[68:71]
	s_barrier
	s_add_i32 s44, 0, 0x14000
	v_add_u32_e32 v138, s44, v141
	s_add_i32 s41, s41, s26
	ds_read_b128 v[196:199], v138
	ds_read_b128 v[204:207], v138 offset:1024
	ds_read_b128 v[208:211], v138 offset:2048
	ds_read_b128 v[214:217], v138 offset:3072
	s_mov_b32 m0, s41
	s_nop 0
	global_load_lds_dwordx4 v192, s[16:17]
	s_add_i32 m0, s41, 0x2000
	s_nop 0
	global_load_lds_dwordx4 v128, s[16:17]
	s_barrier
	s_waitcnt lgkmcnt(0)
	s_waitcnt lgkmcnt(0)
	v_mfma_f32_16x16x32_bf16 v[120:123], v[196:199], v[160:163], v[120:123]
	v_mfma_f32_16x16x32_bf16 v[112:115], v[208:211], v[160:163], v[112:115]
	v_mfma_f32_16x16x32_bf16 v[104:107], v[196:199], v[168:171], v[104:107]
	v_mfma_f32_16x16x32_bf16 v[96:99], v[208:211], v[168:171], v[96:99]
	v_mfma_f32_16x16x32_bf16 v[88:91], v[196:199], v[176:179], v[88:91]
	v_mfma_f32_16x16x32_bf16 v[80:83], v[208:211], v[176:179], v[80:83]
	v_mfma_f32_16x16x32_bf16 v[72:75], v[196:199], v[184:187], v[72:75]
	v_mfma_f32_16x16x32_bf16 v[64:67], v[208:211], v[184:187], v[64:67]
	v_mfma_f32_16x16x32_bf16 v[120:123], v[204:207], v[164:167], v[120:123]
	v_mfma_f32_16x16x32_bf16 v[112:115], v[214:217], v[164:167], v[112:115]
	v_mfma_f32_16x16x32_bf16 v[104:107], v[204:207], v[172:175], v[104:107]
	v_mfma_f32_16x16x32_bf16 v[96:99], v[214:217], v[172:175], v[96:99]
	v_mfma_f32_16x16x32_bf16 v[88:91], v[204:207], v[180:183], v[88:91]
	v_mfma_f32_16x16x32_bf16 v[80:83], v[214:217], v[180:183], v[80:83]
	v_mfma_f32_16x16x32_bf16 v[72:75], v[204:207], v[188:191], v[72:75]
	v_mfma_f32_16x16x32_bf16 v[64:67], v[214:217], v[188:191], v[64:67]
	s_mov_b32 m0, s13
	v_lshl_add_u64 v[220:221], s[18:19], 0, v[132:133]
	s_barrier
	ds_read_b128 v[160:163], v143 offset:16384
	ds_read_b128 v[164:167], v143 offset:17408
	ds_read_b128 v[168:171], v143 offset:18432
	ds_read_b128 v[172:175], v143 offset:19456
	ds_read_b128 v[176:179], v143 offset:20480
	ds_read_b128 v[180:183], v143 offset:21504
	ds_read_b128 v[184:187], v143 offset:22528
	ds_read_b128 v[188:191], v143 offset:23552
	global_load_lds_dwordx4 v132, s[18:19]
	v_lshl_add_u64 v[222:223], s[18:19], 0, v[130:131]
	s_mov_b32 m0, s28
	s_nop 0
	global_load_lds_dwordx4 v130, s[18:19]
	s_barrier
	s_waitcnt lgkmcnt(0)
	s_waitcnt lgkmcnt(0)
	v_mfma_f32_16x16x32_bf16 v[60:63], v[144:147], v[160:163], v[60:63]
	v_mfma_f32_16x16x32_bf16 v[52:55], v[152:155], v[160:163], v[52:55]
	v_mfma_f32_16x16x32_bf16 v[44:47], v[144:147], v[168:171], v[44:47]
	v_mfma_f32_16x16x32_bf16 v[36:39], v[152:155], v[168:171], v[36:39]
	v_mfma_f32_16x16x32_bf16 v[28:31], v[144:147], v[176:179], v[28:31]
	v_mfma_f32_16x16x32_bf16 v[20:23], v[152:155], v[176:179], v[20:23]
	v_mfma_f32_16x16x32_bf16 v[12:15], v[144:147], v[184:187], v[12:15]
	v_mfma_f32_16x16x32_bf16 v[4:7], v[152:155], v[184:187], v[4:7]
	v_mfma_f32_16x16x32_bf16 v[60:63], v[148:151], v[164:167], v[60:63]
	v_mfma_f32_16x16x32_bf16 v[52:55], v[156:159], v[164:167], v[52:55]
	v_mfma_f32_16x16x32_bf16 v[44:47], v[148:151], v[172:175], v[44:47]
	v_mfma_f32_16x16x32_bf16 v[36:39], v[156:159], v[172:175], v[36:39]
	v_mfma_f32_16x16x32_bf16 v[28:31], v[148:151], v[180:183], v[28:31]
	v_mfma_f32_16x16x32_bf16 v[20:23], v[156:159], v[180:183], v[20:23]
	v_mfma_f32_16x16x32_bf16 v[12:15], v[148:151], v[188:191], v[12:15]
	v_mfma_f32_16x16x32_bf16 v[4:7], v[156:159], v[188:191], v[4:7]
	s_barrier
	s_add_u32 s42, s16, 0x80000
	s_addc_u32 s43, s17, 0
	s_add_i32 s41, s44, s26
	s_mov_b32 m0, s41
	s_nop 0
	global_load_lds_dwordx4 v192, s[42:43]
	s_add_i32 m0, s41, 0x2000
	s_nop 0
	global_load_lds_dwordx4 v128, s[42:43]
	s_waitcnt vmcnt(6)
	s_barrier
	v_mfma_f32_16x16x32_bf16 v[56:59], v[196:199], v[160:163], v[56:59]
	v_mfma_f32_16x16x32_bf16 v[48:51], v[208:211], v[160:163], v[48:51]
	v_mfma_f32_16x16x32_bf16 v[40:43], v[196:199], v[168:171], v[40:43]
	v_mfma_f32_16x16x32_bf16 v[32:35], v[208:211], v[168:171], v[32:35]
	v_mfma_f32_16x16x32_bf16 v[24:27], v[196:199], v[176:179], v[24:27]
	v_mfma_f32_16x16x32_bf16 v[16:19], v[208:211], v[176:179], v[16:19]
	v_mfma_f32_16x16x32_bf16 v[8:11], v[196:199], v[184:187], v[8:11]
	v_mfma_f32_16x16x32_bf16 v[0:3], v[208:211], v[184:187], v[0:3]
	v_mfma_f32_16x16x32_bf16 v[56:59], v[204:207], v[164:167], v[56:59]
	v_mfma_f32_16x16x32_bf16 v[48:51], v[214:217], v[164:167], v[48:51]
	v_mfma_f32_16x16x32_bf16 v[40:43], v[204:207], v[172:175], v[40:43]
	v_mfma_f32_16x16x32_bf16 v[32:35], v[214:217], v[172:175], v[32:35]
	v_mfma_f32_16x16x32_bf16 v[24:27], v[204:207], v[180:183], v[24:27]
	v_mfma_f32_16x16x32_bf16 v[16:19], v[214:217], v[180:183], v[16:19]
	v_mfma_f32_16x16x32_bf16 v[8:11], v[204:207], v[188:191], v[8:11]
	v_mfma_f32_16x16x32_bf16 v[0:3], v[214:217], v[188:191], v[0:3]
	s_add_i32 s41, 0, 0x18000
	v_add_u32_e32 v156, s41, v141
	s_barrier
	ds_read_b128 v[144:147], v156
	ds_read_b128 v[148:151], v156 offset:1024
	ds_read_b128 v[152:155], v156 offset:2048
	ds_read_b128 v[156:159], v156 offset:3072
	s_add_u32 s18, s18, 0x80000
	s_addc_u32 s19, s19, 0
	s_mov_b32 m0, s29
	ds_read_b128 v[160:163], v143 offset:32768
	ds_read_b128 v[164:167], v143 offset:33792
	ds_read_b128 v[168:171], v143 offset:34816
	ds_read_b128 v[172:175], v143 offset:35840
	ds_read_b128 v[176:179], v143 offset:36864
	ds_read_b128 v[180:183], v143 offset:37888
	ds_read_b128 v[184:187], v143 offset:38912
	ds_read_b128 v[188:191], v143 offset:39936
	global_load_lds_dwordx4 v132, s[18:19]
	s_mov_b32 m0, s30
	s_nop 0
	global_load_lds_dwordx4 v130, s[18:19]
	s_waitcnt lgkmcnt(8)
	s_barrier
	s_waitcnt lgkmcnt(0)
	s_waitcnt lgkmcnt(0)
	v_mfma_f32_16x16x32_bf16 v[124:127], v[144:147], v[160:163], v[124:127]
	v_mfma_f32_16x16x32_bf16 v[116:119], v[152:155], v[160:163], v[116:119]
	v_mfma_f32_16x16x32_bf16 v[108:111], v[144:147], v[168:171], v[108:111]
	v_mfma_f32_16x16x32_bf16 v[100:103], v[152:155], v[168:171], v[100:103]
	v_mfma_f32_16x16x32_bf16 v[92:95], v[144:147], v[176:179], v[92:95]
	v_mfma_f32_16x16x32_bf16 v[84:87], v[152:155], v[176:179], v[84:87]
	v_mfma_f32_16x16x32_bf16 v[76:79], v[144:147], v[184:187], v[76:79]
	v_mfma_f32_16x16x32_bf16 v[68:71], v[152:155], v[184:187], v[68:71]
	v_mfma_f32_16x16x32_bf16 v[124:127], v[148:151], v[164:167], v[124:127]
	v_mfma_f32_16x16x32_bf16 v[116:119], v[156:159], v[164:167], v[116:119]
	v_mfma_f32_16x16x32_bf16 v[108:111], v[148:151], v[172:175], v[108:111]
	v_mfma_f32_16x16x32_bf16 v[100:103], v[156:159], v[172:175], v[100:103]
	v_mfma_f32_16x16x32_bf16 v[92:95], v[148:151], v[180:183], v[92:95]
	v_mfma_f32_16x16x32_bf16 v[84:87], v[156:159], v[180:183], v[84:87]
	v_mfma_f32_16x16x32_bf16 v[76:79], v[148:151], v[188:191], v[76:79]
	v_mfma_f32_16x16x32_bf16 v[68:71], v[156:159], v[188:191], v[68:71]
	s_barrier
	s_add_i32 s18, 0, 0x1c000
	s_add_i32 s19, s41, s26
	v_add_u32_e32 v212, s18, v141
	s_add_i32 m0, s19, 0xffffff80
	ds_read_b128 v[196:199], v212
	ds_read_b128 v[204:207], v212 offset:1024
	ds_read_b128 v[208:211], v212 offset:2048
	ds_read_b128 v[214:217], v212 offset:3072
	global_load_lds_dwordx4 v192, s[16:17] offset:128
	s_add_i32 m0, s19, 0x1f80
	s_nop 0
	global_load_lds_dwordx4 v128, s[16:17] offset:128
	s_barrier
	s_waitcnt lgkmcnt(0)
	s_waitcnt lgkmcnt(0)
	v_mfma_f32_16x16x32_bf16 v[120:123], v[196:199], v[160:163], v[120:123]
	v_mfma_f32_16x16x32_bf16 v[112:115], v[208:211], v[160:163], v[112:115]
	v_mfma_f32_16x16x32_bf16 v[104:107], v[196:199], v[168:171], v[104:107]
	v_mfma_f32_16x16x32_bf16 v[96:99], v[208:211], v[168:171], v[96:99]
	v_mfma_f32_16x16x32_bf16 v[88:91], v[196:199], v[176:179], v[88:91]
	v_mfma_f32_16x16x32_bf16 v[80:83], v[208:211], v[176:179], v[80:83]
	v_mfma_f32_16x16x32_bf16 v[72:75], v[196:199], v[184:187], v[72:75]
	v_mfma_f32_16x16x32_bf16 v[64:67], v[208:211], v[184:187], v[64:67]
	v_mfma_f32_16x16x32_bf16 v[120:123], v[204:207], v[164:167], v[120:123]
	v_mfma_f32_16x16x32_bf16 v[112:115], v[214:217], v[164:167], v[112:115]
	v_mfma_f32_16x16x32_bf16 v[104:107], v[204:207], v[172:175], v[104:107]
	v_mfma_f32_16x16x32_bf16 v[96:99], v[214:217], v[172:175], v[96:99]
	v_mfma_f32_16x16x32_bf16 v[88:91], v[204:207], v[180:183], v[88:91]
	v_mfma_f32_16x16x32_bf16 v[80:83], v[214:217], v[180:183], v[80:83]
	v_mfma_f32_16x16x32_bf16 v[72:75], v[204:207], v[188:191], v[72:75]
	v_mfma_f32_16x16x32_bf16 v[64:67], v[214:217], v[188:191], v[64:67]
	s_mov_b32 m0, s33
	v_lshl_add_u64 v[138:139], v[220:221], 0, s[48:49]
	s_barrier
	ds_read_b128 v[160:163], v143 offset:49152
	ds_read_b128 v[164:167], v143 offset:50176
	ds_read_b128 v[168:171], v143 offset:51200
	ds_read_b128 v[172:175], v143 offset:52224
	ds_read_b128 v[176:179], v143 offset:53248
	ds_read_b128 v[180:183], v143 offset:54272
	ds_read_b128 v[184:187], v143 offset:55296
	ds_read_b128 v[188:191], v143 offset:56320
	global_load_lds_dwordx4 v[138:139], off
	v_lshl_add_u64 v[138:139], v[222:223], 0, s[48:49]
	s_mov_b32 m0, s34
	s_nop 0
	global_load_lds_dwordx4 v[138:139], off
	s_barrier
	s_waitcnt lgkmcnt(0)
	s_waitcnt lgkmcnt(0)
	v_mfma_f32_16x16x32_bf16 v[60:63], v[144:147], v[160:163], v[60:63]
	v_mfma_f32_16x16x32_bf16 v[52:55], v[152:155], v[160:163], v[52:55]
	v_mfma_f32_16x16x32_bf16 v[44:47], v[144:147], v[168:171], v[44:47]
	v_mfma_f32_16x16x32_bf16 v[36:39], v[152:155], v[168:171], v[36:39]
	v_mfma_f32_16x16x32_bf16 v[28:31], v[144:147], v[176:179], v[28:31]
	v_mfma_f32_16x16x32_bf16 v[20:23], v[152:155], v[176:179], v[20:23]
	v_mfma_f32_16x16x32_bf16 v[12:15], v[144:147], v[184:187], v[12:15]
	v_mfma_f32_16x16x32_bf16 v[4:7], v[152:155], v[184:187], v[4:7]
	v_mfma_f32_16x16x32_bf16 v[60:63], v[148:151], v[164:167], v[60:63]
	v_mfma_f32_16x16x32_bf16 v[52:55], v[156:159], v[164:167], v[52:55]
	v_mfma_f32_16x16x32_bf16 v[44:47], v[148:151], v[172:175], v[44:47]
	v_mfma_f32_16x16x32_bf16 v[36:39], v[156:159], v[172:175], v[36:39]
	v_mfma_f32_16x16x32_bf16 v[28:31], v[148:151], v[180:183], v[28:31]
	v_mfma_f32_16x16x32_bf16 v[20:23], v[156:159], v[180:183], v[20:23]
	v_mfma_f32_16x16x32_bf16 v[12:15], v[148:151], v[188:191], v[12:15]
	v_mfma_f32_16x16x32_bf16 v[4:7], v[156:159], v[188:191], v[4:7]
	s_barrier
	s_add_u32 s16, s16, 0x80080
	s_addc_u32 s17, s17, 0
	s_add_i32 s18, s18, s26
	s_mov_b32 m0, s18
	s_nop 0
	global_load_lds_dwordx4 v192, s[16:17]
	s_add_i32 m0, s18, 0x2000
	s_nop 0
	global_load_lds_dwordx4 v128, s[16:17]
	s_waitcnt vmcnt(6)
	s_barrier
	v_mfma_f32_16x16x32_bf16 v[56:59], v[196:199], v[160:163], v[56:59]
	v_mfma_f32_16x16x32_bf16 v[48:51], v[208:211], v[160:163], v[48:51]
	v_mfma_f32_16x16x32_bf16 v[40:43], v[196:199], v[168:171], v[40:43]
	v_mfma_f32_16x16x32_bf16 v[32:35], v[208:211], v[168:171], v[32:35]
	v_mfma_f32_16x16x32_bf16 v[24:27], v[196:199], v[176:179], v[24:27]
	v_mfma_f32_16x16x32_bf16 v[16:19], v[208:211], v[176:179], v[16:19]
	v_mfma_f32_16x16x32_bf16 v[8:11], v[196:199], v[184:187], v[8:11]
	v_mfma_f32_16x16x32_bf16 v[0:3], v[208:211], v[184:187], v[0:3]
	v_mfma_f32_16x16x32_bf16 v[56:59], v[204:207], v[164:167], v[56:59]
	v_mfma_f32_16x16x32_bf16 v[48:51], v[214:217], v[164:167], v[48:51]
	v_mfma_f32_16x16x32_bf16 v[40:43], v[204:207], v[172:175], v[40:43]
	v_mfma_f32_16x16x32_bf16 v[32:35], v[214:217], v[172:175], v[32:35]
	v_mfma_f32_16x16x32_bf16 v[24:27], v[204:207], v[180:183], v[24:27]
	v_mfma_f32_16x16x32_bf16 v[16:19], v[214:217], v[180:183], v[16:19]
	v_mfma_f32_16x16x32_bf16 v[8:11], v[204:207], v[188:191], v[8:11]
	v_mfma_f32_16x16x32_bf16 v[0:3], v[214:217], v[188:191], v[0:3]
	s_add_i32 s40, s40, 2
	s_add_u32 s14, s14, 0x100
	s_addc_u32 s15, s15, 0
	s_add_u32 s38, s38, 0x100
	s_addc_u32 s39, s39, 0
	s_cmp_gt_u32 s40, 29
	s_barrier
	s_cbranch_scc0 .LBB0_217
	v_mul_f32_e32 v145, 0xbfb8aa3b, v124
	v_exp_f32_e32 v145, v145
	v_lshl_or_b32 v146, s35, 7, v142
	v_lshl_add_u32 v144, s12, 8, v140
	v_ashrrev_i32_e32 v147, 31, v146
	v_add_f32_e32 v145, 1.0, v145
	v_rcp_f32_e32 v145, v145
	v_mov_b64_e32 v[138:139], s[2:3]
	s_movk_i32 s5, 0x2c00
	v_mad_i64_i32 v[148:149], s[14:15], v144, s5, v[138:139]
	v_mul_f32_e32 v124, v124, v145
	v_mul_f32_e32 v120, v124, v120
	v_mul_f32_e32 v124, 0xbfb8aa3b, v125
	v_exp_f32_e32 v124, v124
	s_and_b64 vcc, exec, s[0:1]
	s_mov_b32 s35, s4
	s_mov_b32 s12, s6
	v_add_f32_e32 v124, 1.0, v124
	v_rcp_f32_e32 v124, v124
	s_mov_b64 s[16:17], s[10:11]
	v_mul_f32_e32 v124, v125, v124
	v_mul_f32_e32 v121, v124, v121
	v_mul_f32_e32 v124, 0xbfb8aa3b, v126
	v_exp_f32_e32 v124, v124
	s_nop 0
	v_add_f32_e32 v124, 1.0, v124
	v_rcp_f32_e32 v124, v124
	s_nop 0
	v_mul_f32_e32 v124, v126, v124
	v_mul_f32_e32 v122, v124, v122
	v_mul_f32_e32 v124, 0xbfb8aa3b, v127
	v_exp_f32_e32 v124, v124
	s_nop 0
	v_add_f32_e32 v124, 1.0, v124
	v_rcp_f32_e32 v124, v124
	s_nop 0
	v_mul_f32_e32 v124, v127, v124
	v_mul_f32_e32 v123, v124, v123
	v_mul_f32_e32 v124, 0xbfb8aa3b, v116
	v_exp_f32_e32 v124, v124
	s_nop 0
	v_add_f32_e32 v124, 1.0, v124
	v_rcp_f32_e32 v124, v124
	s_nop 0
	v_mul_f32_e32 v116, v116, v124
	v_mul_f32_e32 v116, v116, v112
	v_mul_f32_e32 v112, 0xbfb8aa3b, v117
	v_exp_f32_e32 v112, v112
	s_nop 0
	v_add_f32_e32 v112, 1.0, v112
	v_rcp_f32_e32 v112, v112
	s_nop 0
	v_mul_f32_e32 v112, v117, v112
	v_mul_f32_e32 v117, v112, v113
	v_mul_f32_e32 v112, 0xbfb8aa3b, v118
	v_exp_f32_e32 v112, v112
	s_nop 0
	v_add_f32_e32 v112, 1.0, v112
	v_rcp_f32_e32 v112, v112
	s_nop 0
	v_mul_f32_e32 v112, v118, v112
	v_mul_f32_e32 v124, v112, v114
	v_mul_f32_e32 v112, 0xbfb8aa3b, v119
	v_exp_f32_e32 v112, v112
	v_cvt_pk_bf16_f32 v114, v120, v121
	s_nop 0
	v_add_f32_e32 v112, 1.0, v112
	v_rcp_f32_e32 v112, v112
	s_nop 0
	v_mul_f32_e32 v112, v119, v112
	v_mul_f32_e32 v125, v112, v115
	v_lshlrev_b64 v[112:113], 1, v[146:147]
	v_lshl_add_u64 v[118:119], v[148:149], 0, v[112:113]
	v_cvt_pk_bf16_f32 v115, v122, v123
	v_cvt_pk_bf16_f32 v116, v116, v117
	v_cvt_pk_bf16_f32 v117, v124, v125
	global_store_dwordx4 v[118:119], v[114:117], off
	s_nop 1
	v_mul_f32_e32 v116, 0xbfb8aa3b, v108
	v_exp_f32_e32 v116, v116
	v_or_b32_e32 v114, 16, v144
	v_mad_i64_i32 v[114:115], s[14:15], v114, s5, v[138:139]
	v_add_f32_e32 v116, 1.0, v116
	v_rcp_f32_e32 v116, v116
	s_nop 0
	v_mul_f32_e32 v108, v108, v116
	v_mul_f32_e32 v104, v108, v104
	v_mul_f32_e32 v108, 0xbfb8aa3b, v109
	v_exp_f32_e32 v108, v108
	s_nop 0
	v_add_f32_e32 v108, 1.0, v108
	v_rcp_f32_e32 v108, v108
	s_nop 0
	v_mul_f32_e32 v108, v109, v108
	v_mul_f32_e32 v105, v108, v105
	v_mul_f32_e32 v108, 0xbfb8aa3b, v110
	v_exp_f32_e32 v108, v108
	s_nop 0
	v_add_f32_e32 v108, 1.0, v108
	v_rcp_f32_e32 v108, v108
	s_nop 0
	v_mul_f32_e32 v108, v110, v108
	v_mul_f32_e32 v106, v108, v106
	v_mul_f32_e32 v108, 0xbfb8aa3b, v111
	v_exp_f32_e32 v108, v108
	s_nop 0
	v_add_f32_e32 v108, 1.0, v108
	v_rcp_f32_e32 v108, v108
	s_nop 0
	v_mul_f32_e32 v108, v111, v108
	v_mul_f32_e32 v107, v108, v107
	v_mul_f32_e32 v108, 0xbfb8aa3b, v100
	v_exp_f32_e32 v108, v108
	s_nop 0
	v_add_f32_e32 v108, 1.0, v108
	v_rcp_f32_e32 v108, v108
	s_nop 0
	v_mul_f32_e32 v100, v100, v108
	v_mul_f32_e32 v108, v100, v96
	v_mul_f32_e32 v96, 0xbfb8aa3b, v101
	v_exp_f32_e32 v96, v96
	s_nop 0
	v_add_f32_e32 v96, 1.0, v96
	v_rcp_f32_e32 v96, v96
	s_nop 0
	v_mul_f32_e32 v96, v101, v96
	v_mul_f32_e32 v109, v96, v97
	v_mul_f32_e32 v96, 0xbfb8aa3b, v102
	v_exp_f32_e32 v96, v96
	v_lshl_add_u64 v[100:101], v[114:115], 0, v[112:113]
	v_add_f32_e32 v96, 1.0, v96
	v_rcp_f32_e32 v96, v96
	s_nop 0
	v_mul_f32_e32 v96, v102, v96
	v_mul_f32_e32 v102, v96, v98
	v_mul_f32_e32 v96, 0xbfb8aa3b, v103
	v_exp_f32_e32 v96, v96
	s_nop 0
	v_add_f32_e32 v96, 1.0, v96
	v_rcp_f32_e32 v96, v96
	s_nop 0
	v_mul_f32_e32 v96, v103, v96
	v_mul_f32_e32 v99, v96, v99
	v_cvt_pk_bf16_f32 v96, v104, v105
	v_cvt_pk_bf16_f32 v97, v106, v107
	v_cvt_pk_bf16_f32 v98, v108, v109
	v_cvt_pk_bf16_f32 v99, v102, v99
	global_store_dwordx4 v[100:101], v[96:99], off
	s_nop 1
	v_mul_f32_e32 v98, 0xbfb8aa3b, v92
	v_exp_f32_e32 v98, v98
	v_or_b32_e32 v96, 32, v144
	v_mad_i64_i32 v[96:97], s[14:15], v96, s5, v[138:139]
	v_add_f32_e32 v98, 1.0, v98
	v_rcp_f32_e32 v98, v98
	s_nop 0
	v_mul_f32_e32 v92, v92, v98
	v_mul_f32_e32 v88, v92, v88
	v_mul_f32_e32 v92, 0xbfb8aa3b, v93
	v_exp_f32_e32 v92, v92
	s_nop 0
	v_add_f32_e32 v92, 1.0, v92
	v_rcp_f32_e32 v92, v92
	s_nop 0
	v_mul_f32_e32 v92, v93, v92
	v_mul_f32_e32 v89, v92, v89
	v_mul_f32_e32 v92, 0xbfb8aa3b, v94
	v_exp_f32_e32 v92, v92
	s_nop 0
	v_add_f32_e32 v92, 1.0, v92
	v_rcp_f32_e32 v92, v92
	s_nop 0
	v_mul_f32_e32 v92, v94, v92
	v_mul_f32_e32 v90, v92, v90
	v_mul_f32_e32 v92, 0xbfb8aa3b, v95
	v_exp_f32_e32 v92, v92
	s_nop 0
	v_add_f32_e32 v92, 1.0, v92
	v_rcp_f32_e32 v92, v92
	s_nop 0
	v_mul_f32_e32 v92, v95, v92
	v_mul_f32_e32 v91, v92, v91
	v_mul_f32_e32 v92, 0xbfb8aa3b, v84
	v_exp_f32_e32 v92, v92
	s_nop 0
	v_add_f32_e32 v92, 1.0, v92
	v_rcp_f32_e32 v92, v92
	s_nop 0
	v_mul_f32_e32 v84, v84, v92
	v_mul_f32_e32 v92, v84, v80
	v_mul_f32_e32 v80, 0xbfb8aa3b, v85
	v_exp_f32_e32 v80, v80
	s_nop 0
	v_add_f32_e32 v80, 1.0, v80
	v_rcp_f32_e32 v80, v80
	s_nop 0
	v_mul_f32_e32 v80, v85, v80
	v_mul_f32_e32 v93, v80, v81
	v_mul_f32_e32 v80, 0xbfb8aa3b, v86
	v_exp_f32_e32 v80, v80
	v_lshl_add_u64 v[84:85], v[96:97], 0, v[112:113]
	v_add_f32_e32 v80, 1.0, v80
	v_rcp_f32_e32 v80, v80
	s_nop 0
	v_mul_f32_e32 v80, v86, v80
	v_mul_f32_e32 v86, v80, v82
	v_mul_f32_e32 v80, 0xbfb8aa3b, v87
	v_exp_f32_e32 v80, v80
	s_nop 0
	v_add_f32_e32 v80, 1.0, v80
	v_rcp_f32_e32 v80, v80
	s_nop 0
	v_mul_f32_e32 v80, v87, v80
	v_mul_f32_e32 v83, v80, v83
	v_cvt_pk_bf16_f32 v80, v88, v89
	v_cvt_pk_bf16_f32 v81, v90, v91
	v_cvt_pk_bf16_f32 v82, v92, v93
	v_cvt_pk_bf16_f32 v83, v86, v83
	global_store_dwordx4 v[84:85], v[80:83], off
	s_nop 1
	v_mul_f32_e32 v82, 0xbfb8aa3b, v76
	v_exp_f32_e32 v82, v82
	v_or_b32_e32 v80, 48, v144
	v_mad_i64_i32 v[80:81], s[14:15], v80, s5, v[138:139]
	v_add_f32_e32 v82, 1.0, v82
	v_rcp_f32_e32 v82, v82
	s_nop 0
	v_mul_f32_e32 v76, v76, v82
	v_mul_f32_e32 v72, v76, v72
	v_mul_f32_e32 v76, 0xbfb8aa3b, v77
	v_exp_f32_e32 v76, v76
	s_nop 0
	v_add_f32_e32 v76, 1.0, v76
	v_rcp_f32_e32 v76, v76
	s_nop 0
	v_mul_f32_e32 v76, v77, v76
	v_mul_f32_e32 v73, v76, v73
	v_mul_f32_e32 v76, 0xbfb8aa3b, v78
	v_exp_f32_e32 v76, v76
	s_nop 0
	v_add_f32_e32 v76, 1.0, v76
	v_rcp_f32_e32 v76, v76
	s_nop 0
	v_mul_f32_e32 v76, v78, v76
	v_mul_f32_e32 v74, v76, v74
	v_mul_f32_e32 v76, 0xbfb8aa3b, v79
	v_exp_f32_e32 v76, v76
	s_nop 0
	v_add_f32_e32 v76, 1.0, v76
	v_rcp_f32_e32 v76, v76
	s_nop 0
	v_mul_f32_e32 v76, v79, v76
	v_mul_f32_e32 v75, v76, v75
	v_mul_f32_e32 v76, 0xbfb8aa3b, v68
	v_exp_f32_e32 v76, v76
	s_nop 0
	v_add_f32_e32 v76, 1.0, v76
	v_rcp_f32_e32 v76, v76
	s_nop 0
	v_mul_f32_e32 v68, v68, v76
	v_mul_f32_e32 v76, v68, v64
	v_mul_f32_e32 v64, 0xbfb8aa3b, v69
	v_exp_f32_e32 v64, v64
	s_nop 0
	v_add_f32_e32 v64, 1.0, v64
	v_rcp_f32_e32 v64, v64
	s_nop 0
	v_mul_f32_e32 v64, v69, v64
	v_mul_f32_e32 v77, v64, v65
	v_mul_f32_e32 v64, 0xbfb8aa3b, v70
	v_exp_f32_e32 v64, v64
	v_lshl_add_u64 v[68:69], v[80:81], 0, v[112:113]
	v_add_f32_e32 v64, 1.0, v64
	v_rcp_f32_e32 v64, v64
	s_nop 0
	v_mul_f32_e32 v64, v70, v64
	v_mul_f32_e32 v70, v64, v66
	v_mul_f32_e32 v64, 0xbfb8aa3b, v71
	v_exp_f32_e32 v64, v64
	s_nop 0
	v_add_f32_e32 v64, 1.0, v64
	v_rcp_f32_e32 v64, v64
	s_nop 0
	v_mul_f32_e32 v64, v71, v64
	v_mul_f32_e32 v67, v64, v67
	v_cvt_pk_bf16_f32 v64, v72, v73
	v_cvt_pk_bf16_f32 v65, v74, v75
	v_cvt_pk_bf16_f32 v66, v76, v77
	v_cvt_pk_bf16_f32 v67, v70, v67
	global_store_dwordx4 v[68:69], v[64:67], off
	s_nop 1
	v_mul_f32_e32 v66, 0xbfb8aa3b, v60
	v_exp_f32_e32 v66, v66
	v_add_u32_e32 v64, 0x80, v144
	v_mad_i64_i32 v[64:65], s[14:15], v64, s5, v[138:139]
	v_add_f32_e32 v66, 1.0, v66
	v_rcp_f32_e32 v66, v66
	s_nop 0
	v_mul_f32_e32 v60, v60, v66
	v_mul_f32_e32 v56, v60, v56
	v_mul_f32_e32 v60, 0xbfb8aa3b, v61
	v_exp_f32_e32 v60, v60
	s_nop 0
	v_add_f32_e32 v60, 1.0, v60
	v_rcp_f32_e32 v60, v60
	s_nop 0
	v_mul_f32_e32 v60, v61, v60
	v_mul_f32_e32 v57, v60, v57
	v_mul_f32_e32 v60, 0xbfb8aa3b, v62
	v_exp_f32_e32 v60, v60
	s_nop 0
	v_add_f32_e32 v60, 1.0, v60
	v_rcp_f32_e32 v60, v60
	s_nop 0
	v_mul_f32_e32 v60, v62, v60
	v_mul_f32_e32 v58, v60, v58
	v_mul_f32_e32 v60, 0xbfb8aa3b, v63
	v_exp_f32_e32 v60, v60
	s_nop 0
	v_add_f32_e32 v60, 1.0, v60
	v_rcp_f32_e32 v60, v60
	s_nop 0
	v_mul_f32_e32 v60, v63, v60
	v_mul_f32_e32 v59, v60, v59
	v_mul_f32_e32 v60, 0xbfb8aa3b, v52
	v_exp_f32_e32 v60, v60
	s_nop 0
	v_add_f32_e32 v60, 1.0, v60
	v_rcp_f32_e32 v60, v60
	s_nop 0
	v_mul_f32_e32 v52, v52, v60
	v_mul_f32_e32 v60, v52, v48
	v_mul_f32_e32 v48, 0xbfb8aa3b, v53
	v_exp_f32_e32 v48, v48
	s_nop 0
	v_add_f32_e32 v48, 1.0, v48
	v_rcp_f32_e32 v48, v48
	s_nop 0
	v_mul_f32_e32 v48, v53, v48
	v_mul_f32_e32 v61, v48, v49
	v_mul_f32_e32 v48, 0xbfb8aa3b, v54
	v_exp_f32_e32 v48, v48
	v_lshl_add_u64 v[52:53], v[64:65], 0, v[112:113]
	v_add_f32_e32 v48, 1.0, v48
	v_rcp_f32_e32 v48, v48
	s_nop 0
	v_mul_f32_e32 v48, v54, v48
	v_mul_f32_e32 v54, v48, v50
	v_mul_f32_e32 v48, 0xbfb8aa3b, v55
	v_exp_f32_e32 v48, v48
	s_nop 0
	v_add_f32_e32 v48, 1.0, v48
	v_rcp_f32_e32 v48, v48
	s_nop 0
	v_mul_f32_e32 v48, v55, v48
	v_mul_f32_e32 v51, v48, v51
	v_cvt_pk_bf16_f32 v48, v56, v57
	v_cvt_pk_bf16_f32 v49, v58, v59
	v_cvt_pk_bf16_f32 v50, v60, v61
	v_cvt_pk_bf16_f32 v51, v54, v51
	global_store_dwordx4 v[52:53], v[48:51], off
	s_nop 1
	v_mul_f32_e32 v50, 0xbfb8aa3b, v44
	v_exp_f32_e32 v50, v50
	v_add_u32_e32 v48, 0x90, v144
	v_mad_i64_i32 v[48:49], s[14:15], v48, s5, v[138:139]
	v_add_f32_e32 v50, 1.0, v50
	v_rcp_f32_e32 v50, v50
	s_nop 0
	v_mul_f32_e32 v44, v44, v50
	v_mul_f32_e32 v40, v44, v40
	v_mul_f32_e32 v44, 0xbfb8aa3b, v45
	v_exp_f32_e32 v44, v44
	s_nop 0
	v_add_f32_e32 v44, 1.0, v44
	v_rcp_f32_e32 v44, v44
	s_nop 0
	v_mul_f32_e32 v44, v45, v44
	v_mul_f32_e32 v41, v44, v41
	v_mul_f32_e32 v44, 0xbfb8aa3b, v46
	v_exp_f32_e32 v44, v44
	s_nop 0
	v_add_f32_e32 v44, 1.0, v44
	v_rcp_f32_e32 v44, v44
	s_nop 0
	v_mul_f32_e32 v44, v46, v44
	v_mul_f32_e32 v42, v44, v42
	v_mul_f32_e32 v44, 0xbfb8aa3b, v47
	v_exp_f32_e32 v44, v44
	s_nop 0
	v_add_f32_e32 v44, 1.0, v44
	v_rcp_f32_e32 v44, v44
	s_nop 0
	v_mul_f32_e32 v44, v47, v44
	v_mul_f32_e32 v43, v44, v43
	v_mul_f32_e32 v44, 0xbfb8aa3b, v36
	v_exp_f32_e32 v44, v44
	s_nop 0
	v_add_f32_e32 v44, 1.0, v44
	v_rcp_f32_e32 v44, v44
	s_nop 0
	v_mul_f32_e32 v36, v36, v44
	v_mul_f32_e32 v44, v36, v32
	v_mul_f32_e32 v32, 0xbfb8aa3b, v37
	v_exp_f32_e32 v32, v32
	s_nop 0
	v_add_f32_e32 v32, 1.0, v32
	v_rcp_f32_e32 v32, v32
	s_nop 0
	v_mul_f32_e32 v32, v37, v32
	v_mul_f32_e32 v45, v32, v33
	v_mul_f32_e32 v32, 0xbfb8aa3b, v38
	v_exp_f32_e32 v32, v32
	v_lshl_add_u64 v[36:37], v[48:49], 0, v[112:113]
	v_add_f32_e32 v32, 1.0, v32
	v_rcp_f32_e32 v32, v32
	s_nop 0
	v_mul_f32_e32 v32, v38, v32
	v_mul_f32_e32 v38, v32, v34
	v_mul_f32_e32 v32, 0xbfb8aa3b, v39
	v_exp_f32_e32 v32, v32
	s_nop 0
	v_add_f32_e32 v32, 1.0, v32
	v_rcp_f32_e32 v32, v32
	s_nop 0
	v_mul_f32_e32 v32, v39, v32
	v_mul_f32_e32 v35, v32, v35
	v_cvt_pk_bf16_f32 v32, v40, v41
	v_cvt_pk_bf16_f32 v33, v42, v43
	v_cvt_pk_bf16_f32 v34, v44, v45
	v_cvt_pk_bf16_f32 v35, v38, v35
	global_store_dwordx4 v[36:37], v[32:35], off
	s_nop 1
	v_mul_f32_e32 v34, 0xbfb8aa3b, v28
	v_exp_f32_e32 v34, v34
	v_add_u32_e32 v32, 0xa0, v144
	v_mad_i64_i32 v[32:33], s[14:15], v32, s5, v[138:139]
	v_add_f32_e32 v34, 1.0, v34
	v_rcp_f32_e32 v34, v34
	s_nop 0
	v_mul_f32_e32 v28, v28, v34
	v_mul_f32_e32 v24, v28, v24
	v_mul_f32_e32 v28, 0xbfb8aa3b, v29
	v_exp_f32_e32 v28, v28
	s_nop 0
	v_add_f32_e32 v28, 1.0, v28
	v_rcp_f32_e32 v28, v28
	s_nop 0
	v_mul_f32_e32 v28, v29, v28
	v_mul_f32_e32 v25, v28, v25
	v_mul_f32_e32 v28, 0xbfb8aa3b, v30
	v_exp_f32_e32 v28, v28
	s_nop 0
	v_add_f32_e32 v28, 1.0, v28
	v_rcp_f32_e32 v28, v28
	s_nop 0
	v_mul_f32_e32 v28, v30, v28
	v_mul_f32_e32 v26, v28, v26
	v_mul_f32_e32 v28, 0xbfb8aa3b, v31
	v_exp_f32_e32 v28, v28
	s_nop 0
	v_add_f32_e32 v28, 1.0, v28
	v_rcp_f32_e32 v28, v28
	s_nop 0
	v_mul_f32_e32 v28, v31, v28
	v_mul_f32_e32 v27, v28, v27
	v_mul_f32_e32 v28, 0xbfb8aa3b, v20
	v_exp_f32_e32 v28, v28
	s_nop 0
	v_add_f32_e32 v28, 1.0, v28
	v_rcp_f32_e32 v28, v28
	s_nop 0
	v_mul_f32_e32 v20, v20, v28
	v_mul_f32_e32 v28, v20, v16
	v_mul_f32_e32 v16, 0xbfb8aa3b, v21
	v_exp_f32_e32 v16, v16
	s_nop 0
	v_add_f32_e32 v16, 1.0, v16
	v_rcp_f32_e32 v16, v16
	s_nop 0
	v_mul_f32_e32 v16, v21, v16
	v_mul_f32_e32 v29, v16, v17
	v_mul_f32_e32 v16, 0xbfb8aa3b, v22
	v_exp_f32_e32 v16, v16
	v_lshl_add_u64 v[20:21], v[32:33], 0, v[112:113]
	v_add_f32_e32 v16, 1.0, v16
	v_rcp_f32_e32 v16, v16
	s_nop 0
	v_mul_f32_e32 v16, v22, v16
	v_mul_f32_e32 v22, v16, v18
	v_mul_f32_e32 v16, 0xbfb8aa3b, v23
	v_exp_f32_e32 v16, v16
	s_nop 0
	v_add_f32_e32 v16, 1.0, v16
	v_rcp_f32_e32 v16, v16
	s_nop 0
	v_mul_f32_e32 v16, v23, v16
	v_mul_f32_e32 v19, v16, v19
	v_cvt_pk_bf16_f32 v16, v24, v25
	v_cvt_pk_bf16_f32 v17, v26, v27
	v_cvt_pk_bf16_f32 v18, v28, v29
	v_cvt_pk_bf16_f32 v19, v22, v19
	global_store_dwordx4 v[20:21], v[16:19], off
	s_nop 1
	v_mul_f32_e32 v18, 0xbfb8aa3b, v12
	v_exp_f32_e32 v18, v18
	v_add_u32_e32 v16, 0xb0, v144
	v_mad_i64_i32 v[16:17], s[14:15], v16, s5, v[138:139]
	v_add_f32_e32 v18, 1.0, v18
	v_rcp_f32_e32 v18, v18
	s_mov_b64 s[14:15], s[8:9]
	v_mul_f32_e32 v12, v12, v18
	v_mul_f32_e32 v8, v12, v8
	v_mul_f32_e32 v12, 0xbfb8aa3b, v13
	v_exp_f32_e32 v12, v12
	s_nop 0
	v_add_f32_e32 v12, 1.0, v12
	v_rcp_f32_e32 v12, v12
	s_nop 0
	v_mul_f32_e32 v12, v13, v12
	v_mul_f32_e32 v9, v12, v9
	v_mul_f32_e32 v12, 0xbfb8aa3b, v14
	v_exp_f32_e32 v12, v12
	s_nop 0
	v_add_f32_e32 v12, 1.0, v12
	v_rcp_f32_e32 v12, v12
	s_nop 0
	v_mul_f32_e32 v12, v14, v12
	v_mul_f32_e32 v10, v12, v10
	v_mul_f32_e32 v12, 0xbfb8aa3b, v15
	v_exp_f32_e32 v12, v12
	s_nop 0
	v_add_f32_e32 v12, 1.0, v12
	v_rcp_f32_e32 v12, v12
	s_nop 0
	v_mul_f32_e32 v12, v15, v12
	v_mul_f32_e32 v11, v12, v11
	v_mul_f32_e32 v12, 0xbfb8aa3b, v4
	v_exp_f32_e32 v12, v12
	s_nop 0
	v_add_f32_e32 v12, 1.0, v12
	v_rcp_f32_e32 v12, v12
	s_nop 0
	v_mul_f32_e32 v4, v4, v12
	v_mul_f32_e32 v12, v4, v0
	v_mul_f32_e32 v0, 0xbfb8aa3b, v5
	v_exp_f32_e32 v0, v0
	s_nop 0
	v_add_f32_e32 v0, 1.0, v0
	v_rcp_f32_e32 v0, v0
	s_nop 0
	v_mul_f32_e32 v0, v5, v0
	v_mul_f32_e32 v13, v0, v1
	v_mul_f32_e32 v0, 0xbfb8aa3b, v6
	v_exp_f32_e32 v0, v0
	v_lshl_add_u64 v[4:5], v[16:17], 0, v[112:113]
	v_add_f32_e32 v0, 1.0, v0
	v_rcp_f32_e32 v0, v0
	s_nop 0
	v_mul_f32_e32 v0, v6, v0
	v_mul_f32_e32 v6, v0, v2
	v_mul_f32_e32 v0, 0xbfb8aa3b, v7
	v_exp_f32_e32 v0, v0
	s_nop 0
	v_add_f32_e32 v0, 1.0, v0
	v_rcp_f32_e32 v0, v0
	s_nop 0
	v_mul_f32_e32 v0, v7, v0
	v_mul_f32_e32 v3, v0, v3
	v_cvt_pk_bf16_f32 v0, v8, v9
	v_cvt_pk_bf16_f32 v1, v10, v11
	v_cvt_pk_bf16_f32 v2, v12, v13
	v_cvt_pk_bf16_f32 v3, v6, v3
	global_store_dwordx4 v[4:5], v[0:3], off
	s_cbranch_vccz .LBB0_214
	s_waitcnt vmcnt(0)
	v_readlane_b32 s34, v254, 18
	s_cmpk_gt_u32 s21, 0xff
	v_readlane_b32 s35, v254, 19
	v_readlane_b32 s31, v254, 20
	s_cbranch_scc1 .LBB0_221
	s_barrier

.LBB0_246:
	s_add_i32 s44, s12, 2
	s_add_u32 s14, s10, 0x80
	s_addc_u32 s13, s11, 0
	s_add_i32 s45, 0, 0x10000
	v_add_u32_e32 v132, s45, v191
	ds_read_b128 v[120:123], v132
	ds_read_b128 v[124:127], v132 offset:1024
	ds_read_b128 v[128:131], v132 offset:2048
	ds_read_b128 v[132:135], v132 offset:3072
	s_cmp_eq_u32 s36, s12
	s_cselect_b32 s12, s4, s14
	s_cselect_b32 s13, s5, s13
	s_cselect_b32 s15, s7, s43
	s_cselect_b32 s14, s6, s42
	s_add_i32 m0, s26, 0xc000
	ds_read_b128 v[144:147], v205
	ds_read_b128 v[148:151], v205 offset:1024
	ds_read_b128 v[152:155], v205 offset:2048
	ds_read_b128 v[156:159], v205 offset:3072
	ds_read_b128 v[160:163], v205 offset:4096
	ds_read_b128 v[164:167], v205 offset:5120
	ds_read_b128 v[178:181], v205 offset:6144
	ds_read_b128 v[182:185], v205 offset:7168
	global_load_lds_dwordx4 v174, s[10:11]
	s_add_i32 m0, s26, 0xe000
	s_nop 0
	global_load_lds_dwordx4 v176, s[10:11]
	s_waitcnt lgkmcnt(8)
	s_barrier
	s_waitcnt lgkmcnt(0)
	s_waitcnt lgkmcnt(0)
	v_mfma_f32_16x16x32_bf16 v[140:143], v[120:123], v[144:147], v[140:143]
	v_mfma_f32_16x16x32_bf16 v[136:139], v[128:131], v[144:147], v[136:139]
	v_mfma_f32_16x16x32_bf16 v[108:111], v[120:123], v[152:155], v[108:111]
	v_mfma_f32_16x16x32_bf16 v[104:107], v[128:131], v[152:155], v[104:107]
	v_mfma_f32_16x16x32_bf16 v[92:95], v[120:123], v[160:163], v[92:95]
	v_mfma_f32_16x16x32_bf16 v[88:91], v[128:131], v[160:163], v[88:91]
	v_mfma_f32_16x16x32_bf16 v[76:79], v[120:123], v[178:181], v[76:79]
	v_mfma_f32_16x16x32_bf16 v[72:75], v[128:131], v[178:181], v[72:75]
	v_mfma_f32_16x16x32_bf16 v[140:143], v[124:127], v[148:151], v[140:143]
	v_mfma_f32_16x16x32_bf16 v[136:139], v[132:135], v[148:151], v[136:139]
	v_mfma_f32_16x16x32_bf16 v[108:111], v[124:127], v[156:159], v[108:111]
	v_mfma_f32_16x16x32_bf16 v[104:107], v[132:135], v[156:159], v[104:107]
	v_mfma_f32_16x16x32_bf16 v[92:95], v[124:127], v[164:167], v[92:95]
	v_mfma_f32_16x16x32_bf16 v[88:91], v[132:135], v[164:167], v[88:91]
	v_mfma_f32_16x16x32_bf16 v[76:79], v[124:127], v[182:185], v[76:79]
	v_mfma_f32_16x16x32_bf16 v[72:75], v[132:135], v[182:185], v[72:75]
	s_barrier
	s_add_i32 s46, 0, 0x14000
	v_add_u32_e32 v210, s46, v191
	s_add_i32 s45, s45, s25
	ds_read_b128 v[186:189], v210
	ds_read_b128 v[196:199], v210 offset:1024
	ds_read_b128 v[206:209], v210 offset:2048
	ds_read_b128 v[214:217], v210 offset:3072
	v_lshl_add_u64 v[210:211], s[14:15], 0, v[192:193]
	s_mov_b32 m0, s45
	v_lshl_add_u64 v[218:219], s[14:15], 0, v[172:173]
	global_load_lds_dwordx4 v192, s[14:15]
	s_add_i32 m0, s45, 0x2000
	s_nop 0
	global_load_lds_dwordx4 v172, s[14:15]
	s_barrier
	s_waitcnt lgkmcnt(0)
	s_waitcnt lgkmcnt(0)
	v_mfma_f32_16x16x32_bf16 v[116:119], v[186:189], v[144:147], v[116:119]
	v_mfma_f32_16x16x32_bf16 v[112:115], v[206:209], v[144:147], v[112:115]
	v_mfma_f32_16x16x32_bf16 v[100:103], v[186:189], v[152:155], v[100:103]
	v_mfma_f32_16x16x32_bf16 v[96:99], v[206:209], v[152:155], v[96:99]
	v_mfma_f32_16x16x32_bf16 v[84:87], v[186:189], v[160:163], v[84:87]
	v_mfma_f32_16x16x32_bf16 v[80:83], v[206:209], v[160:163], v[80:83]
	v_mfma_f32_16x16x32_bf16 v[68:71], v[186:189], v[178:181], v[68:71]
	v_mfma_f32_16x16x32_bf16 v[64:67], v[206:209], v[178:181], v[64:67]
	v_mfma_f32_16x16x32_bf16 v[116:119], v[196:199], v[148:151], v[116:119]
	v_mfma_f32_16x16x32_bf16 v[112:115], v[214:217], v[148:151], v[112:115]
	v_mfma_f32_16x16x32_bf16 v[100:103], v[196:199], v[156:159], v[100:103]
	v_mfma_f32_16x16x32_bf16 v[96:99], v[214:217], v[156:159], v[96:99]
	v_mfma_f32_16x16x32_bf16 v[84:87], v[196:199], v[164:167], v[84:87]
	v_mfma_f32_16x16x32_bf16 v[80:83], v[214:217], v[164:167], v[80:83]
	v_mfma_f32_16x16x32_bf16 v[68:71], v[196:199], v[182:185], v[68:71]
	v_mfma_f32_16x16x32_bf16 v[64:67], v[214:217], v[182:185], v[64:67]
	s_mov_b32 m0, s26
	v_lshl_add_u64 v[220:221], s[12:13], 0, v[168:169]
	s_barrier
	ds_read_b128 v[144:147], v205 offset:16384
	ds_read_b128 v[148:151], v205 offset:17408
	ds_read_b128 v[152:155], v205 offset:18432
	ds_read_b128 v[156:159], v205 offset:19456
	ds_read_b128 v[160:163], v205 offset:20480
	ds_read_b128 v[164:167], v205 offset:21504
	ds_read_b128 v[178:181], v205 offset:22528
	ds_read_b128 v[182:185], v205 offset:23552
	global_load_lds_dwordx4 v168, s[12:13]
	v_lshl_add_u64 v[222:223], s[12:13], 0, v[170:171]
	s_mov_b32 m0, s27
	s_nop 0
	global_load_lds_dwordx4 v170, s[12:13]
	s_barrier
	s_waitcnt lgkmcnt(0)
	s_waitcnt lgkmcnt(0)
	v_mfma_f32_16x16x32_bf16 v[60:63], v[120:123], v[144:147], v[60:63]
	v_mfma_f32_16x16x32_bf16 v[56:59], v[128:131], v[144:147], v[56:59]
	v_mfma_f32_16x16x32_bf16 v[44:47], v[120:123], v[152:155], v[44:47]
	v_mfma_f32_16x16x32_bf16 v[40:43], v[128:131], v[152:155], v[40:43]
	v_mfma_f32_16x16x32_bf16 v[28:31], v[120:123], v[160:163], v[28:31]
	v_mfma_f32_16x16x32_bf16 v[24:27], v[128:131], v[160:163], v[24:27]
	v_mfma_f32_16x16x32_bf16 v[12:15], v[120:123], v[178:181], v[12:15]
	v_mfma_f32_16x16x32_bf16 v[8:11], v[128:131], v[178:181], v[8:11]
	v_mfma_f32_16x16x32_bf16 v[60:63], v[124:127], v[148:151], v[60:63]
	v_mfma_f32_16x16x32_bf16 v[56:59], v[132:135], v[148:151], v[56:59]
	v_mfma_f32_16x16x32_bf16 v[44:47], v[124:127], v[156:159], v[44:47]
	v_mfma_f32_16x16x32_bf16 v[40:43], v[132:135], v[156:159], v[40:43]
	v_mfma_f32_16x16x32_bf16 v[28:31], v[124:127], v[164:167], v[28:31]
	v_mfma_f32_16x16x32_bf16 v[24:27], v[132:135], v[164:167], v[24:27]
	v_mfma_f32_16x16x32_bf16 v[12:15], v[124:127], v[182:185], v[12:15]
	v_mfma_f32_16x16x32_bf16 v[8:11], v[132:135], v[182:185], v[8:11]
	s_barrier
	s_add_u32 s14, s14, s52
	s_addc_u32 s15, s15, 0
	s_add_i32 s45, s46, s25
	v_lshl_add_u64 v[224:225], s[14:15], 0, v[192:193]
	s_mov_b32 m0, s45
	v_lshl_add_u64 v[226:227], s[14:15], 0, v[172:173]
	global_load_lds_dwordx4 v192, s[14:15]
	s_add_i32 m0, s45, 0x2000
	s_nop 0
	global_load_lds_dwordx4 v172, s[14:15]
	s_waitcnt vmcnt(6)
	s_barrier
	v_mfma_f32_16x16x32_bf16 v[52:55], v[186:189], v[144:147], v[52:55]
	v_mfma_f32_16x16x32_bf16 v[48:51], v[206:209], v[144:147], v[48:51]
	v_mfma_f32_16x16x32_bf16 v[36:39], v[186:189], v[152:155], v[36:39]
	v_mfma_f32_16x16x32_bf16 v[32:35], v[206:209], v[152:155], v[32:35]
	v_mfma_f32_16x16x32_bf16 v[20:23], v[186:189], v[160:163], v[20:23]
	v_mfma_f32_16x16x32_bf16 v[16:19], v[206:209], v[160:163], v[16:19]
	v_mfma_f32_16x16x32_bf16 v[4:7], v[186:189], v[178:181], v[4:7]
	v_mfma_f32_16x16x32_bf16 v[0:3], v[206:209], v[178:181], v[0:3]
	v_mfma_f32_16x16x32_bf16 v[52:55], v[196:199], v[148:151], v[52:55]
	v_mfma_f32_16x16x32_bf16 v[48:51], v[214:217], v[148:151], v[48:51]
	v_mfma_f32_16x16x32_bf16 v[36:39], v[196:199], v[156:159], v[36:39]
	v_mfma_f32_16x16x32_bf16 v[32:35], v[214:217], v[156:159], v[32:35]
	v_mfma_f32_16x16x32_bf16 v[20:23], v[196:199], v[164:167], v[20:23]
	v_mfma_f32_16x16x32_bf16 v[16:19], v[214:217], v[164:167], v[16:19]
	v_mfma_f32_16x16x32_bf16 v[4:7], v[196:199], v[182:185], v[4:7]
	v_mfma_f32_16x16x32_bf16 v[0:3], v[214:217], v[182:185], v[0:3]
	s_add_i32 s14, 0, 0x18000
	v_add_u32_e32 v132, s14, v191
	s_barrier
	ds_read_b128 v[120:123], v132
	ds_read_b128 v[124:127], v132 offset:1024
	ds_read_b128 v[128:131], v132 offset:2048
	ds_read_b128 v[132:135], v132 offset:3072
	s_add_u32 s12, s12, s52
	s_addc_u32 s13, s13, 0
	s_mov_b32 m0, s28
	ds_read_b128 v[144:147], v205 offset:32768
	ds_read_b128 v[148:151], v205 offset:33792
	ds_read_b128 v[152:155], v205 offset:34816
	ds_read_b128 v[156:159], v205 offset:35840
	ds_read_b128 v[160:163], v205 offset:36864
	ds_read_b128 v[164:167], v205 offset:37888
	ds_read_b128 v[178:181], v205 offset:38912
	ds_read_b128 v[182:185], v205 offset:39936
	global_load_lds_dwordx4 v168, s[12:13]
	s_mov_b32 m0, s29
	s_nop 0
	global_load_lds_dwordx4 v170, s[12:13]
	s_waitcnt lgkmcnt(8)
	s_barrier
	s_waitcnt lgkmcnt(0)
	s_waitcnt lgkmcnt(0)
	v_mfma_f32_16x16x32_bf16 v[140:143], v[120:123], v[144:147], v[140:143]
	v_mfma_f32_16x16x32_bf16 v[136:139], v[128:131], v[144:147], v[136:139]
	v_mfma_f32_16x16x32_bf16 v[108:111], v[120:123], v[152:155], v[108:111]
	v_mfma_f32_16x16x32_bf16 v[104:107], v[128:131], v[152:155], v[104:107]
	v_mfma_f32_16x16x32_bf16 v[92:95], v[120:123], v[160:163], v[92:95]
	v_mfma_f32_16x16x32_bf16 v[88:91], v[128:131], v[160:163], v[88:91]
	v_mfma_f32_16x16x32_bf16 v[76:79], v[120:123], v[178:181], v[76:79]
	v_mfma_f32_16x16x32_bf16 v[72:75], v[128:131], v[178:181], v[72:75]
	v_mfma_f32_16x16x32_bf16 v[140:143], v[124:127], v[148:151], v[140:143]
	v_mfma_f32_16x16x32_bf16 v[136:139], v[132:135], v[148:151], v[136:139]
	v_mfma_f32_16x16x32_bf16 v[108:111], v[124:127], v[156:159], v[108:111]
	v_mfma_f32_16x16x32_bf16 v[104:107], v[132:135], v[156:159], v[104:107]
	v_mfma_f32_16x16x32_bf16 v[92:95], v[124:127], v[164:167], v[92:95]
	v_mfma_f32_16x16x32_bf16 v[88:91], v[132:135], v[164:167], v[88:91]
	v_mfma_f32_16x16x32_bf16 v[76:79], v[124:127], v[182:185], v[76:79]
	v_mfma_f32_16x16x32_bf16 v[72:75], v[132:135], v[182:185], v[72:75]
	s_barrier
	s_add_i32 s12, 0, 0x1c000
	s_add_i32 s13, s14, s25
	v_add_u32_e32 v212, s12, v191
	v_lshl_add_u64 v[210:211], v[210:211], 0, s[48:49]
	s_mov_b32 m0, s13
	ds_read_b128 v[186:189], v212
	ds_read_b128 v[196:199], v212 offset:1024
	ds_read_b128 v[206:209], v212 offset:2048
	ds_read_b128 v[214:217], v212 offset:3072
	global_load_lds_dwordx4 v[210:211], off
	v_lshl_add_u64 v[210:211], v[218:219], 0, s[48:49]
	s_add_i32 m0, s13, 0x2000
	s_nop 0
	global_load_lds_dwordx4 v[210:211], off
	s_barrier
	s_waitcnt lgkmcnt(0)
	s_waitcnt lgkmcnt(0)
	v_mfma_f32_16x16x32_bf16 v[116:119], v[186:189], v[144:147], v[116:119]
	v_mfma_f32_16x16x32_bf16 v[112:115], v[206:209], v[144:147], v[112:115]
	v_mfma_f32_16x16x32_bf16 v[100:103], v[186:189], v[152:155], v[100:103]
	v_mfma_f32_16x16x32_bf16 v[96:99], v[206:209], v[152:155], v[96:99]
	v_mfma_f32_16x16x32_bf16 v[84:87], v[186:189], v[160:163], v[84:87]
	v_mfma_f32_16x16x32_bf16 v[80:83], v[206:209], v[160:163], v[80:83]
	v_mfma_f32_16x16x32_bf16 v[68:71], v[186:189], v[178:181], v[68:71]
	v_mfma_f32_16x16x32_bf16 v[64:67], v[206:209], v[178:181], v[64:67]
	v_mfma_f32_16x16x32_bf16 v[116:119], v[196:199], v[148:151], v[116:119]
	v_mfma_f32_16x16x32_bf16 v[112:115], v[214:217], v[148:151], v[112:115]
	v_mfma_f32_16x16x32_bf16 v[100:103], v[196:199], v[156:159], v[100:103]
	v_mfma_f32_16x16x32_bf16 v[96:99], v[214:217], v[156:159], v[96:99]
	v_mfma_f32_16x16x32_bf16 v[84:87], v[196:199], v[164:167], v[84:87]
	v_mfma_f32_16x16x32_bf16 v[80:83], v[214:217], v[164:167], v[80:83]
	v_mfma_f32_16x16x32_bf16 v[68:71], v[196:199], v[182:185], v[68:71]
	v_mfma_f32_16x16x32_bf16 v[64:67], v[214:217], v[182:185], v[64:67]
	s_mov_b32 m0, s34
	v_lshl_add_u64 v[210:211], v[220:221], 0, s[48:49]
	s_barrier
	ds_read_b128 v[144:147], v205 offset:49152
	ds_read_b128 v[148:151], v205 offset:50176
	ds_read_b128 v[152:155], v205 offset:51200
	ds_read_b128 v[156:159], v205 offset:52224
	ds_read_b128 v[160:163], v205 offset:53248
	ds_read_b128 v[164:167], v205 offset:54272
	ds_read_b128 v[178:181], v205 offset:55296
	ds_read_b128 v[182:185], v205 offset:56320
	global_load_lds_dwordx4 v[210:211], off
	v_lshl_add_u64 v[210:211], v[222:223], 0, s[48:49]
	s_mov_b32 m0, s35
	s_nop 0
	global_load_lds_dwordx4 v[210:211], off
	s_barrier
	s_waitcnt lgkmcnt(0)
	s_waitcnt lgkmcnt(0)
	v_mfma_f32_16x16x32_bf16 v[60:63], v[120:123], v[144:147], v[60:63]
	v_mfma_f32_16x16x32_bf16 v[56:59], v[128:131], v[144:147], v[56:59]
	v_mfma_f32_16x16x32_bf16 v[44:47], v[120:123], v[152:155], v[44:47]
	v_mfma_f32_16x16x32_bf16 v[40:43], v[128:131], v[152:155], v[40:43]
	v_mfma_f32_16x16x32_bf16 v[28:31], v[120:123], v[160:163], v[28:31]
	v_mfma_f32_16x16x32_bf16 v[24:27], v[128:131], v[160:163], v[24:27]
	v_mfma_f32_16x16x32_bf16 v[12:15], v[120:123], v[178:181], v[12:15]
	v_mfma_f32_16x16x32_bf16 v[8:11], v[128:131], v[178:181], v[8:11]
	v_mfma_f32_16x16x32_bf16 v[60:63], v[124:127], v[148:151], v[60:63]
	v_mfma_f32_16x16x32_bf16 v[56:59], v[132:135], v[148:151], v[56:59]
	v_mfma_f32_16x16x32_bf16 v[44:47], v[124:127], v[156:159], v[44:47]
	v_mfma_f32_16x16x32_bf16 v[40:43], v[132:135], v[156:159], v[40:43]
	v_mfma_f32_16x16x32_bf16 v[28:31], v[124:127], v[164:167], v[28:31]
	v_mfma_f32_16x16x32_bf16 v[24:27], v[132:135], v[164:167], v[24:27]
	v_mfma_f32_16x16x32_bf16 v[12:15], v[124:127], v[182:185], v[12:15]
	v_mfma_f32_16x16x32_bf16 v[8:11], v[132:135], v[182:185], v[8:11]
	s_barrier
	s_add_i32 s12, s12, s25
	v_lshl_add_u64 v[120:121], v[224:225], 0, s[48:49]
	s_mov_b32 m0, s12
	s_nop 0
	global_load_lds_dwordx4 v[120:121], off
	v_lshl_add_u64 v[120:121], v[226:227], 0, s[48:49]
	s_add_i32 m0, s12, 0x2000
	s_nop 0
	global_load_lds_dwordx4 v[120:121], off
	s_waitcnt vmcnt(6)
	s_barrier
	v_mfma_f32_16x16x32_bf16 v[52:55], v[186:189], v[144:147], v[52:55]
	v_mfma_f32_16x16x32_bf16 v[48:51], v[206:209], v[144:147], v[48:51]
	v_mfma_f32_16x16x32_bf16 v[36:39], v[186:189], v[152:155], v[36:39]
	v_mfma_f32_16x16x32_bf16 v[32:35], v[206:209], v[152:155], v[32:35]
	v_mfma_f32_16x16x32_bf16 v[20:23], v[186:189], v[160:163], v[20:23]
	v_mfma_f32_16x16x32_bf16 v[16:19], v[206:209], v[160:163], v[16:19]
	v_mfma_f32_16x16x32_bf16 v[4:7], v[186:189], v[178:181], v[4:7]
	v_mfma_f32_16x16x32_bf16 v[0:3], v[206:209], v[178:181], v[0:3]
	v_mfma_f32_16x16x32_bf16 v[52:55], v[196:199], v[148:151], v[52:55]
	v_mfma_f32_16x16x32_bf16 v[48:51], v[214:217], v[148:151], v[48:51]
	v_mfma_f32_16x16x32_bf16 v[36:39], v[196:199], v[156:159], v[36:39]
	v_mfma_f32_16x16x32_bf16 v[32:35], v[214:217], v[156:159], v[32:35]
	v_mfma_f32_16x16x32_bf16 v[20:23], v[196:199], v[164:167], v[20:23]
	v_mfma_f32_16x16x32_bf16 v[16:19], v[214:217], v[164:167], v[16:19]
	v_mfma_f32_16x16x32_bf16 v[4:7], v[196:199], v[182:185], v[4:7]
	v_mfma_f32_16x16x32_bf16 v[0:3], v[214:217], v[182:185], v[0:3]
	s_add_u32 s10, s10, 0x100
	s_addc_u32 s11, s11, 0
	s_add_u32 s42, s42, 0x100
	s_addc_u32 s43, s43, 0
	s_cmp_ge_u32 s44, s33
	s_mov_b32 s12, s44
	s_barrier
	s_cbranch_scc0 .LBB0_246
	v_lshl_or_b32 v144, s41, 8, v204
	s_ashr_i32 s10, s40, 4
	s_mul_hi_i32 s11, s10, 0xc000
	s_mul_i32 s10, s10, 0xc000
	v_ashrrev_i32_e32 v145, 31, v144
	v_lshl_add_u32 v146, s40, 8, v190
	s_add_u32 s10, s30, s10
	v_lshlrev_b64 v[178:179], 1, v[144:145]
	v_ashrrev_i32_e32 v147, 31, v146
	s_addc_u32 s11, s31, s11
	v_lshl_add_u64 v[180:181], s[2:3], 0, v[178:179]
	v_lshlrev_b64 v[182:183], 12, v[146:147]
	v_lshl_add_u64 v[124:125], v[144:145], 2, s[10:11]
	v_lshl_add_u64 v[144:145], v[180:181], 0, v[182:183]
	global_load_dwordx4 v[128:131], v[124:125], off offset:16
	global_load_dwordx4 v[132:135], v[124:125], off
	global_load_dwordx4 v[120:123], v[124:125], off offset:528
	s_nop 0
	global_load_dwordx4 v[124:127], v[124:125], off offset:512
	s_nop 0
	global_load_dwordx4 v[196:199], v[144:145], off
	global_load_dwordx4 v[206:209], v[144:145], off offset:256
	v_or_b32_e32 v144, 16, v146
	v_ashrrev_i32_e32 v145, 31, v144
	v_lshlrev_b64 v[188:189], 12, v[144:145]
	v_lshl_add_u64 v[144:145], v[180:181], 0, v[188:189]
	global_load_dwordx4 v[164:167], v[144:145], off
	global_load_dwordx4 v[160:163], v[144:145], off offset:256
	v_or_b32_e32 v144, 32, v146
	v_ashrrev_i32_e32 v145, 31, v144
	v_lshlrev_b64 v[186:187], 12, v[144:145]
	v_lshl_add_u64 v[144:145], v[180:181], 0, v[186:187]
	global_load_dwordx4 v[156:159], v[144:145], off
	global_load_dwordx4 v[152:155], v[144:145], off offset:256
	v_or_b32_e32 v144, 48, v146
	v_ashrrev_i32_e32 v145, 31, v144
	v_lshlrev_b64 v[184:185], 12, v[144:145]
	v_lshl_add_u64 v[144:145], v[180:181], 0, v[184:185]
	global_load_dwordx4 v[148:151], v[144:145], off
	s_nop 0
	global_load_dwordx4 v[144:147], v[144:145], off offset:256
	s_mov_b64 s[10:11], 0x80000
	s_and_b64 vcc, exec, s[0:1]
	s_mov_b32 s41, s38
	s_mov_b32 s40, s39
	s_mov_b64 s[12:13], s[6:7]
	v_readlane_b32 s14, v254, 21
	s_movk_i32 s15, 0x2000
	s_waitcnt vmcnt(0)
	v_lshlrev_b32_e32 v210, 16, v196
	v_and_b32_e32 v211, 0xffff0000, v196
	v_lshlrev_b32_e32 v196, 16, v197
	v_and_b32_e32 v197, 0xffff0000, v197
	v_lshlrev_b32_e32 v214, 16, v198
	v_and_b32_e32 v215, 0xffff0000, v198
	v_lshlrev_b32_e32 v198, 16, v199
	v_and_b32_e32 v199, 0xffff0000, v199
	v_pk_fma_f32 v[140:141], v[140:141], v[132:133], v[210:211]
	v_pk_fma_f32 v[142:143], v[142:143], v[134:135], v[196:197]
	v_pk_fma_f32 v[196:197], v[138:139], v[130:131], v[198:199]
	v_pk_fma_f32 v[138:139], v[136:137], v[128:129], v[214:215]
	v_cvt_pk_bf16_f32 v136, v140, v141
	v_lshl_add_u64 v[140:141], s[8:9], 0, v[182:183]
	v_cvt_pk_bf16_f32 v137, v142, v143
	v_cvt_pk_bf16_f32 v138, v138, v139
	v_cvt_pk_bf16_f32 v139, v196, v197
	v_lshl_add_u64 v[140:141], v[140:141], 0, v[178:179]
	global_store_dwordx4 v[140:141], v[136:139], off
	v_lshlrev_b32_e32 v142, 16, v208
	v_and_b32_e32 v143, 0xffff0000, v208
	v_lshlrev_b32_e32 v136, 16, v206
	v_and_b32_e32 v137, 0xffff0000, v206
	v_lshlrev_b32_e32 v138, 16, v207
	v_and_b32_e32 v139, 0xffff0000, v207
	v_lshlrev_b32_e32 v196, 16, v209
	v_and_b32_e32 v197, 0xffff0000, v209
	v_pk_fma_f32 v[118:119], v[118:119], v[126:127], v[138:139]
	v_pk_fma_f32 v[116:117], v[116:117], v[124:125], v[136:137]
	v_pk_fma_f32 v[136:137], v[114:115], v[122:123], v[196:197]
	v_pk_fma_f32 v[114:115], v[112:113], v[120:121], v[142:143]
	v_cvt_pk_bf16_f32 v112, v116, v117
	v_cvt_pk_bf16_f32 v113, v118, v119
	v_lshlrev_b32_e32 v116, 16, v166
	v_cvt_pk_bf16_f32 v114, v114, v115
	v_cvt_pk_bf16_f32 v115, v136, v137
	global_store_dwordx4 v[140:141], v[112:115], off offset:256
	v_and_b32_e32 v117, 0xffff0000, v166
	v_lshlrev_b32_e32 v118, 16, v167
	v_lshlrev_b32_e32 v112, 16, v164
	v_and_b32_e32 v113, 0xffff0000, v164
	v_and_b32_e32 v119, 0xffff0000, v167
	v_pk_fma_f32 v[108:109], v[108:109], v[132:133], v[112:113]
	v_lshlrev_b32_e32 v114, 16, v165
	v_and_b32_e32 v115, 0xffff0000, v165
	v_pk_fma_f32 v[112:113], v[106:107], v[130:131], v[118:119]
	v_pk_fma_f32 v[106:107], v[104:105], v[128:129], v[116:117]
	v_cvt_pk_bf16_f32 v104, v108, v109
	v_lshl_add_u64 v[108:109], s[8:9], 0, v[188:189]
	v_pk_fma_f32 v[110:111], v[110:111], v[134:135], v[114:115]
	v_lshl_add_u64 v[108:109], v[108:109], 0, v[178:179]
	v_cvt_pk_bf16_f32 v105, v110, v111
	v_cvt_pk_bf16_f32 v106, v106, v107
	v_cvt_pk_bf16_f32 v107, v112, v113
	global_store_dwordx4 v[108:109], v[104:107], off
	v_lshlrev_b32_e32 v110, 16, v162
	v_and_b32_e32 v111, 0xffff0000, v162
	v_lshlrev_b32_e32 v104, 16, v160
	v_and_b32_e32 v105, 0xffff0000, v160
	v_lshlrev_b32_e32 v106, 16, v161
	v_and_b32_e32 v107, 0xffff0000, v161
	v_lshlrev_b32_e32 v112, 16, v163
	v_and_b32_e32 v113, 0xffff0000, v163
	v_pk_fma_f32 v[102:103], v[102:103], v[126:127], v[106:107]
	v_pk_fma_f32 v[100:101], v[100:101], v[124:125], v[104:105]
	v_pk_fma_f32 v[104:105], v[98:99], v[122:123], v[112:113]
	v_pk_fma_f32 v[98:99], v[96:97], v[120:121], v[110:111]
	v_cvt_pk_bf16_f32 v96, v100, v101
	v_cvt_pk_bf16_f32 v97, v102, v103
	v_lshlrev_b32_e32 v100, 16, v158
	v_cvt_pk_bf16_f32 v98, v98, v99
	v_cvt_pk_bf16_f32 v99, v104, v105
	global_store_dwordx4 v[108:109], v[96:99], off offset:256
	v_and_b32_e32 v101, 0xffff0000, v158
	v_lshlrev_b32_e32 v102, 16, v159
	v_lshlrev_b32_e32 v96, 16, v156
	v_and_b32_e32 v97, 0xffff0000, v156
	v_and_b32_e32 v103, 0xffff0000, v159
	v_pk_fma_f32 v[92:93], v[92:93], v[132:133], v[96:97]
	v_lshlrev_b32_e32 v98, 16, v157
	v_and_b32_e32 v99, 0xffff0000, v157
	v_pk_fma_f32 v[96:97], v[90:91], v[130:131], v[102:103]
	v_pk_fma_f32 v[90:91], v[88:89], v[128:129], v[100:101]
	v_cvt_pk_bf16_f32 v88, v92, v93
	v_lshl_add_u64 v[92:93], s[8:9], 0, v[186:187]
	v_pk_fma_f32 v[94:95], v[94:95], v[134:135], v[98:99]
	v_lshl_add_u64 v[92:93], v[92:93], 0, v[178:179]
	v_cvt_pk_bf16_f32 v89, v94, v95
	v_cvt_pk_bf16_f32 v90, v90, v91
	v_cvt_pk_bf16_f32 v91, v96, v97
	global_store_dwordx4 v[92:93], v[88:91], off
	v_lshlrev_b32_e32 v94, 16, v154
	v_and_b32_e32 v95, 0xffff0000, v154
	v_lshlrev_b32_e32 v88, 16, v152
	v_and_b32_e32 v89, 0xffff0000, v152
	v_lshlrev_b32_e32 v90, 16, v153
	v_and_b32_e32 v91, 0xffff0000, v153
	v_lshlrev_b32_e32 v96, 16, v155
	v_and_b32_e32 v97, 0xffff0000, v155
	v_pk_fma_f32 v[86:87], v[86:87], v[126:127], v[90:91]
	v_pk_fma_f32 v[84:85], v[84:85], v[124:125], v[88:89]
	v_pk_fma_f32 v[88:89], v[82:83], v[122:123], v[96:97]
	v_pk_fma_f32 v[82:83], v[80:81], v[120:121], v[94:95]
	v_cvt_pk_bf16_f32 v80, v84, v85
	v_cvt_pk_bf16_f32 v81, v86, v87
	v_lshlrev_b32_e32 v84, 16, v150
	v_cvt_pk_bf16_f32 v82, v82, v83
	v_cvt_pk_bf16_f32 v83, v88, v89
	global_store_dwordx4 v[92:93], v[80:83], off offset:256
	v_and_b32_e32 v85, 0xffff0000, v150
	v_lshlrev_b32_e32 v86, 16, v151
	v_lshlrev_b32_e32 v80, 16, v148
	v_and_b32_e32 v81, 0xffff0000, v148
	v_and_b32_e32 v87, 0xffff0000, v151
	v_pk_fma_f32 v[76:77], v[76:77], v[132:133], v[80:81]
	v_lshlrev_b32_e32 v82, 16, v149
	v_and_b32_e32 v83, 0xffff0000, v149
	v_pk_fma_f32 v[80:81], v[74:75], v[130:131], v[86:87]
	v_pk_fma_f32 v[74:75], v[72:73], v[128:129], v[84:85]
	v_cvt_pk_bf16_f32 v72, v76, v77
	v_lshl_add_u64 v[76:77], s[8:9], 0, v[184:185]
	v_pk_fma_f32 v[78:79], v[78:79], v[134:135], v[82:83]
	v_lshl_add_u64 v[76:77], v[76:77], 0, v[178:179]
	v_cvt_pk_bf16_f32 v73, v78, v79
	v_cvt_pk_bf16_f32 v74, v74, v75
	v_cvt_pk_bf16_f32 v75, v80, v81
	global_store_dwordx4 v[76:77], v[72:75], off
	v_lshlrev_b32_e32 v78, 16, v146
	v_and_b32_e32 v79, 0xffff0000, v146
	v_lshlrev_b32_e32 v72, 16, v144
	v_and_b32_e32 v73, 0xffff0000, v144
	v_lshlrev_b32_e32 v74, 16, v145
	v_and_b32_e32 v75, 0xffff0000, v145
	v_lshlrev_b32_e32 v80, 16, v147
	v_and_b32_e32 v81, 0xffff0000, v147
	v_pk_fma_f32 v[70:71], v[70:71], v[126:127], v[74:75]
	v_pk_fma_f32 v[68:69], v[68:69], v[124:125], v[72:73]
	v_pk_fma_f32 v[72:73], v[66:67], v[122:123], v[80:81]
	v_pk_fma_f32 v[66:67], v[64:65], v[120:121], v[78:79]
	v_cvt_pk_bf16_f32 v64, v68, v69
	v_cvt_pk_bf16_f32 v65, v70, v71
	v_lshl_add_u64 v[98:99], v[182:183], 0, s[10:11]
	v_cvt_pk_bf16_f32 v66, v66, v67
	v_cvt_pk_bf16_f32 v67, v72, v73
	global_store_dwordx4 v[76:77], v[64:67], off offset:256
	s_mov_b64 s[10:11], 0x90000
	v_lshl_add_u64 v[100:101], v[182:183], 0, s[10:11]
	v_lshl_add_u64 v[64:65], v[180:181], 0, v[98:99]
	global_load_dwordx4 v[74:77], v[64:65], off
	global_load_dwordx4 v[78:81], v[64:65], off offset:256
	v_lshl_add_u64 v[64:65], v[180:181], 0, v[100:101]
	global_load_dwordx4 v[82:85], v[64:65], off
	global_load_dwordx4 v[86:89], v[64:65], off offset:256
	s_mov_b64 s[10:11], 0xa0000
	v_lshl_add_u64 v[102:103], v[182:183], 0, s[10:11]
	v_lshl_add_u64 v[64:65], v[180:181], 0, v[102:103]
	global_load_dwordx4 v[90:93], v[64:65], off
	global_load_dwordx4 v[94:97], v[64:65], off offset:256
	s_mov_b64 s[10:11], 0xb0000
	v_lshl_add_u64 v[72:73], v[182:183], 0, s[10:11]
	v_lshl_add_u64 v[64:65], v[180:181], 0, v[72:73]
	global_load_dwordx4 v[68:71], v[64:65], off
	s_nop 0
	global_load_dwordx4 v[64:67], v[64:65], off offset:256
	s_mov_b64 s[10:11], s[4:5]
	s_waitcnt vmcnt(0)
	v_lshlrev_b32_e32 v104, 16, v74
	v_and_b32_e32 v105, 0xffff0000, v74
	v_lshlrev_b32_e32 v74, 16, v75
	v_and_b32_e32 v75, 0xffff0000, v75
	v_lshlrev_b32_e32 v106, 16, v76
	v_and_b32_e32 v107, 0xffff0000, v76
	v_lshlrev_b32_e32 v76, 16, v77
	v_and_b32_e32 v77, 0xffff0000, v77
	v_pk_fma_f32 v[60:61], v[60:61], v[132:133], v[104:105]
	v_pk_fma_f32 v[62:63], v[62:63], v[134:135], v[74:75]
	v_pk_fma_f32 v[74:75], v[58:59], v[130:131], v[76:77]
	v_pk_fma_f32 v[58:59], v[56:57], v[128:129], v[106:107]
	v_cvt_pk_bf16_f32 v56, v60, v61
	v_lshl_add_u64 v[60:61], s[8:9], 0, v[98:99]
	v_cvt_pk_bf16_f32 v57, v62, v63
	v_cvt_pk_bf16_f32 v58, v58, v59
	v_cvt_pk_bf16_f32 v59, v74, v75
	v_lshl_add_u64 v[60:61], v[60:61], 0, v[178:179]
	global_store_dwordx4 v[60:61], v[56:59], off
	v_lshlrev_b32_e32 v62, 16, v80
	v_and_b32_e32 v63, 0xffff0000, v80
	v_lshlrev_b32_e32 v56, 16, v78
	v_and_b32_e32 v57, 0xffff0000, v78
	v_lshlrev_b32_e32 v58, 16, v79
	v_and_b32_e32 v59, 0xffff0000, v79
	v_lshlrev_b32_e32 v74, 16, v81
	v_and_b32_e32 v75, 0xffff0000, v81
	v_pk_fma_f32 v[54:55], v[54:55], v[126:127], v[58:59]
	v_pk_fma_f32 v[52:53], v[52:53], v[124:125], v[56:57]
	v_pk_fma_f32 v[56:57], v[50:51], v[122:123], v[74:75]
	v_pk_fma_f32 v[50:51], v[48:49], v[120:121], v[62:63]
	v_cvt_pk_bf16_f32 v48, v52, v53
	v_cvt_pk_bf16_f32 v49, v54, v55
	v_lshlrev_b32_e32 v52, 16, v84
	v_cvt_pk_bf16_f32 v50, v50, v51
	v_cvt_pk_bf16_f32 v51, v56, v57
	global_store_dwordx4 v[60:61], v[48:51], off offset:256
	v_and_b32_e32 v53, 0xffff0000, v84
	v_lshlrev_b32_e32 v54, 16, v85
	v_lshlrev_b32_e32 v48, 16, v82
	v_and_b32_e32 v49, 0xffff0000, v82
	v_and_b32_e32 v55, 0xffff0000, v85
	v_pk_fma_f32 v[44:45], v[44:45], v[132:133], v[48:49]
	v_lshlrev_b32_e32 v50, 16, v83
	v_and_b32_e32 v51, 0xffff0000, v83
	v_pk_fma_f32 v[48:49], v[42:43], v[130:131], v[54:55]
	v_pk_fma_f32 v[42:43], v[40:41], v[128:129], v[52:53]
	v_cvt_pk_bf16_f32 v40, v44, v45
	v_lshl_add_u64 v[44:45], s[8:9], 0, v[100:101]
	v_pk_fma_f32 v[46:47], v[46:47], v[134:135], v[50:51]
	v_lshl_add_u64 v[44:45], v[44:45], 0, v[178:179]
	v_cvt_pk_bf16_f32 v41, v46, v47
	v_cvt_pk_bf16_f32 v42, v42, v43
	v_cvt_pk_bf16_f32 v43, v48, v49
	global_store_dwordx4 v[44:45], v[40:43], off
	v_lshlrev_b32_e32 v46, 16, v88
	v_and_b32_e32 v47, 0xffff0000, v88
	v_lshlrev_b32_e32 v40, 16, v86
	v_and_b32_e32 v41, 0xffff0000, v86
	v_lshlrev_b32_e32 v42, 16, v87
	v_and_b32_e32 v43, 0xffff0000, v87
	v_lshlrev_b32_e32 v48, 16, v89
	v_and_b32_e32 v49, 0xffff0000, v89
	v_pk_fma_f32 v[38:39], v[38:39], v[126:127], v[42:43]
	v_pk_fma_f32 v[36:37], v[36:37], v[124:125], v[40:41]
	v_pk_fma_f32 v[40:41], v[34:35], v[122:123], v[48:49]
	v_pk_fma_f32 v[34:35], v[32:33], v[120:121], v[46:47]
	v_cvt_pk_bf16_f32 v32, v36, v37
	v_cvt_pk_bf16_f32 v33, v38, v39
	v_lshlrev_b32_e32 v36, 16, v92
	v_cvt_pk_bf16_f32 v34, v34, v35
	v_cvt_pk_bf16_f32 v35, v40, v41
	global_store_dwordx4 v[44:45], v[32:35], off offset:256
	v_and_b32_e32 v37, 0xffff0000, v92
	v_lshlrev_b32_e32 v38, 16, v93
	v_lshlrev_b32_e32 v32, 16, v90
	v_and_b32_e32 v33, 0xffff0000, v90
	v_and_b32_e32 v39, 0xffff0000, v93
	v_pk_fma_f32 v[28:29], v[28:29], v[132:133], v[32:33]
	v_lshlrev_b32_e32 v34, 16, v91
	v_and_b32_e32 v35, 0xffff0000, v91
	v_pk_fma_f32 v[32:33], v[26:27], v[130:131], v[38:39]
	v_pk_fma_f32 v[26:27], v[24:25], v[128:129], v[36:37]
	v_cvt_pk_bf16_f32 v24, v28, v29
	v_lshl_add_u64 v[28:29], s[8:9], 0, v[102:103]
	v_pk_fma_f32 v[30:31], v[30:31], v[134:135], v[34:35]
	v_lshl_add_u64 v[28:29], v[28:29], 0, v[178:179]
	v_cvt_pk_bf16_f32 v25, v30, v31
	v_cvt_pk_bf16_f32 v26, v26, v27
	v_cvt_pk_bf16_f32 v27, v32, v33
	global_store_dwordx4 v[28:29], v[24:27], off
	v_lshlrev_b32_e32 v30, 16, v96
	v_and_b32_e32 v31, 0xffff0000, v96
	v_lshlrev_b32_e32 v24, 16, v94
	v_and_b32_e32 v25, 0xffff0000, v94
	v_lshlrev_b32_e32 v26, 16, v95
	v_and_b32_e32 v27, 0xffff0000, v95
	v_lshlrev_b32_e32 v32, 16, v97
	v_and_b32_e32 v33, 0xffff0000, v97
	v_pk_fma_f32 v[22:23], v[22:23], v[126:127], v[26:27]
	v_pk_fma_f32 v[20:21], v[20:21], v[124:125], v[24:25]
	v_pk_fma_f32 v[24:25], v[18:19], v[122:123], v[32:33]
	v_pk_fma_f32 v[18:19], v[16:17], v[120:121], v[30:31]
	v_cvt_pk_bf16_f32 v16, v20, v21
	v_cvt_pk_bf16_f32 v17, v22, v23
	v_lshlrev_b32_e32 v20, 16, v70
	v_cvt_pk_bf16_f32 v18, v18, v19
	v_cvt_pk_bf16_f32 v19, v24, v25
	global_store_dwordx4 v[28:29], v[16:19], off offset:256
	v_and_b32_e32 v21, 0xffff0000, v70
	v_lshlrev_b32_e32 v22, 16, v71
	v_lshlrev_b32_e32 v16, 16, v68
	v_and_b32_e32 v17, 0xffff0000, v68
	v_and_b32_e32 v23, 0xffff0000, v71
	v_pk_fma_f32 v[12:13], v[12:13], v[132:133], v[16:17]
	v_lshlrev_b32_e32 v18, 16, v69
	v_and_b32_e32 v19, 0xffff0000, v69
	v_pk_fma_f32 v[16:17], v[10:11], v[130:131], v[22:23]
	v_pk_fma_f32 v[10:11], v[8:9], v[128:129], v[20:21]
	v_cvt_pk_bf16_f32 v8, v12, v13
	v_lshl_add_u64 v[12:13], s[8:9], 0, v[72:73]
	v_pk_fma_f32 v[14:15], v[14:15], v[134:135], v[18:19]
	v_lshl_add_u64 v[12:13], v[12:13], 0, v[178:179]
	v_cvt_pk_bf16_f32 v9, v14, v15
	v_cvt_pk_bf16_f32 v10, v10, v11
	v_cvt_pk_bf16_f32 v11, v16, v17
	global_store_dwordx4 v[12:13], v[8:11], off
	v_lshlrev_b32_e32 v14, 16, v66
	v_and_b32_e32 v15, 0xffff0000, v66
	v_lshlrev_b32_e32 v8, 16, v64
	v_and_b32_e32 v9, 0xffff0000, v64
	v_lshlrev_b32_e32 v16, 16, v67
	v_and_b32_e32 v17, 0xffff0000, v67
	v_lshlrev_b32_e32 v10, 16, v65
	v_and_b32_e32 v11, 0xffff0000, v65
	v_pk_fma_f32 v[4:5], v[4:5], v[124:125], v[8:9]
	v_pk_fma_f32 v[8:9], v[2:3], v[122:123], v[16:17]
	v_pk_fma_f32 v[2:3], v[0:1], v[120:121], v[14:15]
	v_pk_fma_f32 v[6:7], v[6:7], v[126:127], v[10:11]
	v_cvt_pk_bf16_f32 v0, v4, v5
	s_nop 0
	v_cvt_pk_bf16_f32 v1, v6, v7
	v_cvt_pk_bf16_f32 v2, v2, v3
	v_cvt_pk_bf16_f32 v3, v8, v9
	global_store_dwordx4 v[12:13], v[0:3], off offset:256
	s_cbranch_vccz .LBB0_235
	s_waitcnt vmcnt(0)
	s_cmpk_gt_u32 s16, 0xff
	s_cbranch_scc1 .LBB0_250
	s_barrier

.LBB0_272:
	s_add_u32 s10, s8, 0x100
	s_addc_u32 s11, s9, 0
	s_add_i32 s42, 0, 0x10000
	v_add_u32_e32 v120, s42, v187
	ds_read_b128 v[108:111], v120
	ds_read_b128 v[112:115], v120 offset:1024
	ds_read_b128 v[116:119], v120 offset:2048
	ds_read_b128 v[120:123], v120 offset:3072
	s_cmpk_eq_i32 s41, 0x54
	s_cselect_b32 s15, s5, s11
	s_cselect_b32 s14, s4, s10
	s_cselect_b32 s13, s7, s40
	s_cselect_b32 s12, s6, s39
	s_add_i32 m0, s25, 0xc000
	ds_read_b128 v[144:147], v189
	ds_read_b128 v[148:151], v189 offset:1024
	ds_read_b128 v[152:155], v189 offset:2048
	ds_read_b128 v[156:159], v189 offset:3072
	ds_read_b128 v[160:163], v189 offset:4096
	ds_read_b128 v[174:177], v189 offset:5120
	ds_read_b128 v[178:181], v189 offset:6144
	ds_read_b128 v[182:185], v189 offset:7168
	global_load_lds_dwordx4 v170, s[8:9]
	s_add_i32 m0, s25, 0xe000
	s_nop 0
	global_load_lds_dwordx4 v172, s[8:9]
	s_waitcnt lgkmcnt(8)
	s_barrier
	s_waitcnt lgkmcnt(0)
	s_waitcnt lgkmcnt(0)
	v_mfma_f32_16x16x32_bf16 v[140:143], v[108:111], v[144:147], v[140:143]
	v_mfma_f32_16x16x32_bf16 v[136:139], v[116:119], v[144:147], v[136:139]
	v_mfma_f32_16x16x32_bf16 v[132:135], v[108:111], v[152:155], v[132:135]
	v_mfma_f32_16x16x32_bf16 v[104:107], v[116:119], v[152:155], v[104:107]
	v_mfma_f32_16x16x32_bf16 v[96:99], v[108:111], v[160:163], v[96:99]
	v_mfma_f32_16x16x32_bf16 v[88:91], v[116:119], v[160:163], v[88:91]
	v_mfma_f32_16x16x32_bf16 v[80:83], v[108:111], v[178:181], v[80:83]
	v_mfma_f32_16x16x32_bf16 v[72:75], v[116:119], v[178:181], v[72:75]
	v_mfma_f32_16x16x32_bf16 v[140:143], v[112:115], v[148:151], v[140:143]
	v_mfma_f32_16x16x32_bf16 v[136:139], v[120:123], v[148:151], v[136:139]
	v_mfma_f32_16x16x32_bf16 v[132:135], v[112:115], v[156:159], v[132:135]
	v_mfma_f32_16x16x32_bf16 v[104:107], v[120:123], v[156:159], v[104:107]
	v_mfma_f32_16x16x32_bf16 v[96:99], v[112:115], v[174:177], v[96:99]
	v_mfma_f32_16x16x32_bf16 v[88:91], v[120:123], v[174:177], v[88:91]
	v_mfma_f32_16x16x32_bf16 v[80:83], v[112:115], v[182:185], v[80:83]
	v_mfma_f32_16x16x32_bf16 v[72:75], v[120:123], v[182:185], v[72:75]
	s_barrier
	s_add_i32 s43, 0, 0x14000
	v_add_u32_e32 v190, s43, v187
	s_add_i32 s8, s42, s19
	ds_read_b128 v[196:199], v190
	ds_read_b128 v[204:207], v190 offset:1024
	ds_read_b128 v[208:211], v190 offset:2048
	ds_read_b128 v[214:217], v190 offset:3072
	s_mov_b32 m0, s8
	s_nop 0
	global_load_lds_dwordx4 v192, s[12:13]
	s_add_i32 m0, s8, 0x2000
	s_nop 0
	global_load_lds_dwordx4 v168, s[12:13]
	s_barrier
	s_waitcnt lgkmcnt(0)
	s_waitcnt lgkmcnt(0)
	v_mfma_f32_16x16x32_bf16 v[128:131], v[196:199], v[144:147], v[128:131]
	v_mfma_f32_16x16x32_bf16 v[124:127], v[208:211], v[144:147], v[124:127]
	v_mfma_f32_16x16x32_bf16 v[100:103], v[196:199], v[152:155], v[100:103]
	v_mfma_f32_16x16x32_bf16 v[92:95], v[208:211], v[152:155], v[92:95]
	v_mfma_f32_16x16x32_bf16 v[84:87], v[196:199], v[160:163], v[84:87]
	v_mfma_f32_16x16x32_bf16 v[76:79], v[208:211], v[160:163], v[76:79]
	v_mfma_f32_16x16x32_bf16 v[68:71], v[196:199], v[178:181], v[68:71]
	v_mfma_f32_16x16x32_bf16 v[64:67], v[208:211], v[178:181], v[64:67]
	v_mfma_f32_16x16x32_bf16 v[128:131], v[204:207], v[148:151], v[128:131]
	v_mfma_f32_16x16x32_bf16 v[124:127], v[214:217], v[148:151], v[124:127]
	v_mfma_f32_16x16x32_bf16 v[100:103], v[204:207], v[156:159], v[100:103]
	v_mfma_f32_16x16x32_bf16 v[92:95], v[214:217], v[156:159], v[92:95]
	v_mfma_f32_16x16x32_bf16 v[84:87], v[204:207], v[174:177], v[84:87]
	v_mfma_f32_16x16x32_bf16 v[76:79], v[214:217], v[174:177], v[76:79]
	v_mfma_f32_16x16x32_bf16 v[68:71], v[204:207], v[182:185], v[68:71]
	v_mfma_f32_16x16x32_bf16 v[64:67], v[214:217], v[182:185], v[64:67]
	s_mov_b32 m0, s25
	v_lshl_add_u64 v[220:221], s[14:15], 0, v[164:165]
	s_barrier
	ds_read_b128 v[144:147], v189 offset:16384
	ds_read_b128 v[148:151], v189 offset:17408
	ds_read_b128 v[152:155], v189 offset:18432
	ds_read_b128 v[156:159], v189 offset:19456
	ds_read_b128 v[160:163], v189 offset:20480
	ds_read_b128 v[174:177], v189 offset:21504
	ds_read_b128 v[178:181], v189 offset:22528
	ds_read_b128 v[182:185], v189 offset:23552
	global_load_lds_dwordx4 v164, s[14:15]
	v_lshl_add_u64 v[222:223], s[14:15], 0, v[166:167]
	s_mov_b32 m0, s26
	s_nop 0
	global_load_lds_dwordx4 v166, s[14:15]
	s_barrier
	s_waitcnt lgkmcnt(0)
	s_waitcnt lgkmcnt(0)
	v_mfma_f32_16x16x32_bf16 v[60:63], v[108:111], v[144:147], v[60:63]
	v_mfma_f32_16x16x32_bf16 v[56:59], v[116:119], v[144:147], v[56:59]
	v_mfma_f32_16x16x32_bf16 v[48:51], v[108:111], v[152:155], v[48:51]
	v_mfma_f32_16x16x32_bf16 v[40:43], v[116:119], v[152:155], v[40:43]
	v_mfma_f32_16x16x32_bf16 v[32:35], v[108:111], v[160:163], v[32:35]
	v_mfma_f32_16x16x32_bf16 v[24:27], v[116:119], v[160:163], v[24:27]
	v_mfma_f32_16x16x32_bf16 v[16:19], v[108:111], v[178:181], v[16:19]
	v_mfma_f32_16x16x32_bf16 v[8:11], v[116:119], v[178:181], v[8:11]
	v_mfma_f32_16x16x32_bf16 v[60:63], v[112:115], v[148:151], v[60:63]
	v_mfma_f32_16x16x32_bf16 v[56:59], v[120:123], v[148:151], v[56:59]
	v_mfma_f32_16x16x32_bf16 v[48:51], v[112:115], v[156:159], v[48:51]
	v_mfma_f32_16x16x32_bf16 v[40:43], v[120:123], v[156:159], v[40:43]
	v_mfma_f32_16x16x32_bf16 v[32:35], v[112:115], v[174:177], v[32:35]
	v_mfma_f32_16x16x32_bf16 v[24:27], v[120:123], v[174:177], v[24:27]
	v_mfma_f32_16x16x32_bf16 v[16:19], v[112:115], v[182:185], v[16:19]
	v_mfma_f32_16x16x32_bf16 v[8:11], v[120:123], v[182:185], v[8:11]
	s_barrier
	s_add_u32 s8, s12, 0x160000
	s_addc_u32 s9, s13, 0
	s_add_i32 s42, s43, s19
	s_mov_b32 m0, s42
	s_nop 0
	global_load_lds_dwordx4 v192, s[8:9]
	s_add_i32 m0, s42, 0x2000
	s_nop 0
	global_load_lds_dwordx4 v168, s[8:9]
	s_waitcnt vmcnt(6)
	s_barrier
	v_mfma_f32_16x16x32_bf16 v[52:55], v[196:199], v[144:147], v[52:55]
	v_mfma_f32_16x16x32_bf16 v[44:47], v[208:211], v[144:147], v[44:47]
	v_mfma_f32_16x16x32_bf16 v[36:39], v[196:199], v[152:155], v[36:39]
	v_mfma_f32_16x16x32_bf16 v[28:31], v[208:211], v[152:155], v[28:31]
	v_mfma_f32_16x16x32_bf16 v[20:23], v[196:199], v[160:163], v[20:23]
	v_mfma_f32_16x16x32_bf16 v[12:15], v[208:211], v[160:163], v[12:15]
	v_mfma_f32_16x16x32_bf16 v[4:7], v[196:199], v[178:181], v[4:7]
	v_mfma_f32_16x16x32_bf16 v[0:3], v[208:211], v[178:181], v[0:3]
	v_mfma_f32_16x16x32_bf16 v[52:55], v[204:207], v[148:151], v[52:55]
	v_mfma_f32_16x16x32_bf16 v[44:47], v[214:217], v[148:151], v[44:47]
	v_mfma_f32_16x16x32_bf16 v[36:39], v[204:207], v[156:159], v[36:39]
	v_mfma_f32_16x16x32_bf16 v[28:31], v[214:217], v[156:159], v[28:31]
	v_mfma_f32_16x16x32_bf16 v[20:23], v[204:207], v[174:177], v[20:23]
	v_mfma_f32_16x16x32_bf16 v[12:15], v[214:217], v[174:177], v[12:15]
	v_mfma_f32_16x16x32_bf16 v[4:7], v[204:207], v[182:185], v[4:7]
	v_mfma_f32_16x16x32_bf16 v[0:3], v[214:217], v[182:185], v[0:3]
	s_add_i32 s42, 0, 0x18000
	v_add_u32_e32 v120, s42, v187
	s_barrier
	ds_read_b128 v[108:111], v120
	ds_read_b128 v[112:115], v120 offset:1024
	ds_read_b128 v[116:119], v120 offset:2048
	ds_read_b128 v[120:123], v120 offset:3072
	s_add_u32 s8, s14, 0x160000
	s_addc_u32 s9, s15, 0
	s_mov_b32 m0, s27
	ds_read_b128 v[144:147], v189 offset:32768
	ds_read_b128 v[148:151], v189 offset:33792
	ds_read_b128 v[152:155], v189 offset:34816
	ds_read_b128 v[156:159], v189 offset:35840
	ds_read_b128 v[160:163], v189 offset:36864
	ds_read_b128 v[174:177], v189 offset:37888
	ds_read_b128 v[178:181], v189 offset:38912
	ds_read_b128 v[182:185], v189 offset:39936
	global_load_lds_dwordx4 v164, s[8:9]
	s_mov_b32 m0, s28
	s_nop 0
	global_load_lds_dwordx4 v166, s[8:9]
	s_waitcnt lgkmcnt(8)
	s_barrier
	s_waitcnt lgkmcnt(0)
	s_waitcnt lgkmcnt(0)
	v_mfma_f32_16x16x32_bf16 v[140:143], v[108:111], v[144:147], v[140:143]
	v_mfma_f32_16x16x32_bf16 v[136:139], v[116:119], v[144:147], v[136:139]
	v_mfma_f32_16x16x32_bf16 v[132:135], v[108:111], v[152:155], v[132:135]
	v_mfma_f32_16x16x32_bf16 v[104:107], v[116:119], v[152:155], v[104:107]
	v_mfma_f32_16x16x32_bf16 v[96:99], v[108:111], v[160:163], v[96:99]
	v_mfma_f32_16x16x32_bf16 v[88:91], v[116:119], v[160:163], v[88:91]
	v_mfma_f32_16x16x32_bf16 v[80:83], v[108:111], v[178:181], v[80:83]
	v_mfma_f32_16x16x32_bf16 v[72:75], v[116:119], v[178:181], v[72:75]
	v_mfma_f32_16x16x32_bf16 v[140:143], v[112:115], v[148:151], v[140:143]
	v_mfma_f32_16x16x32_bf16 v[136:139], v[120:123], v[148:151], v[136:139]
	v_mfma_f32_16x16x32_bf16 v[132:135], v[112:115], v[156:159], v[132:135]
	v_mfma_f32_16x16x32_bf16 v[104:107], v[120:123], v[156:159], v[104:107]
	v_mfma_f32_16x16x32_bf16 v[96:99], v[112:115], v[174:177], v[96:99]
	v_mfma_f32_16x16x32_bf16 v[88:91], v[120:123], v[174:177], v[88:91]
	v_mfma_f32_16x16x32_bf16 v[80:83], v[112:115], v[182:185], v[80:83]
	v_mfma_f32_16x16x32_bf16 v[72:75], v[120:123], v[182:185], v[72:75]
	s_barrier
	s_add_i32 s14, 0, 0x1c000
	s_add_i32 s8, s42, s19
	v_add_u32_e32 v212, s14, v187
	s_add_i32 m0, s8, 0xffffff80
	ds_read_b128 v[196:199], v212
	ds_read_b128 v[204:207], v212 offset:1024
	ds_read_b128 v[208:211], v212 offset:2048
	ds_read_b128 v[214:217], v212 offset:3072
	global_load_lds_dwordx4 v192, s[12:13] offset:128
	s_add_i32 m0, s8, 0x1f80
	s_nop 0
	global_load_lds_dwordx4 v168, s[12:13] offset:128
	s_barrier
	s_waitcnt lgkmcnt(0)
	s_waitcnt lgkmcnt(0)
	v_mfma_f32_16x16x32_bf16 v[128:131], v[196:199], v[144:147], v[128:131]
	v_mfma_f32_16x16x32_bf16 v[124:127], v[208:211], v[144:147], v[124:127]
	v_mfma_f32_16x16x32_bf16 v[100:103], v[196:199], v[152:155], v[100:103]
	v_mfma_f32_16x16x32_bf16 v[92:95], v[208:211], v[152:155], v[92:95]
	v_mfma_f32_16x16x32_bf16 v[84:87], v[196:199], v[160:163], v[84:87]
	v_mfma_f32_16x16x32_bf16 v[76:79], v[208:211], v[160:163], v[76:79]
	v_mfma_f32_16x16x32_bf16 v[68:71], v[196:199], v[178:181], v[68:71]
	v_mfma_f32_16x16x32_bf16 v[64:67], v[208:211], v[178:181], v[64:67]
	v_mfma_f32_16x16x32_bf16 v[128:131], v[204:207], v[148:151], v[128:131]
	v_mfma_f32_16x16x32_bf16 v[124:127], v[214:217], v[148:151], v[124:127]
	v_mfma_f32_16x16x32_bf16 v[100:103], v[204:207], v[156:159], v[100:103]
	v_mfma_f32_16x16x32_bf16 v[92:95], v[214:217], v[156:159], v[92:95]
	v_mfma_f32_16x16x32_bf16 v[84:87], v[204:207], v[174:177], v[84:87]
	v_mfma_f32_16x16x32_bf16 v[76:79], v[214:217], v[174:177], v[76:79]
	v_mfma_f32_16x16x32_bf16 v[68:71], v[204:207], v[182:185], v[68:71]
	v_mfma_f32_16x16x32_bf16 v[64:67], v[214:217], v[182:185], v[64:67]
	s_mov_b32 m0, s31
	v_lshl_add_u64 v[190:191], v[220:221], 0, s[44:45]
	s_barrier
	ds_read_b128 v[144:147], v189 offset:49152
	ds_read_b128 v[148:151], v189 offset:50176
	ds_read_b128 v[152:155], v189 offset:51200
	ds_read_b128 v[156:159], v189 offset:52224
	ds_read_b128 v[160:163], v189 offset:53248
	ds_read_b128 v[174:177], v189 offset:54272
	ds_read_b128 v[178:181], v189 offset:55296
	ds_read_b128 v[182:185], v189 offset:56320
	global_load_lds_dwordx4 v[190:191], off
	v_lshl_add_u64 v[190:191], v[222:223], 0, s[44:45]
	s_mov_b32 m0, s33
	s_nop 0
	global_load_lds_dwordx4 v[190:191], off
	s_barrier
	s_waitcnt lgkmcnt(0)
	s_waitcnt lgkmcnt(0)
	v_mfma_f32_16x16x32_bf16 v[60:63], v[108:111], v[144:147], v[60:63]
	v_mfma_f32_16x16x32_bf16 v[56:59], v[116:119], v[144:147], v[56:59]
	v_mfma_f32_16x16x32_bf16 v[48:51], v[108:111], v[152:155], v[48:51]
	v_mfma_f32_16x16x32_bf16 v[40:43], v[116:119], v[152:155], v[40:43]
	v_mfma_f32_16x16x32_bf16 v[32:35], v[108:111], v[160:163], v[32:35]
	v_mfma_f32_16x16x32_bf16 v[24:27], v[116:119], v[160:163], v[24:27]
	v_mfma_f32_16x16x32_bf16 v[16:19], v[108:111], v[178:181], v[16:19]
	v_mfma_f32_16x16x32_bf16 v[8:11], v[116:119], v[178:181], v[8:11]
	v_mfma_f32_16x16x32_bf16 v[60:63], v[112:115], v[148:151], v[60:63]
	v_mfma_f32_16x16x32_bf16 v[56:59], v[120:123], v[148:151], v[56:59]
	v_mfma_f32_16x16x32_bf16 v[48:51], v[112:115], v[156:159], v[48:51]
	v_mfma_f32_16x16x32_bf16 v[40:43], v[120:123], v[156:159], v[40:43]
	v_mfma_f32_16x16x32_bf16 v[32:35], v[112:115], v[174:177], v[32:35]
	v_mfma_f32_16x16x32_bf16 v[24:27], v[120:123], v[174:177], v[24:27]
	v_mfma_f32_16x16x32_bf16 v[16:19], v[112:115], v[182:185], v[16:19]
	v_mfma_f32_16x16x32_bf16 v[8:11], v[120:123], v[182:185], v[8:11]
	s_barrier
	s_add_u32 s8, s12, 0x160080
	s_addc_u32 s9, s13, 0
	s_add_i32 s12, s14, s19
	s_mov_b32 m0, s12
	s_nop 0
	global_load_lds_dwordx4 v192, s[8:9]
	s_add_i32 m0, s12, 0x2000
	s_nop 0
	global_load_lds_dwordx4 v168, s[8:9]
	s_waitcnt vmcnt(6)
	s_barrier
	v_mfma_f32_16x16x32_bf16 v[52:55], v[196:199], v[144:147], v[52:55]
	v_mfma_f32_16x16x32_bf16 v[44:47], v[208:211], v[144:147], v[44:47]
	v_mfma_f32_16x16x32_bf16 v[36:39], v[196:199], v[152:155], v[36:39]
	v_mfma_f32_16x16x32_bf16 v[28:31], v[208:211], v[152:155], v[28:31]
	v_mfma_f32_16x16x32_bf16 v[20:23], v[196:199], v[160:163], v[20:23]
	v_mfma_f32_16x16x32_bf16 v[12:15], v[208:211], v[160:163], v[12:15]
	v_mfma_f32_16x16x32_bf16 v[4:7], v[196:199], v[178:181], v[4:7]
	v_mfma_f32_16x16x32_bf16 v[0:3], v[208:211], v[178:181], v[0:3]
	v_mfma_f32_16x16x32_bf16 v[52:55], v[204:207], v[148:151], v[52:55]
	v_mfma_f32_16x16x32_bf16 v[44:47], v[214:217], v[148:151], v[44:47]
	v_mfma_f32_16x16x32_bf16 v[36:39], v[204:207], v[156:159], v[36:39]
	v_mfma_f32_16x16x32_bf16 v[28:31], v[214:217], v[156:159], v[28:31]
	v_mfma_f32_16x16x32_bf16 v[20:23], v[204:207], v[174:177], v[20:23]
	v_mfma_f32_16x16x32_bf16 v[12:15], v[214:217], v[174:177], v[12:15]
	v_mfma_f32_16x16x32_bf16 v[4:7], v[204:207], v[182:185], v[4:7]
	v_mfma_f32_16x16x32_bf16 v[0:3], v[214:217], v[182:185], v[0:3]
	s_add_i32 s41, s41, 2
	s_add_u32 s39, s39, 0x100
	s_addc_u32 s40, s40, 0
	s_cmpk_gt_u32 s41, 0x55
	s_mov_b64 s[8:9], s[10:11]
	s_barrier
	s_cbranch_scc0 .LBB0_272
	s_ashr_i32 s8, s37, 4
	v_lshl_or_b32 v144, s38, 8, v188
	s_mul_hi_i32 s9, s8, 0xc000
	s_mul_i32 s8, s8, 0xc000
	v_lshl_add_u32 v178, s37, 8, v186
	s_add_u32 s8, s29, s8
	v_ashrrev_i32_e32 v145, 31, v144
	v_ashrrev_i32_e32 v179, 31, v178
	s_addc_u32 s9, s30, s9
	v_lshlrev_b64 v[174:175], 2, v[144:145]
	v_lshl_add_u64 v[176:177], v[144:145], 1, s[2:3]
	v_lshlrev_b64 v[144:145], 12, v[178:179]
	v_lshl_add_u64 v[112:113], s[8:9], 0, v[174:175]
	v_lshl_add_u64 v[144:145], v[176:177], 0, v[144:145]
	global_load_dwordx4 v[116:119], v[112:113], off offset:16
	global_load_dwordx4 v[120:123], v[112:113], off
	global_load_dwordx4 v[108:111], v[112:113], off offset:528
	s_nop 0
	global_load_dwordx4 v[112:115], v[112:113], off offset:512
	s_nop 0
	global_load_dwordx4 v[196:199], v[144:145], off
	global_load_dwordx4 v[204:207], v[144:145], off offset:256
	v_or_b32_e32 v184, 16, v178
	v_ashrrev_i32_e32 v185, 31, v184
	v_lshlrev_b64 v[144:145], 12, v[184:185]
	v_lshl_add_u64 v[144:145], v[176:177], 0, v[144:145]
	global_load_dwordx4 v[208:211], v[144:145], off
	global_load_dwordx4 v[160:163], v[144:145], off offset:256
	v_or_b32_e32 v182, 32, v178
	v_ashrrev_i32_e32 v183, 31, v182
	v_lshlrev_b64 v[144:145], 12, v[182:183]
	v_lshl_add_u64 v[144:145], v[176:177], 0, v[144:145]
	global_load_dwordx4 v[156:159], v[144:145], off
	global_load_dwordx4 v[152:155], v[144:145], off offset:256
	v_or_b32_e32 v180, 48, v178
	v_ashrrev_i32_e32 v181, 31, v180
	v_lshlrev_b64 v[144:145], 12, v[180:181]
	v_lshl_add_u64 v[144:145], v[176:177], 0, v[144:145]
	global_load_dwordx4 v[148:151], v[144:145], off
	s_nop 0
	global_load_dwordx4 v[144:147], v[144:145], off offset:256
	v_readlane_b32 s52, v254, 39
	v_readlane_b32 s66, v254, 53
	v_readlane_b32 s67, v254, 54
	s_and_b64 vcc, exec, s[0:1]
	s_mov_b32 s38, s35
	s_mov_b32 s37, s36
	s_mov_b64 s[10:11], s[6:7]
	s_mov_b64 s[8:9], s[4:5]
	v_readlane_b32 s14, v254, 21
	s_movk_i32 s15, 0x2000
	v_readlane_b32 s53, v254, 40
	v_readlane_b32 s54, v254, 41
	v_readlane_b32 s55, v254, 42
	v_readlane_b32 s56, v254, 43
	v_readlane_b32 s57, v254, 44
	v_readlane_b32 s58, v254, 45
	v_readlane_b32 s59, v254, 46
	v_readlane_b32 s60, v254, 47
	v_readlane_b32 s61, v254, 48
	v_readlane_b32 s62, v254, 49
	v_readlane_b32 s63, v254, 50
	v_readlane_b32 s64, v254, 51
	v_readlane_b32 s65, v254, 52
	s_waitcnt vmcnt(0)
	v_lshlrev_b32_e32 v190, 16, v196
	v_and_b32_e32 v191, 0xffff0000, v196
	v_pk_fma_f32 v[140:141], v[140:141], v[120:121], v[190:191]
	v_lshlrev_b64 v[190:191], 13, v[178:179]
	v_lshlrev_b32_e32 v196, 16, v197
	v_and_b32_e32 v197, 0xffff0000, v197
	v_lshl_add_u64 v[190:191], s[66:67], 0, v[190:191]
	v_pk_fma_f32 v[142:143], v[142:143], v[122:123], v[196:197]
	v_lshl_add_u64 v[190:191], v[190:191], 0, v[174:175]
	global_store_dwordx4 v[190:191], v[140:143], off
	v_lshlrev_b32_e32 v214, 16, v198
	v_and_b32_e32 v215, 0xffff0000, v198
	v_lshlrev_b32_e32 v140, 16, v206
	v_and_b32_e32 v141, 0xffff0000, v206
	v_lshlrev_b32_e32 v142, 16, v207
	v_and_b32_e32 v143, 0xffff0000, v207
	v_pk_fma_f32 v[126:127], v[126:127], v[110:111], v[142:143]
	v_pk_fma_f32 v[124:125], v[124:125], v[108:109], v[140:141]
	global_store_dwordx4 v[190:191], v[124:127], off offset:528
	v_lshlrev_b32_e32 v198, 16, v199
	v_and_b32_e32 v199, 0xffff0000, v199
	v_lshlrev_b32_e32 v124, 16, v208
	v_and_b32_e32 v125, 0xffff0000, v208
	v_pk_fma_f32 v[124:125], v[132:133], v[120:121], v[124:125]
	v_lshlrev_b64 v[132:133], 13, v[184:185]
	v_lshlrev_b32_e32 v126, 16, v209
	v_and_b32_e32 v127, 0xffff0000, v209
	v_lshl_add_u64 v[132:133], s[66:67], 0, v[132:133]
	v_pk_fma_f32 v[126:127], v[134:135], v[122:123], v[126:127]
	v_lshl_add_u64 v[132:133], v[132:133], 0, v[174:175]
	v_pk_fma_f32 v[138:139], v[138:139], v[118:119], v[198:199]
	v_pk_fma_f32 v[136:137], v[136:137], v[116:117], v[214:215]
	global_store_dwordx4 v[132:133], v[124:127], off
	global_store_dwordx4 v[190:191], v[136:139], off offset:16
	s_nop 0
	v_lshlrev_b32_e32 v124, 16, v162
	v_and_b32_e32 v125, 0xffff0000, v162
	v_lshlrev_b32_e32 v126, 16, v163
	v_and_b32_e32 v127, 0xffff0000, v163
	v_lshlrev_b32_e32 v136, 16, v204
	v_and_b32_e32 v137, 0xffff0000, v204
	v_lshlrev_b32_e32 v138, 16, v205
	v_and_b32_e32 v139, 0xffff0000, v205
	v_pk_fma_f32 v[94:95], v[94:95], v[110:111], v[126:127]
	v_pk_fma_f32 v[92:93], v[92:93], v[108:109], v[124:125]
	v_pk_fma_f32 v[130:131], v[130:131], v[114:115], v[138:139]
	v_pk_fma_f32 v[128:129], v[128:129], v[112:113], v[136:137]
	global_store_dwordx4 v[132:133], v[92:95], off offset:528
	global_store_dwordx4 v[190:191], v[128:131], off offset:512
	s_nop 0
	v_lshlrev_b32_e32 v92, 16, v156
	v_and_b32_e32 v93, 0xffff0000, v156
	v_lshlrev_b32_e32 v128, 16, v210
	v_and_b32_e32 v129, 0xffff0000, v210
	v_lshlrev_b32_e32 v130, 16, v211
	v_and_b32_e32 v131, 0xffff0000, v211
	v_pk_fma_f32 v[92:93], v[96:97], v[120:121], v[92:93]
	v_lshlrev_b64 v[96:97], 13, v[182:183]
	v_pk_fma_f32 v[106:107], v[106:107], v[118:119], v[130:131]
	v_pk_fma_f32 v[104:105], v[104:105], v[116:117], v[128:129]
	v_lshlrev_b32_e32 v94, 16, v157
	v_and_b32_e32 v95, 0xffff0000, v157
	v_lshl_add_u64 v[96:97], s[66:67], 0, v[96:97]
	global_store_dwordx4 v[132:133], v[104:107], off offset:16
	v_pk_fma_f32 v[94:95], v[98:99], v[122:123], v[94:95]
	v_lshl_add_u64 v[96:97], v[96:97], 0, v[174:175]
	v_lshlrev_b32_e32 v104, 16, v160
	v_and_b32_e32 v105, 0xffff0000, v160
	v_lshlrev_b32_e32 v106, 16, v161
	v_and_b32_e32 v107, 0xffff0000, v161
	v_pk_fma_f32 v[102:103], v[102:103], v[114:115], v[106:107]
	v_pk_fma_f32 v[100:101], v[100:101], v[112:113], v[104:105]
	global_store_dwordx4 v[96:97], v[92:95], off
	global_store_dwordx4 v[132:133], v[100:103], off offset:512
	v_add_u32_e32 v98, 0x90, v178
	v_lshlrev_b32_e32 v92, 16, v154
	v_and_b32_e32 v93, 0xffff0000, v154
	v_lshlrev_b32_e32 v94, 16, v155
	v_and_b32_e32 v95, 0xffff0000, v155
	v_lshlrev_b32_e32 v100, 16, v158
	v_and_b32_e32 v101, 0xffff0000, v158
	v_lshlrev_b32_e32 v102, 16, v159
	v_and_b32_e32 v103, 0xffff0000, v159
	v_pk_fma_f32 v[78:79], v[78:79], v[110:111], v[94:95]
	v_pk_fma_f32 v[76:77], v[76:77], v[108:109], v[92:93]
	v_pk_fma_f32 v[90:91], v[90:91], v[118:119], v[102:103]
	v_pk_fma_f32 v[88:89], v[88:89], v[116:117], v[100:101]
	global_store_dwordx4 v[96:97], v[76:79], off offset:528
	global_store_dwordx4 v[96:97], v[88:91], off offset:16
	v_ashrrev_i32_e32 v99, 31, v98
	v_lshlrev_b32_e32 v76, 16, v148
	v_and_b32_e32 v77, 0xffff0000, v148
	v_lshlrev_b32_e32 v88, 16, v152
	v_and_b32_e32 v89, 0xffff0000, v152
	v_lshlrev_b32_e32 v90, 16, v153
	v_and_b32_e32 v91, 0xffff0000, v153
	v_pk_fma_f32 v[76:77], v[80:81], v[120:121], v[76:77]
	v_lshlrev_b64 v[80:81], 13, v[180:181]
	v_pk_fma_f32 v[86:87], v[86:87], v[114:115], v[90:91]
	v_pk_fma_f32 v[84:85], v[84:85], v[112:113], v[88:89]
	v_lshlrev_b32_e32 v78, 16, v149
	v_and_b32_e32 v79, 0xffff0000, v149
	v_lshl_add_u64 v[80:81], s[66:67], 0, v[80:81]
	global_store_dwordx4 v[96:97], v[84:87], off offset:512
	v_pk_fma_f32 v[78:79], v[82:83], v[122:123], v[78:79]
	v_lshl_add_u64 v[80:81], v[80:81], 0, v[174:175]
	v_lshlrev_b32_e32 v84, 16, v150
	v_and_b32_e32 v85, 0xffff0000, v150
	v_lshlrev_b32_e32 v86, 16, v151
	v_and_b32_e32 v87, 0xffff0000, v151
	global_store_dwordx4 v[80:81], v[76:79], off
	v_pk_fma_f32 v[74:75], v[74:75], v[118:119], v[86:87]
	v_pk_fma_f32 v[72:73], v[72:73], v[116:117], v[84:85]
	v_lshlrev_b32_e32 v76, 16, v146
	v_and_b32_e32 v77, 0xffff0000, v146
	v_lshlrev_b32_e32 v78, 16, v147
	v_and_b32_e32 v79, 0xffff0000, v147
	v_add_u32_e32 v96, 0x80, v178
	global_store_dwordx4 v[80:81], v[72:75], off offset:16
	v_pk_fma_f32 v[66:67], v[66:67], v[110:111], v[78:79]
	v_pk_fma_f32 v[64:65], v[64:65], v[108:109], v[76:77]
	v_lshlrev_b32_e32 v72, 16, v144
	v_and_b32_e32 v73, 0xffff0000, v144
	v_lshlrev_b32_e32 v74, 16, v145
	v_and_b32_e32 v75, 0xffff0000, v145
	v_ashrrev_i32_e32 v97, 31, v96
	v_pk_fma_f32 v[70:71], v[70:71], v[114:115], v[74:75]
	v_pk_fma_f32 v[68:69], v[68:69], v[112:113], v[72:73]
	global_store_dwordx4 v[80:81], v[64:67], off offset:528
	global_store_dwordx4 v[80:81], v[68:71], off offset:512
	v_add_u32_e32 v100, 0xa0, v178
	v_lshlrev_b64 v[64:65], 12, v[96:97]
	v_lshl_add_u64 v[64:65], v[176:177], 0, v[64:65]
	global_load_dwordx4 v[68:71], v[64:65], off
	global_load_dwordx4 v[72:75], v[64:65], off offset:256
	v_lshlrev_b64 v[64:65], 12, v[98:99]
	v_lshl_add_u64 v[64:65], v[176:177], 0, v[64:65]
	global_load_dwordx4 v[76:79], v[64:65], off
	global_load_dwordx4 v[80:83], v[64:65], off offset:256
	v_ashrrev_i32_e32 v101, 31, v100
	v_lshlrev_b64 v[64:65], 12, v[100:101]
	v_lshl_add_u64 v[64:65], v[176:177], 0, v[64:65]
	global_load_dwordx4 v[84:87], v[64:65], off
	global_load_dwordx4 v[88:91], v[64:65], off offset:256
	v_add_u32_e32 v102, 0xb0, v178
	v_ashrrev_i32_e32 v103, 31, v102
	v_lshlrev_b64 v[64:65], 12, v[102:103]
	v_lshl_add_u64 v[64:65], v[176:177], 0, v[64:65]
	global_load_dwordx4 v[92:95], v[64:65], off
	s_nop 0
	global_load_dwordx4 v[64:67], v[64:65], off offset:256
	s_waitcnt vmcnt(0)
	v_lshlrev_b32_e32 v104, 16, v68
	v_and_b32_e32 v105, 0xffff0000, v68
	v_lshlrev_b32_e32 v68, 16, v69
	v_and_b32_e32 v69, 0xffff0000, v69
	v_pk_fma_f32 v[62:63], v[62:63], v[122:123], v[68:69]
	v_lshlrev_b64 v[68:69], 13, v[96:97]
	v_lshl_add_u64 v[68:69], s[66:67], 0, v[68:69]
	v_pk_fma_f32 v[60:61], v[60:61], v[120:121], v[104:105]
	v_lshl_add_u64 v[68:69], v[68:69], 0, v[174:175]
	global_store_dwordx4 v[68:69], v[60:63], off
	v_lshlrev_b32_e32 v106, 16, v70
	v_and_b32_e32 v107, 0xffff0000, v70
	v_lshlrev_b32_e32 v60, 16, v74
	v_and_b32_e32 v61, 0xffff0000, v74
	v_lshlrev_b32_e32 v62, 16, v75
	v_and_b32_e32 v63, 0xffff0000, v75
	v_pk_fma_f32 v[46:47], v[46:47], v[110:111], v[62:63]
	v_pk_fma_f32 v[44:45], v[44:45], v[108:109], v[60:61]
	global_store_dwordx4 v[68:69], v[44:47], off offset:528
	v_lshlrev_b32_e32 v70, 16, v71
	v_and_b32_e32 v71, 0xffff0000, v71
	v_lshlrev_b32_e32 v44, 16, v76
	v_and_b32_e32 v45, 0xffff0000, v76
	v_pk_fma_f32 v[44:45], v[48:49], v[120:121], v[44:45]
	v_lshlrev_b64 v[48:49], 13, v[98:99]
	v_lshlrev_b32_e32 v46, 16, v77
	v_and_b32_e32 v47, 0xffff0000, v77
	v_lshl_add_u64 v[48:49], s[66:67], 0, v[48:49]
	v_pk_fma_f32 v[58:59], v[58:59], v[118:119], v[70:71]
	v_pk_fma_f32 v[56:57], v[56:57], v[116:117], v[106:107]
	v_pk_fma_f32 v[46:47], v[50:51], v[122:123], v[46:47]
	v_lshl_add_u64 v[48:49], v[48:49], 0, v[174:175]
	global_store_dwordx4 v[68:69], v[56:59], off offset:16
	global_store_dwordx4 v[48:49], v[44:47], off
	s_nop 0
	v_lshlrev_b32_e32 v56, 16, v72
	v_and_b32_e32 v57, 0xffff0000, v72
	v_lshlrev_b32_e32 v58, 16, v73
	v_and_b32_e32 v59, 0xffff0000, v73
	v_lshlrev_b32_e32 v44, 16, v82
	v_and_b32_e32 v45, 0xffff0000, v82
	v_lshlrev_b32_e32 v46, 16, v83
	v_and_b32_e32 v47, 0xffff0000, v83
	v_pk_fma_f32 v[54:55], v[54:55], v[114:115], v[58:59]
	v_pk_fma_f32 v[52:53], v[52:53], v[112:113], v[56:57]
	v_pk_fma_f32 v[30:31], v[30:31], v[110:111], v[46:47]
	v_pk_fma_f32 v[28:29], v[28:29], v[108:109], v[44:45]
	global_store_dwordx4 v[68:69], v[52:55], off offset:512
	global_store_dwordx4 v[48:49], v[28:31], off offset:528
	s_nop 0
	v_lshlrev_b32_e32 v52, 16, v78
	v_and_b32_e32 v53, 0xffff0000, v78
	v_lshlrev_b32_e32 v54, 16, v79
	v_and_b32_e32 v55, 0xffff0000, v79
	v_lshlrev_b32_e32 v28, 16, v84
	v_and_b32_e32 v29, 0xffff0000, v84
	v_pk_fma_f32 v[42:43], v[42:43], v[118:119], v[54:55]
	v_pk_fma_f32 v[40:41], v[40:41], v[116:117], v[52:53]
	v_pk_fma_f32 v[28:29], v[32:33], v[120:121], v[28:29]
	v_lshlrev_b64 v[32:33], 13, v[100:101]
	global_store_dwordx4 v[48:49], v[40:43], off offset:16
	v_lshlrev_b32_e32 v30, 16, v85
	v_and_b32_e32 v31, 0xffff0000, v85
	v_lshlrev_b32_e32 v40, 16, v80
	v_and_b32_e32 v41, 0xffff0000, v80
	v_lshlrev_b32_e32 v42, 16, v81
	v_and_b32_e32 v43, 0xffff0000, v81
	v_lshl_add_u64 v[32:33], s[66:67], 0, v[32:33]
	v_pk_fma_f32 v[38:39], v[38:39], v[114:115], v[42:43]
	v_pk_fma_f32 v[36:37], v[36:37], v[112:113], v[40:41]
	v_pk_fma_f32 v[30:31], v[34:35], v[122:123], v[30:31]
	v_lshl_add_u64 v[32:33], v[32:33], 0, v[174:175]
	global_store_dwordx4 v[48:49], v[36:39], off offset:512
	global_store_dwordx4 v[32:33], v[28:31], off
	s_nop 0
	v_lshlrev_b32_e32 v36, 16, v86
	v_and_b32_e32 v37, 0xffff0000, v86
	v_lshlrev_b32_e32 v38, 16, v87
	v_and_b32_e32 v39, 0xffff0000, v87
	v_lshlrev_b32_e32 v28, 16, v90
	v_and_b32_e32 v29, 0xffff0000, v90
	v_lshlrev_b32_e32 v30, 16, v91
	v_and_b32_e32 v31, 0xffff0000, v91
	v_pk_fma_f32 v[26:27], v[26:27], v[118:119], v[38:39]
	v_pk_fma_f32 v[24:25], v[24:25], v[116:117], v[36:37]
	v_pk_fma_f32 v[14:15], v[14:15], v[110:111], v[30:31]
	v_pk_fma_f32 v[12:13], v[12:13], v[108:109], v[28:29]
	global_store_dwordx4 v[32:33], v[24:27], off offset:16
	global_store_dwordx4 v[32:33], v[12:15], off offset:528
	s_nop 0
	v_lshlrev_b32_e32 v24, 16, v88
	v_and_b32_e32 v25, 0xffff0000, v88
	v_lshlrev_b32_e32 v26, 16, v89
	v_and_b32_e32 v27, 0xffff0000, v89
	v_lshlrev_b32_e32 v12, 16, v92
	v_and_b32_e32 v13, 0xffff0000, v92
	v_pk_fma_f32 v[22:23], v[22:23], v[114:115], v[26:27]
	v_pk_fma_f32 v[20:21], v[20:21], v[112:113], v[24:25]
	v_pk_fma_f32 v[12:13], v[16:17], v[120:121], v[12:13]
	v_lshlrev_b64 v[16:17], 13, v[102:103]
	global_store_dwordx4 v[32:33], v[20:23], off offset:512
	v_lshlrev_b32_e32 v14, 16, v93
	v_and_b32_e32 v15, 0xffff0000, v93
	v_lshlrev_b32_e32 v20, 16, v94
	v_and_b32_e32 v21, 0xffff0000, v94
	v_lshlrev_b32_e32 v22, 16, v95
	v_and_b32_e32 v23, 0xffff0000, v95
	v_lshl_add_u64 v[16:17], s[66:67], 0, v[16:17]
	v_pk_fma_f32 v[14:15], v[18:19], v[122:123], v[14:15]
	v_lshl_add_u64 v[16:17], v[16:17], 0, v[174:175]
	v_pk_fma_f32 v[10:11], v[10:11], v[118:119], v[22:23]
	v_pk_fma_f32 v[8:9], v[8:9], v[116:117], v[20:21]
	global_store_dwordx4 v[16:17], v[12:15], off
	global_store_dwordx4 v[16:17], v[8:11], off offset:16
	s_nop 0
	v_lshlrev_b32_e32 v12, 16, v66
	v_lshlrev_b32_e32 v8, 16, v64
	v_and_b32_e32 v9, 0xffff0000, v64
	v_lshlrev_b32_e32 v10, 16, v65
	v_and_b32_e32 v11, 0xffff0000, v65
	v_and_b32_e32 v13, 0xffff0000, v66
	v_lshlrev_b32_e32 v14, 16, v67
	v_and_b32_e32 v15, 0xffff0000, v67
	v_pk_fma_f32 v[6:7], v[6:7], v[114:115], v[10:11]
	v_pk_fma_f32 v[4:5], v[4:5], v[112:113], v[8:9]
	v_pk_fma_f32 v[2:3], v[2:3], v[110:111], v[14:15]
	v_pk_fma_f32 v[0:1], v[0:1], v[108:109], v[12:13]
	global_store_dwordx4 v[16:17], v[4:7], off offset:512
	global_store_dwordx4 v[16:17], v[0:3], off offset:528
	s_cbranch_vccz .LBB0_261
	s_waitcnt vmcnt(0)
	s_cmpk_gt_u32 s16, 0xff
	s_cbranch_scc1 .LBB0_276
	s_barrier

.LBB0_294:
	s_add_u32 s16, s14, 0xfff80080
	s_addc_u32 s17, s15, -1
	s_add_i32 s43, 0, 0x10000
	v_add_u32_e32 v76, s43, v159
	ds_read_b128 v[64:67], v76
	ds_read_b128 v[68:71], v76 offset:1024
	ds_read_b128 v[72:75], v76 offset:2048
	ds_read_b128 v[76:79], v76 offset:3072
	s_cmp_eq_u32 s42, 28
	s_cselect_b32 s19, s7, s17
	s_cselect_b32 s18, s38, s16
	s_cselect_b32 s17, s5, s41
	s_cselect_b32 s16, s39, s40
	s_add_i32 m0, s13, 0xc000
	ds_read_b128 v[154:157], v161
	ds_read_b128 v[162:165], v161 offset:1024
	ds_read_b128 v[166:169], v161 offset:2048
	ds_read_b128 v[170:173], v161 offset:3072
	ds_read_b128 v[174:177], v161 offset:4096
	ds_read_b128 v[178:181], v161 offset:5120
	ds_read_b128 v[182:185], v161 offset:6144
	ds_read_b128 v[186:189], v161 offset:7168
	global_load_lds_dwordx4 v150, s[14:15]
	s_add_i32 m0, s13, 0xe000
	s_nop 0
	global_load_lds_dwordx4 v152, s[14:15]
	s_waitcnt lgkmcnt(8)
	s_barrier
	s_waitcnt lgkmcnt(0)
	s_waitcnt lgkmcnt(0)
	v_mfma_f32_16x16x32_bf16 v[140:143], v[64:67], v[154:157], v[140:143]
	v_mfma_f32_16x16x32_bf16 v[136:139], v[72:75], v[154:157], v[136:139]
	v_mfma_f32_16x16x32_bf16 v[132:135], v[64:67], v[166:169], v[132:135]
	v_mfma_f32_16x16x32_bf16 v[128:131], v[72:75], v[166:169], v[128:131]
	v_mfma_f32_16x16x32_bf16 v[108:111], v[64:67], v[174:177], v[108:111]
	v_mfma_f32_16x16x32_bf16 v[104:107], v[72:75], v[174:177], v[104:107]
	v_mfma_f32_16x16x32_bf16 v[100:103], v[64:67], v[182:185], v[100:103]
	v_mfma_f32_16x16x32_bf16 v[96:99], v[72:75], v[182:185], v[96:99]
	v_mfma_f32_16x16x32_bf16 v[140:143], v[68:71], v[162:165], v[140:143]
	v_mfma_f32_16x16x32_bf16 v[136:139], v[76:79], v[162:165], v[136:139]
	v_mfma_f32_16x16x32_bf16 v[132:135], v[68:71], v[170:173], v[132:135]
	v_mfma_f32_16x16x32_bf16 v[128:131], v[76:79], v[170:173], v[128:131]
	v_mfma_f32_16x16x32_bf16 v[108:111], v[68:71], v[178:181], v[108:111]
	v_mfma_f32_16x16x32_bf16 v[104:107], v[76:79], v[178:181], v[104:107]
	v_mfma_f32_16x16x32_bf16 v[100:103], v[68:71], v[186:189], v[100:103]
	v_mfma_f32_16x16x32_bf16 v[96:99], v[76:79], v[186:189], v[96:99]
	s_barrier
	s_add_i32 s46, 0, 0x14000
	v_add_u32_e32 v190, s46, v159
	s_add_i32 s43, s43, s27
	ds_read_b128 v[196:199], v190
	ds_read_b128 v[204:207], v190 offset:1024
	ds_read_b128 v[208:211], v190 offset:2048
	ds_read_b128 v[214:217], v190 offset:3072
	s_mov_b32 m0, s43
	s_nop 0
	global_load_lds_dwordx4 v192, s[16:17]
	s_add_i32 m0, s43, 0x2000
	s_nop 0
	global_load_lds_dwordx4 v148, s[16:17]
	s_barrier
	s_waitcnt lgkmcnt(0)
	s_waitcnt lgkmcnt(0)
	v_mfma_f32_16x16x32_bf16 v[124:127], v[196:199], v[154:157], v[124:127]
	v_mfma_f32_16x16x32_bf16 v[120:123], v[208:211], v[154:157], v[120:123]
	v_mfma_f32_16x16x32_bf16 v[116:119], v[196:199], v[166:169], v[116:119]
	v_mfma_f32_16x16x32_bf16 v[112:115], v[208:211], v[166:169], v[112:115]
	v_mfma_f32_16x16x32_bf16 v[92:95], v[196:199], v[174:177], v[92:95]
	v_mfma_f32_16x16x32_bf16 v[88:91], v[208:211], v[174:177], v[88:91]
	v_mfma_f32_16x16x32_bf16 v[84:87], v[196:199], v[182:185], v[84:87]
	v_mfma_f32_16x16x32_bf16 v[80:83], v[208:211], v[182:185], v[80:83]
	v_mfma_f32_16x16x32_bf16 v[124:127], v[204:207], v[162:165], v[124:127]
	v_mfma_f32_16x16x32_bf16 v[120:123], v[214:217], v[162:165], v[120:123]
	v_mfma_f32_16x16x32_bf16 v[116:119], v[204:207], v[170:173], v[116:119]
	v_mfma_f32_16x16x32_bf16 v[112:115], v[214:217], v[170:173], v[112:115]
	v_mfma_f32_16x16x32_bf16 v[92:95], v[204:207], v[178:181], v[92:95]
	v_mfma_f32_16x16x32_bf16 v[88:91], v[214:217], v[178:181], v[88:91]
	v_mfma_f32_16x16x32_bf16 v[84:87], v[204:207], v[186:189], v[84:87]
	v_mfma_f32_16x16x32_bf16 v[80:83], v[214:217], v[186:189], v[80:83]
	s_mov_b32 m0, s13
	v_lshl_add_u64 v[220:221], s[18:19], 0, v[144:145]
	s_barrier
	ds_read_b128 v[154:157], v161 offset:16384
	ds_read_b128 v[162:165], v161 offset:17408
	ds_read_b128 v[166:169], v161 offset:18432
	ds_read_b128 v[170:173], v161 offset:19456
	ds_read_b128 v[174:177], v161 offset:20480
	ds_read_b128 v[178:181], v161 offset:21504
	ds_read_b128 v[182:185], v161 offset:22528
	ds_read_b128 v[186:189], v161 offset:23552
	global_load_lds_dwordx4 v144, s[18:19]
	v_lshl_add_u64 v[222:223], s[18:19], 0, v[146:147]
	s_mov_b32 m0, s28
	s_nop 0
	global_load_lds_dwordx4 v146, s[18:19]
	s_barrier
	s_waitcnt lgkmcnt(0)
	s_waitcnt lgkmcnt(0)
	v_mfma_f32_16x16x32_bf16 v[60:63], v[64:67], v[154:157], v[60:63]
	v_mfma_f32_16x16x32_bf16 v[56:59], v[72:75], v[154:157], v[56:59]
	v_mfma_f32_16x16x32_bf16 v[52:55], v[64:67], v[166:169], v[52:55]
	v_mfma_f32_16x16x32_bf16 v[48:51], v[72:75], v[166:169], v[48:51]
	v_mfma_f32_16x16x32_bf16 v[28:31], v[64:67], v[174:177], v[28:31]
	v_mfma_f32_16x16x32_bf16 v[24:27], v[72:75], v[174:177], v[24:27]
	v_mfma_f32_16x16x32_bf16 v[20:23], v[64:67], v[182:185], v[20:23]
	v_mfma_f32_16x16x32_bf16 v[16:19], v[72:75], v[182:185], v[16:19]
	v_mfma_f32_16x16x32_bf16 v[60:63], v[68:71], v[162:165], v[60:63]
	v_mfma_f32_16x16x32_bf16 v[56:59], v[76:79], v[162:165], v[56:59]
	v_mfma_f32_16x16x32_bf16 v[52:55], v[68:71], v[170:173], v[52:55]
	v_mfma_f32_16x16x32_bf16 v[48:51], v[76:79], v[170:173], v[48:51]
	v_mfma_f32_16x16x32_bf16 v[28:31], v[68:71], v[178:181], v[28:31]
	v_mfma_f32_16x16x32_bf16 v[24:27], v[76:79], v[178:181], v[24:27]
	v_mfma_f32_16x16x32_bf16 v[20:23], v[68:71], v[186:189], v[20:23]
	v_mfma_f32_16x16x32_bf16 v[16:19], v[76:79], v[186:189], v[16:19]
	s_barrier
	s_add_u32 s44, s16, 0x80000
	s_addc_u32 s45, s17, 0
	s_add_i32 s43, s46, s27
	s_mov_b32 m0, s43
	s_nop 0
	global_load_lds_dwordx4 v192, s[44:45]
	s_add_i32 m0, s43, 0x2000
	s_nop 0
	global_load_lds_dwordx4 v148, s[44:45]
	s_waitcnt vmcnt(6)
	s_barrier
	v_mfma_f32_16x16x32_bf16 v[44:47], v[196:199], v[154:157], v[44:47]
	v_mfma_f32_16x16x32_bf16 v[40:43], v[208:211], v[154:157], v[40:43]
	v_mfma_f32_16x16x32_bf16 v[36:39], v[196:199], v[166:169], v[36:39]
	v_mfma_f32_16x16x32_bf16 v[32:35], v[208:211], v[166:169], v[32:35]
	v_mfma_f32_16x16x32_bf16 v[12:15], v[196:199], v[174:177], v[12:15]
	v_mfma_f32_16x16x32_bf16 v[8:11], v[208:211], v[174:177], v[8:11]
	v_mfma_f32_16x16x32_bf16 v[4:7], v[196:199], v[182:185], v[4:7]
	v_mfma_f32_16x16x32_bf16 v[0:3], v[208:211], v[182:185], v[0:3]
	v_mfma_f32_16x16x32_bf16 v[44:47], v[204:207], v[162:165], v[44:47]
	v_mfma_f32_16x16x32_bf16 v[40:43], v[214:217], v[162:165], v[40:43]
	v_mfma_f32_16x16x32_bf16 v[36:39], v[204:207], v[170:173], v[36:39]
	v_mfma_f32_16x16x32_bf16 v[32:35], v[214:217], v[170:173], v[32:35]
	v_mfma_f32_16x16x32_bf16 v[12:15], v[204:207], v[178:181], v[12:15]
	v_mfma_f32_16x16x32_bf16 v[8:11], v[214:217], v[178:181], v[8:11]
	v_mfma_f32_16x16x32_bf16 v[4:7], v[204:207], v[186:189], v[4:7]
	v_mfma_f32_16x16x32_bf16 v[0:3], v[214:217], v[186:189], v[0:3]
	s_add_i32 s43, 0, 0x18000
	v_add_u32_e32 v76, s43, v159
	s_barrier
	ds_read_b128 v[64:67], v76
	ds_read_b128 v[68:71], v76 offset:1024
	ds_read_b128 v[72:75], v76 offset:2048
	ds_read_b128 v[76:79], v76 offset:3072
	s_add_u32 s18, s18, 0x80000
	s_addc_u32 s19, s19, 0
	s_mov_b32 m0, s29
	ds_read_b128 v[154:157], v161 offset:32768
	ds_read_b128 v[162:165], v161 offset:33792
	ds_read_b128 v[166:169], v161 offset:34816
	ds_read_b128 v[170:173], v161 offset:35840
	ds_read_b128 v[174:177], v161 offset:36864
	ds_read_b128 v[178:181], v161 offset:37888
	ds_read_b128 v[182:185], v161 offset:38912
	ds_read_b128 v[186:189], v161 offset:39936
	global_load_lds_dwordx4 v144, s[18:19]
	s_mov_b32 m0, s30
	s_nop 0
	global_load_lds_dwordx4 v146, s[18:19]
	s_waitcnt lgkmcnt(8)
	s_barrier
	s_waitcnt lgkmcnt(0)
	s_waitcnt lgkmcnt(0)
	v_mfma_f32_16x16x32_bf16 v[140:143], v[64:67], v[154:157], v[140:143]
	v_mfma_f32_16x16x32_bf16 v[136:139], v[72:75], v[154:157], v[136:139]
	v_mfma_f32_16x16x32_bf16 v[132:135], v[64:67], v[166:169], v[132:135]
	v_mfma_f32_16x16x32_bf16 v[128:131], v[72:75], v[166:169], v[128:131]
	v_mfma_f32_16x16x32_bf16 v[108:111], v[64:67], v[174:177], v[108:111]
	v_mfma_f32_16x16x32_bf16 v[104:107], v[72:75], v[174:177], v[104:107]
	v_mfma_f32_16x16x32_bf16 v[100:103], v[64:67], v[182:185], v[100:103]
	v_mfma_f32_16x16x32_bf16 v[96:99], v[72:75], v[182:185], v[96:99]
	v_mfma_f32_16x16x32_bf16 v[140:143], v[68:71], v[162:165], v[140:143]
	v_mfma_f32_16x16x32_bf16 v[136:139], v[76:79], v[162:165], v[136:139]
	v_mfma_f32_16x16x32_bf16 v[132:135], v[68:71], v[170:173], v[132:135]
	v_mfma_f32_16x16x32_bf16 v[128:131], v[76:79], v[170:173], v[128:131]
	v_mfma_f32_16x16x32_bf16 v[108:111], v[68:71], v[178:181], v[108:111]
	v_mfma_f32_16x16x32_bf16 v[104:107], v[76:79], v[178:181], v[104:107]
	v_mfma_f32_16x16x32_bf16 v[100:103], v[68:71], v[186:189], v[100:103]
	v_mfma_f32_16x16x32_bf16 v[96:99], v[76:79], v[186:189], v[96:99]
	s_barrier
	s_add_i32 s18, 0, 0x1c000
	s_add_i32 s19, s43, s27
	v_add_u32_e32 v212, s18, v159
	s_add_i32 m0, s19, 0xffffff80
	ds_read_b128 v[196:199], v212
	ds_read_b128 v[204:207], v212 offset:1024
	ds_read_b128 v[208:211], v212 offset:2048
	ds_read_b128 v[214:217], v212 offset:3072
	global_load_lds_dwordx4 v192, s[16:17] offset:128
	s_add_i32 m0, s19, 0x1f80
	s_nop 0
	global_load_lds_dwordx4 v148, s[16:17] offset:128
	s_barrier
	s_waitcnt lgkmcnt(0)
	s_waitcnt lgkmcnt(0)
	v_mfma_f32_16x16x32_bf16 v[124:127], v[196:199], v[154:157], v[124:127]
	v_mfma_f32_16x16x32_bf16 v[120:123], v[208:211], v[154:157], v[120:123]
	v_mfma_f32_16x16x32_bf16 v[116:119], v[196:199], v[166:169], v[116:119]
	v_mfma_f32_16x16x32_bf16 v[112:115], v[208:211], v[166:169], v[112:115]
	v_mfma_f32_16x16x32_bf16 v[92:95], v[196:199], v[174:177], v[92:95]
	v_mfma_f32_16x16x32_bf16 v[88:91], v[208:211], v[174:177], v[88:91]
	v_mfma_f32_16x16x32_bf16 v[84:87], v[196:199], v[182:185], v[84:87]
	v_mfma_f32_16x16x32_bf16 v[80:83], v[208:211], v[182:185], v[80:83]
	v_mfma_f32_16x16x32_bf16 v[124:127], v[204:207], v[162:165], v[124:127]
	v_mfma_f32_16x16x32_bf16 v[120:123], v[214:217], v[162:165], v[120:123]
	v_mfma_f32_16x16x32_bf16 v[116:119], v[204:207], v[170:173], v[116:119]
	v_mfma_f32_16x16x32_bf16 v[112:115], v[214:217], v[170:173], v[112:115]
	v_mfma_f32_16x16x32_bf16 v[92:95], v[204:207], v[178:181], v[92:95]
	v_mfma_f32_16x16x32_bf16 v[88:91], v[214:217], v[178:181], v[88:91]
	v_mfma_f32_16x16x32_bf16 v[84:87], v[204:207], v[186:189], v[84:87]
	v_mfma_f32_16x16x32_bf16 v[80:83], v[214:217], v[186:189], v[80:83]
	s_mov_b32 m0, s34
	v_lshl_add_u64 v[190:191], v[220:221], 0, s[48:49]
	s_barrier
	ds_read_b128 v[154:157], v161 offset:49152
	ds_read_b128 v[162:165], v161 offset:50176
	ds_read_b128 v[166:169], v161 offset:51200
	ds_read_b128 v[170:173], v161 offset:52224
	ds_read_b128 v[174:177], v161 offset:53248
	ds_read_b128 v[178:181], v161 offset:54272
	ds_read_b128 v[182:185], v161 offset:55296
	ds_read_b128 v[186:189], v161 offset:56320
	global_load_lds_dwordx4 v[190:191], off
	v_lshl_add_u64 v[190:191], v[222:223], 0, s[48:49]
	s_mov_b32 m0, s35
	s_nop 0
	global_load_lds_dwordx4 v[190:191], off
	s_barrier
	s_waitcnt lgkmcnt(0)
	s_waitcnt lgkmcnt(0)
	v_mfma_f32_16x16x32_bf16 v[60:63], v[64:67], v[154:157], v[60:63]
	v_mfma_f32_16x16x32_bf16 v[56:59], v[72:75], v[154:157], v[56:59]
	v_mfma_f32_16x16x32_bf16 v[52:55], v[64:67], v[166:169], v[52:55]
	v_mfma_f32_16x16x32_bf16 v[48:51], v[72:75], v[166:169], v[48:51]
	v_mfma_f32_16x16x32_bf16 v[28:31], v[64:67], v[174:177], v[28:31]
	v_mfma_f32_16x16x32_bf16 v[24:27], v[72:75], v[174:177], v[24:27]
	v_mfma_f32_16x16x32_bf16 v[20:23], v[64:67], v[182:185], v[20:23]
	v_mfma_f32_16x16x32_bf16 v[16:19], v[72:75], v[182:185], v[16:19]
	v_mfma_f32_16x16x32_bf16 v[60:63], v[68:71], v[162:165], v[60:63]
	v_mfma_f32_16x16x32_bf16 v[56:59], v[76:79], v[162:165], v[56:59]
	v_mfma_f32_16x16x32_bf16 v[52:55], v[68:71], v[170:173], v[52:55]
	v_mfma_f32_16x16x32_bf16 v[48:51], v[76:79], v[170:173], v[48:51]
	v_mfma_f32_16x16x32_bf16 v[28:31], v[68:71], v[178:181], v[28:31]
	v_mfma_f32_16x16x32_bf16 v[24:27], v[76:79], v[178:181], v[24:27]
	v_mfma_f32_16x16x32_bf16 v[20:23], v[68:71], v[186:189], v[20:23]
	v_mfma_f32_16x16x32_bf16 v[16:19], v[76:79], v[186:189], v[16:19]
	s_barrier
	s_add_u32 s16, s16, 0x80080
	s_addc_u32 s17, s17, 0
	s_add_i32 s18, s18, s27
	s_mov_b32 m0, s18
	s_nop 0
	global_load_lds_dwordx4 v192, s[16:17]
	s_add_i32 m0, s18, 0x2000
	s_nop 0
	global_load_lds_dwordx4 v148, s[16:17]
	s_waitcnt vmcnt(6)
	s_barrier
	v_mfma_f32_16x16x32_bf16 v[44:47], v[196:199], v[154:157], v[44:47]
	v_mfma_f32_16x16x32_bf16 v[40:43], v[208:211], v[154:157], v[40:43]
	v_mfma_f32_16x16x32_bf16 v[36:39], v[196:199], v[166:169], v[36:39]
	v_mfma_f32_16x16x32_bf16 v[32:35], v[208:211], v[166:169], v[32:35]
	v_mfma_f32_16x16x32_bf16 v[12:15], v[196:199], v[174:177], v[12:15]
	v_mfma_f32_16x16x32_bf16 v[8:11], v[208:211], v[174:177], v[8:11]
	v_mfma_f32_16x16x32_bf16 v[4:7], v[196:199], v[182:185], v[4:7]
	v_mfma_f32_16x16x32_bf16 v[0:3], v[208:211], v[182:185], v[0:3]
	v_mfma_f32_16x16x32_bf16 v[44:47], v[204:207], v[162:165], v[44:47]
	v_mfma_f32_16x16x32_bf16 v[40:43], v[214:217], v[162:165], v[40:43]
	v_mfma_f32_16x16x32_bf16 v[36:39], v[204:207], v[170:173], v[36:39]
	v_mfma_f32_16x16x32_bf16 v[32:35], v[214:217], v[170:173], v[32:35]
	v_mfma_f32_16x16x32_bf16 v[12:15], v[204:207], v[178:181], v[12:15]
	v_mfma_f32_16x16x32_bf16 v[8:11], v[214:217], v[178:181], v[8:11]
	v_mfma_f32_16x16x32_bf16 v[4:7], v[204:207], v[186:189], v[4:7]
	v_mfma_f32_16x16x32_bf16 v[0:3], v[214:217], v[186:189], v[0:3]
	s_add_i32 s42, s42, 2
	s_add_u32 s14, s14, 0x100
	s_addc_u32 s15, s15, 0
	s_add_u32 s40, s40, 0x100
	s_addc_u32 s41, s41, 0
	s_cmp_gt_u32 s42, 29
	s_barrier
	s_cbranch_scc0 .LBB0_294
	s_ashr_i32 s5, s12, 4
	v_lshl_or_b32 v190, s37, 8, v160
	s_mul_hi_i32 s7, s5, 0xc000
	s_mul_i32 s5, s5, 0xc000
	s_add_u32 s14, s31, s5
	v_ashrrev_i32_e32 v191, 31, v190
	v_lshl_add_u32 v154, s12, 8, v158
	v_readlane_b32 s52, v254, 23
	s_addc_u32 s15, s33, s7
	v_lshlrev_b64 v[156:157], 2, v[190:191]
	v_readlane_b32 s53, v254, 24
	v_ashrrev_i32_e32 v155, 31, v154
	v_lshl_add_u64 v[68:69], s[14:15], 0, v[156:157]
	v_lshl_add_u64 v[156:157], s[52:53], 0, v[156:157]
	v_lshlrev_b64 v[162:163], 13, v[154:155]
	v_lshl_add_u64 v[174:175], v[156:157], 0, v[162:163]
	global_load_dwordx4 v[72:75], v[68:69], off offset:16
	global_load_dwordx4 v[76:79], v[68:69], off
	global_load_dwordx4 v[64:67], v[68:69], off offset:528
	s_nop 0
	global_load_dwordx4 v[68:71], v[68:69], off offset:512
	s_nop 0
	global_load_dwordx4 v[162:165], v[174:175], off offset:16
	global_load_dwordx4 v[166:169], v[174:175], off
	global_load_dwordx4 v[170:173], v[174:175], off offset:528
	s_nop 0
	global_load_dwordx4 v[174:177], v[174:175], off offset:512
	v_or_b32_e32 v204, 16, v154
	v_ashrrev_i32_e32 v205, 31, v204
	v_lshlrev_b64 v[178:179], 13, v[204:205]
	v_lshl_add_u64 v[196:197], v[156:157], 0, v[178:179]
	global_load_dwordx4 v[178:181], v[196:197], off offset:16
	global_load_dwordx4 v[182:185], v[196:197], off
	global_load_dwordx4 v[186:189], v[196:197], off offset:528
	s_nop 0
	global_load_dwordx4 v[196:199], v[196:197], off offset:512
	v_lshlrev_b64 v[206:207], 12, v[154:155]
	s_and_b64 vcc, exec, s[0:1]
	s_mov_b32 s37, s4
	s_mov_b32 s12, s6
	s_mov_b64 s[16:17], s[10:11]
	s_mov_b64 s[14:15], s[8:9]
	s_mov_b32 s11, 0xc000
	v_readlane_b32 s54, v254, 25
	v_readlane_b32 s55, v254, 26
	v_readlane_b32 s56, v254, 27
	v_readlane_b32 s57, v254, 28
	v_readlane_b32 s58, v254, 29
	v_readlane_b32 s59, v254, 30
	v_readlane_b32 s60, v254, 31
	v_readlane_b32 s61, v254, 32
	v_readlane_b32 s62, v254, 33
	v_readlane_b32 s63, v254, 34
	v_readlane_b32 s64, v254, 35
	v_readlane_b32 s65, v254, 36
	v_readlane_b32 s66, v254, 37
	v_readlane_b32 s67, v254, 38
	s_waitcnt vmcnt(0)
	v_pk_fma_f32 v[136:137], v[136:137], v[72:73], v[162:163]
	v_pk_fma_f32 v[142:143], v[142:143], v[78:79], v[168:169]
	v_pk_fma_f32 v[140:141], v[140:141], v[76:77], v[166:167]
	v_pk_fma_f32 v[164:165], v[138:139], v[74:75], v[164:165]
	v_cvt_pk_bf16_f32 v138, v140, v141
	v_cvt_pk_bf16_f32 v139, v142, v143
	v_cvt_pk_bf16_f32 v140, v136, v137
	v_lshl_add_u64 v[142:143], s[2:3], 0, v[206:207]
	v_lshlrev_b64 v[136:137], 1, v[190:191]
	v_lshl_add_u64 v[142:143], v[142:143], 0, v[136:137]
	v_pk_fma_f32 v[124:125], v[124:125], v[68:69], v[174:175]
	v_cvt_pk_bf16_f32 v141, v164, v165
	global_store_dwordx4 v[142:143], v[138:141], off
	v_pk_fma_f32 v[126:127], v[126:127], v[70:71], v[176:177]
	v_pk_fma_f32 v[128:129], v[128:129], v[72:73], v[178:179]
	v_pk_fma_f32 v[138:139], v[122:123], v[66:67], v[172:173]
	v_pk_fma_f32 v[122:123], v[120:121], v[64:65], v[170:171]
	v_cvt_pk_bf16_f32 v120, v124, v125
	v_cvt_pk_bf16_f32 v121, v126, v127
	v_lshlrev_b64 v[124:125], 12, v[204:205]
	v_cvt_pk_bf16_f32 v122, v122, v123
	v_cvt_pk_bf16_f32 v123, v138, v139
	global_store_dwordx4 v[142:143], v[120:123], off offset:256
	v_lshl_add_u64 v[124:125], s[2:3], 0, v[124:125]
	v_lshl_add_u64 v[124:125], v[124:125], 0, v[136:137]
	v_pk_fma_f32 v[120:121], v[132:133], v[76:77], v[182:183]
	v_pk_fma_f32 v[122:123], v[134:135], v[78:79], v[184:185]
	v_cvt_pk_bf16_f32 v120, v120, v121
	v_or_b32_e32 v142, 32, v154
	v_cvt_pk_bf16_f32 v121, v122, v123
	v_pk_fma_f32 v[126:127], v[130:131], v[74:75], v[180:181]
	v_cvt_pk_bf16_f32 v122, v128, v129
	v_pk_fma_f32 v[118:119], v[118:119], v[70:71], v[198:199]
	v_cvt_pk_bf16_f32 v123, v126, v127
	global_store_dwordx4 v[124:125], v[120:123], off
	v_pk_fma_f32 v[116:117], v[116:117], v[68:69], v[196:197]
	v_ashrrev_i32_e32 v143, 31, v142
	v_pk_fma_f32 v[120:121], v[114:115], v[66:67], v[188:189]
	v_pk_fma_f32 v[114:115], v[112:113], v[64:65], v[186:187]
	v_cvt_pk_bf16_f32 v112, v116, v117
	v_cvt_pk_bf16_f32 v113, v118, v119
	v_or_b32_e32 v166, 48, v154
	v_cvt_pk_bf16_f32 v114, v114, v115
	v_cvt_pk_bf16_f32 v115, v120, v121
	global_store_dwordx4 v[124:125], v[112:115], off offset:256
	v_ashrrev_i32_e32 v167, 31, v166
	v_lshlrev_b64 v[128:129], 13, v[166:167]
	v_lshlrev_b64 v[112:113], 13, v[142:143]
	v_lshl_add_u64 v[124:125], v[156:157], 0, v[112:113]
	global_load_dwordx4 v[112:115], v[124:125], off offset:16
	global_load_dwordx4 v[116:119], v[124:125], off
	global_load_dwordx4 v[120:123], v[124:125], off offset:528
	s_nop 0
	global_load_dwordx4 v[124:127], v[124:125], off offset:512
	v_lshl_add_u64 v[162:163], v[156:157], 0, v[128:129]
	global_load_dwordx4 v[128:131], v[162:163], off offset:16
	global_load_dwordx4 v[132:135], v[162:163], off
	global_load_dwordx4 v[138:141], v[162:163], off offset:528
	s_nop 0
	global_load_dwordx4 v[162:165], v[162:163], off offset:512
	v_lshlrev_b64 v[142:143], 12, v[142:143]
	s_waitcnt vmcnt(0)
	v_pk_fma_f32 v[114:115], v[106:107], v[74:75], v[114:115]
	v_pk_fma_f32 v[108:109], v[108:109], v[76:77], v[116:117]
	v_pk_fma_f32 v[106:107], v[104:105], v[72:73], v[112:113]
	v_cvt_pk_bf16_f32 v104, v108, v109
	v_lshl_add_u64 v[108:109], s[2:3], 0, v[142:143]
	v_pk_fma_f32 v[110:111], v[110:111], v[78:79], v[118:119]
	v_lshl_add_u64 v[108:109], v[108:109], 0, v[136:137]
	v_cvt_pk_bf16_f32 v105, v110, v111
	v_pk_fma_f32 v[92:93], v[92:93], v[68:69], v[124:125]
	v_cvt_pk_bf16_f32 v106, v106, v107
	v_cvt_pk_bf16_f32 v107, v114, v115
	global_store_dwordx4 v[108:109], v[104:107], off
	v_pk_fma_f32 v[94:95], v[94:95], v[70:71], v[126:127]
	v_add_u32_e32 v112, 0x80, v154
	v_pk_fma_f32 v[104:105], v[90:91], v[66:67], v[122:123]
	v_pk_fma_f32 v[90:91], v[88:89], v[64:65], v[120:121]
	v_cvt_pk_bf16_f32 v88, v92, v93
	v_cvt_pk_bf16_f32 v89, v94, v95
	v_lshlrev_b64 v[92:93], 12, v[166:167]
	v_cvt_pk_bf16_f32 v90, v90, v91
	v_cvt_pk_bf16_f32 v91, v104, v105
	global_store_dwordx4 v[108:109], v[88:91], off offset:256
	v_lshl_add_u64 v[92:93], s[2:3], 0, v[92:93]
	v_lshl_add_u64 v[92:93], v[92:93], 0, v[136:137]
	v_pk_fma_f32 v[88:89], v[100:101], v[76:77], v[132:133]
	v_pk_fma_f32 v[90:91], v[102:103], v[78:79], v[134:135]
	v_cvt_pk_bf16_f32 v88, v88, v89
	v_pk_fma_f32 v[94:95], v[98:99], v[74:75], v[130:131]
	v_cvt_pk_bf16_f32 v89, v90, v91
	v_pk_fma_f32 v[96:97], v[96:97], v[72:73], v[128:129]
	v_pk_fma_f32 v[86:87], v[86:87], v[70:71], v[164:165]
	v_cvt_pk_bf16_f32 v90, v96, v97
	v_cvt_pk_bf16_f32 v91, v94, v95
	global_store_dwordx4 v[92:93], v[88:91], off
	v_pk_fma_f32 v[84:85], v[84:85], v[68:69], v[162:163]
	v_ashrrev_i32_e32 v113, 31, v112
	v_pk_fma_f32 v[88:89], v[82:83], v[66:67], v[140:141]
	v_pk_fma_f32 v[82:83], v[80:81], v[64:65], v[138:139]
	v_cvt_pk_bf16_f32 v80, v84, v85
	v_cvt_pk_bf16_f32 v81, v86, v87
	v_add_u32_e32 v114, 0x90, v154
	v_cvt_pk_bf16_f32 v82, v82, v83
	v_cvt_pk_bf16_f32 v83, v88, v89
	global_store_dwordx4 v[92:93], v[80:83], off offset:256
	v_ashrrev_i32_e32 v115, 31, v114
	v_lshlrev_b64 v[96:97], 13, v[114:115]
	v_lshlrev_b64 v[80:81], 13, v[112:113]
	v_lshl_add_u64 v[92:93], v[156:157], 0, v[80:81]
	global_load_dwordx4 v[80:83], v[92:93], off offset:16
	global_load_dwordx4 v[84:87], v[92:93], off
	global_load_dwordx4 v[88:91], v[92:93], off offset:528
	s_nop 0
	global_load_dwordx4 v[92:95], v[92:93], off offset:512
	v_lshl_add_u64 v[108:109], v[156:157], 0, v[96:97]
	global_load_dwordx4 v[96:99], v[108:109], off offset:16
	global_load_dwordx4 v[100:103], v[108:109], off
	global_load_dwordx4 v[104:107], v[108:109], off offset:528
	s_nop 0
	global_load_dwordx4 v[108:111], v[108:109], off offset:512
	v_lshlrev_b64 v[112:113], 12, v[112:113]
	s_waitcnt vmcnt(0)
	v_pk_fma_f32 v[82:83], v[58:59], v[74:75], v[82:83]
	v_pk_fma_f32 v[60:61], v[60:61], v[76:77], v[84:85]
	v_pk_fma_f32 v[58:59], v[56:57], v[72:73], v[80:81]
	v_cvt_pk_bf16_f32 v56, v60, v61
	v_lshl_add_u64 v[60:61], s[2:3], 0, v[112:113]
	v_pk_fma_f32 v[62:63], v[62:63], v[78:79], v[86:87]
	v_lshl_add_u64 v[60:61], v[60:61], 0, v[136:137]
	v_cvt_pk_bf16_f32 v57, v62, v63
	v_pk_fma_f32 v[44:45], v[44:45], v[68:69], v[92:93]
	v_cvt_pk_bf16_f32 v58, v58, v59
	v_cvt_pk_bf16_f32 v59, v82, v83
	global_store_dwordx4 v[60:61], v[56:59], off
	v_pk_fma_f32 v[46:47], v[46:47], v[70:71], v[94:95]
	v_add_u32_e32 v80, 0xa0, v154
	v_pk_fma_f32 v[56:57], v[42:43], v[66:67], v[90:91]
	v_pk_fma_f32 v[42:43], v[40:41], v[64:65], v[88:89]
	v_cvt_pk_bf16_f32 v40, v44, v45
	v_cvt_pk_bf16_f32 v41, v46, v47
	v_lshlrev_b64 v[44:45], 12, v[114:115]
	v_cvt_pk_bf16_f32 v42, v42, v43
	v_cvt_pk_bf16_f32 v43, v56, v57
	global_store_dwordx4 v[60:61], v[40:43], off offset:256
	v_lshl_add_u64 v[44:45], s[2:3], 0, v[44:45]
	v_lshl_add_u64 v[44:45], v[44:45], 0, v[136:137]
	v_pk_fma_f32 v[40:41], v[52:53], v[76:77], v[100:101]
	v_pk_fma_f32 v[42:43], v[54:55], v[78:79], v[102:103]
	v_cvt_pk_bf16_f32 v40, v40, v41
	v_pk_fma_f32 v[46:47], v[50:51], v[74:75], v[98:99]
	v_cvt_pk_bf16_f32 v41, v42, v43
	v_pk_fma_f32 v[48:49], v[48:49], v[72:73], v[96:97]
	v_pk_fma_f32 v[38:39], v[38:39], v[70:71], v[110:111]
	v_cvt_pk_bf16_f32 v42, v48, v49
	v_cvt_pk_bf16_f32 v43, v46, v47
	global_store_dwordx4 v[44:45], v[40:43], off
	v_pk_fma_f32 v[36:37], v[36:37], v[68:69], v[108:109]
	v_ashrrev_i32_e32 v81, 31, v80
	v_pk_fma_f32 v[40:41], v[34:35], v[66:67], v[106:107]
	v_pk_fma_f32 v[34:35], v[32:33], v[64:65], v[104:105]
	v_cvt_pk_bf16_f32 v32, v36, v37
	v_cvt_pk_bf16_f32 v33, v38, v39
	v_add_u32_e32 v82, 0xb0, v154
	v_cvt_pk_bf16_f32 v34, v34, v35
	v_cvt_pk_bf16_f32 v35, v40, v41
	global_store_dwordx4 v[44:45], v[32:35], off offset:256
	v_ashrrev_i32_e32 v83, 31, v82
	v_lshlrev_b64 v[48:49], 13, v[82:83]
	v_lshlrev_b64 v[32:33], 13, v[80:81]
	v_lshl_add_u64 v[44:45], v[156:157], 0, v[32:33]
	global_load_dwordx4 v[32:35], v[44:45], off offset:16
	global_load_dwordx4 v[36:39], v[44:45], off
	global_load_dwordx4 v[40:43], v[44:45], off offset:528
	s_nop 0
	global_load_dwordx4 v[44:47], v[44:45], off offset:512
	v_lshl_add_u64 v[60:61], v[156:157], 0, v[48:49]
	global_load_dwordx4 v[48:51], v[60:61], off offset:16
	global_load_dwordx4 v[52:55], v[60:61], off
	global_load_dwordx4 v[56:59], v[60:61], off offset:528
	s_nop 0
	global_load_dwordx4 v[60:63], v[60:61], off offset:512
	v_lshlrev_b64 v[80:81], 12, v[80:81]
	s_waitcnt vmcnt(0)
	v_pk_fma_f32 v[34:35], v[26:27], v[74:75], v[34:35]
	v_pk_fma_f32 v[28:29], v[28:29], v[76:77], v[36:37]
	v_pk_fma_f32 v[26:27], v[24:25], v[72:73], v[32:33]
	v_cvt_pk_bf16_f32 v24, v28, v29
	v_lshl_add_u64 v[28:29], s[2:3], 0, v[80:81]
	v_pk_fma_f32 v[30:31], v[30:31], v[78:79], v[38:39]
	v_lshl_add_u64 v[28:29], v[28:29], 0, v[136:137]
	v_cvt_pk_bf16_f32 v25, v30, v31
	v_pk_fma_f32 v[12:13], v[12:13], v[68:69], v[44:45]
	v_cvt_pk_bf16_f32 v26, v26, v27
	v_cvt_pk_bf16_f32 v27, v34, v35
	global_store_dwordx4 v[28:29], v[24:27], off
	v_pk_fma_f32 v[14:15], v[14:15], v[70:71], v[46:47]
	v_pk_fma_f32 v[16:17], v[16:17], v[72:73], v[48:49]
	v_pk_fma_f32 v[24:25], v[10:11], v[66:67], v[42:43]
	v_pk_fma_f32 v[10:11], v[8:9], v[64:65], v[40:41]
	v_cvt_pk_bf16_f32 v8, v12, v13
	v_cvt_pk_bf16_f32 v9, v14, v15
	v_lshlrev_b64 v[12:13], 12, v[82:83]
	v_cvt_pk_bf16_f32 v10, v10, v11
	v_cvt_pk_bf16_f32 v11, v24, v25
	global_store_dwordx4 v[28:29], v[8:11], off offset:256
	v_lshl_add_u64 v[12:13], s[2:3], 0, v[12:13]
	v_lshl_add_u64 v[12:13], v[12:13], 0, v[136:137]
	v_pk_fma_f32 v[8:9], v[20:21], v[76:77], v[52:53]
	v_pk_fma_f32 v[10:11], v[22:23], v[78:79], v[54:55]
	v_cvt_pk_bf16_f32 v8, v8, v9
	v_pk_fma_f32 v[14:15], v[18:19], v[74:75], v[50:51]
	v_cvt_pk_bf16_f32 v9, v10, v11
	v_cvt_pk_bf16_f32 v10, v16, v17
	v_pk_fma_f32 v[6:7], v[6:7], v[70:71], v[62:63]
	v_cvt_pk_bf16_f32 v11, v14, v15
	global_store_dwordx4 v[12:13], v[8:11], off
	v_pk_fma_f32 v[4:5], v[4:5], v[68:69], v[60:61]
	s_nop 0
	v_pk_fma_f32 v[8:9], v[2:3], v[66:67], v[58:59]
	v_pk_fma_f32 v[2:3], v[0:1], v[64:65], v[56:57]
	v_cvt_pk_bf16_f32 v0, v4, v5
	v_cvt_pk_bf16_f32 v1, v6, v7
	s_nop 0
	v_cvt_pk_bf16_f32 v2, v2, v3
	v_cvt_pk_bf16_f32 v3, v8, v9
	global_store_dwordx4 v[12:13], v[0:3], off offset:256
	s_cbranch_vccz .LBB0_287
	s_waitcnt vmcnt(0)
	s_cmpk_gt_u32 s25, 0xff
	s_cbranch_scc1 .LBB0_298
	s_barrier

.LBB0_415:
	s_add_u32 s18, s16, 0xfff80080
	s_addc_u32 s19, s17, -1
	s_add_i32 s43, 0, 0x10000
	v_add_u32_e32 v140, s43, v143
	ds_read_b128 v[146:149], v140
	ds_read_b128 v[150:153], v140 offset:1024
	ds_read_b128 v[154:157], v140 offset:2048
	ds_read_b128 v[158:161], v140 offset:3072
	s_cmp_eq_u32 s42, 28
	s_cselect_b32 s21, s9, s19
	s_cselect_b32 s20, s38, s18
	s_cselect_b32 s19, s7, s41
	s_cselect_b32 s18, s39, s40
	s_add_i32 m0, s30, 0xc000
	ds_read_b128 v[162:165], v145
	ds_read_b128 v[166:169], v145 offset:1024
	ds_read_b128 v[170:173], v145 offset:2048
	ds_read_b128 v[174:177], v145 offset:3072
	ds_read_b128 v[178:181], v145 offset:4096
	ds_read_b128 v[182:185], v145 offset:5120
	ds_read_b128 v[186:189], v145 offset:6144
	ds_read_b128 v[204:207], v145 offset:7168
	global_load_lds_dwordx4 v136, s[16:17]
	s_add_i32 m0, s30, 0xe000
	s_nop 0
	global_load_lds_dwordx4 v138, s[16:17]
	s_waitcnt lgkmcnt(8)
	s_barrier
	s_waitcnt lgkmcnt(0)
	s_waitcnt lgkmcnt(0)
	v_mfma_f32_16x16x32_bf16 v[124:127], v[146:149], v[162:165], v[124:127]
	v_mfma_f32_16x16x32_bf16 v[120:123], v[154:157], v[162:165], v[120:123]
	v_mfma_f32_16x16x32_bf16 v[116:119], v[146:149], v[170:173], v[116:119]
	v_mfma_f32_16x16x32_bf16 v[108:111], v[154:157], v[170:173], v[108:111]
	v_mfma_f32_16x16x32_bf16 v[100:103], v[146:149], v[178:181], v[100:103]
	v_mfma_f32_16x16x32_bf16 v[92:95], v[154:157], v[178:181], v[92:95]
	v_mfma_f32_16x16x32_bf16 v[84:87], v[146:149], v[186:189], v[84:87]
	v_mfma_f32_16x16x32_bf16 v[76:79], v[154:157], v[186:189], v[76:79]
	v_mfma_f32_16x16x32_bf16 v[124:127], v[150:153], v[166:169], v[124:127]
	v_mfma_f32_16x16x32_bf16 v[120:123], v[158:161], v[166:169], v[120:123]
	v_mfma_f32_16x16x32_bf16 v[116:119], v[150:153], v[174:177], v[116:119]
	v_mfma_f32_16x16x32_bf16 v[108:111], v[158:161], v[174:177], v[108:111]
	v_mfma_f32_16x16x32_bf16 v[100:103], v[150:153], v[182:185], v[100:103]
	v_mfma_f32_16x16x32_bf16 v[92:95], v[158:161], v[182:185], v[92:95]
	v_mfma_f32_16x16x32_bf16 v[84:87], v[150:153], v[204:207], v[84:87]
	v_mfma_f32_16x16x32_bf16 v[76:79], v[158:161], v[204:207], v[76:79]
	s_barrier
	s_add_i32 s46, 0, 0x14000
	v_add_u32_e32 v140, s46, v143
	s_add_i32 s43, s43, s28
	ds_read_b128 v[208:211], v140
	ds_read_b128 v[214:217], v140 offset:1024
	ds_read_b128 v[218:221], v140 offset:2048
	ds_read_b128 v[222:225], v140 offset:3072
	s_mov_b32 m0, s43
	s_nop 0
	global_load_lds_dwordx4 v192, s[18:19]
	s_add_i32 m0, s43, 0x2000
	s_nop 0
	global_load_lds_dwordx4 v128, s[18:19]
	s_barrier
	s_waitcnt lgkmcnt(0)
	s_waitcnt lgkmcnt(0)
	v_mfma_f32_16x16x32_bf16 v[112:115], v[208:211], v[162:165], v[112:115]
	v_mfma_f32_16x16x32_bf16 v[104:107], v[218:221], v[162:165], v[104:107]
	v_mfma_f32_16x16x32_bf16 v[96:99], v[208:211], v[170:173], v[96:99]
	v_mfma_f32_16x16x32_bf16 v[88:91], v[218:221], v[170:173], v[88:91]
	v_mfma_f32_16x16x32_bf16 v[80:83], v[208:211], v[178:181], v[80:83]
	v_mfma_f32_16x16x32_bf16 v[72:75], v[218:221], v[178:181], v[72:75]
	v_mfma_f32_16x16x32_bf16 v[68:71], v[208:211], v[186:189], v[68:71]
	v_mfma_f32_16x16x32_bf16 v[64:67], v[218:221], v[186:189], v[64:67]
	v_mfma_f32_16x16x32_bf16 v[112:115], v[214:217], v[166:169], v[112:115]
	v_mfma_f32_16x16x32_bf16 v[104:107], v[222:225], v[166:169], v[104:107]
	v_mfma_f32_16x16x32_bf16 v[96:99], v[214:217], v[174:177], v[96:99]
	v_mfma_f32_16x16x32_bf16 v[88:91], v[222:225], v[174:177], v[88:91]
	v_mfma_f32_16x16x32_bf16 v[80:83], v[214:217], v[182:185], v[80:83]
	v_mfma_f32_16x16x32_bf16 v[72:75], v[222:225], v[182:185], v[72:75]
	v_mfma_f32_16x16x32_bf16 v[68:71], v[214:217], v[204:207], v[68:71]
	v_mfma_f32_16x16x32_bf16 v[64:67], v[222:225], v[204:207], v[64:67]
	s_mov_b32 m0, s30
	v_lshl_add_u64 v[196:197], s[20:21], 0, v[132:133]
	s_barrier
	ds_read_b128 v[162:165], v145 offset:16384
	ds_read_b128 v[166:169], v145 offset:17408
	ds_read_b128 v[170:173], v145 offset:18432
	ds_read_b128 v[174:177], v145 offset:19456
	ds_read_b128 v[178:181], v145 offset:20480
	ds_read_b128 v[182:185], v145 offset:21504
	ds_read_b128 v[186:189], v145 offset:22528
	ds_read_b128 v[204:207], v145 offset:23552
	global_load_lds_dwordx4 v132, s[20:21]
	v_lshl_add_u64 v[198:199], s[20:21], 0, v[130:131]
	s_mov_b32 m0, s31
	s_nop 0
	global_load_lds_dwordx4 v130, s[20:21]
	s_barrier
	s_waitcnt lgkmcnt(0)
	s_waitcnt lgkmcnt(0)
	v_mfma_f32_16x16x32_bf16 v[60:63], v[146:149], v[162:165], v[60:63]
	v_mfma_f32_16x16x32_bf16 v[56:59], v[154:157], v[162:165], v[56:59]
	v_mfma_f32_16x16x32_bf16 v[52:55], v[146:149], v[170:173], v[52:55]
	v_mfma_f32_16x16x32_bf16 v[44:47], v[154:157], v[170:173], v[44:47]
	v_mfma_f32_16x16x32_bf16 v[36:39], v[146:149], v[178:181], v[36:39]
	v_mfma_f32_16x16x32_bf16 v[28:31], v[154:157], v[178:181], v[28:31]
	v_mfma_f32_16x16x32_bf16 v[20:23], v[146:149], v[186:189], v[20:23]
	v_mfma_f32_16x16x32_bf16 v[12:15], v[154:157], v[186:189], v[12:15]
	v_mfma_f32_16x16x32_bf16 v[60:63], v[150:153], v[166:169], v[60:63]
	v_mfma_f32_16x16x32_bf16 v[56:59], v[158:161], v[166:169], v[56:59]
	v_mfma_f32_16x16x32_bf16 v[52:55], v[150:153], v[174:177], v[52:55]
	v_mfma_f32_16x16x32_bf16 v[44:47], v[158:161], v[174:177], v[44:47]
	v_mfma_f32_16x16x32_bf16 v[36:39], v[150:153], v[182:185], v[36:39]
	v_mfma_f32_16x16x32_bf16 v[28:31], v[158:161], v[182:185], v[28:31]
	v_mfma_f32_16x16x32_bf16 v[20:23], v[150:153], v[204:207], v[20:23]
	v_mfma_f32_16x16x32_bf16 v[12:15], v[158:161], v[204:207], v[12:15]
	s_barrier
	s_add_u32 s44, s18, 0x80000
	s_addc_u32 s45, s19, 0
	s_add_i32 s43, s46, s28
	s_mov_b32 m0, s43
	s_nop 0
	global_load_lds_dwordx4 v192, s[44:45]
	s_add_i32 m0, s43, 0x2000
	s_nop 0
	global_load_lds_dwordx4 v128, s[44:45]
	s_waitcnt vmcnt(6)
	s_barrier
	v_mfma_f32_16x16x32_bf16 v[48:51], v[208:211], v[162:165], v[48:51]
	v_mfma_f32_16x16x32_bf16 v[40:43], v[218:221], v[162:165], v[40:43]
	v_mfma_f32_16x16x32_bf16 v[32:35], v[208:211], v[170:173], v[32:35]
	v_mfma_f32_16x16x32_bf16 v[24:27], v[218:221], v[170:173], v[24:27]
	v_mfma_f32_16x16x32_bf16 v[16:19], v[208:211], v[178:181], v[16:19]
	v_mfma_f32_16x16x32_bf16 v[8:11], v[218:221], v[178:181], v[8:11]
	v_mfma_f32_16x16x32_bf16 v[4:7], v[208:211], v[186:189], v[4:7]
	v_mfma_f32_16x16x32_bf16 v[0:3], v[218:221], v[186:189], v[0:3]
	v_mfma_f32_16x16x32_bf16 v[48:51], v[214:217], v[166:169], v[48:51]
	v_mfma_f32_16x16x32_bf16 v[40:43], v[222:225], v[166:169], v[40:43]
	v_mfma_f32_16x16x32_bf16 v[32:35], v[214:217], v[174:177], v[32:35]
	v_mfma_f32_16x16x32_bf16 v[24:27], v[222:225], v[174:177], v[24:27]
	v_mfma_f32_16x16x32_bf16 v[16:19], v[214:217], v[182:185], v[16:19]
	v_mfma_f32_16x16x32_bf16 v[8:11], v[222:225], v[182:185], v[8:11]
	v_mfma_f32_16x16x32_bf16 v[4:7], v[214:217], v[204:207], v[4:7]
	v_mfma_f32_16x16x32_bf16 v[0:3], v[222:225], v[204:207], v[0:3]
	s_add_i32 s43, 0, 0x18000
	v_add_u32_e32 v158, s43, v143
	s_barrier
	ds_read_b128 v[146:149], v158
	ds_read_b128 v[150:153], v158 offset:1024
	ds_read_b128 v[154:157], v158 offset:2048
	ds_read_b128 v[158:161], v158 offset:3072
	s_add_u32 s20, s20, 0x80000
	s_addc_u32 s21, s21, 0
	s_mov_b32 m0, s33
	ds_read_b128 v[162:165], v145 offset:32768
	ds_read_b128 v[166:169], v145 offset:33792
	ds_read_b128 v[170:173], v145 offset:34816
	ds_read_b128 v[174:177], v145 offset:35840
	ds_read_b128 v[178:181], v145 offset:36864
	ds_read_b128 v[182:185], v145 offset:37888
	ds_read_b128 v[186:189], v145 offset:38912
	ds_read_b128 v[204:207], v145 offset:39936
	global_load_lds_dwordx4 v132, s[20:21]
	s_mov_b32 m0, s34
	s_nop 0
	global_load_lds_dwordx4 v130, s[20:21]
	s_waitcnt lgkmcnt(8)
	s_barrier
	s_waitcnt lgkmcnt(0)
	s_waitcnt lgkmcnt(0)
	v_mfma_f32_16x16x32_bf16 v[124:127], v[146:149], v[162:165], v[124:127]
	v_mfma_f32_16x16x32_bf16 v[120:123], v[154:157], v[162:165], v[120:123]
	v_mfma_f32_16x16x32_bf16 v[116:119], v[146:149], v[170:173], v[116:119]
	v_mfma_f32_16x16x32_bf16 v[108:111], v[154:157], v[170:173], v[108:111]
	v_mfma_f32_16x16x32_bf16 v[100:103], v[146:149], v[178:181], v[100:103]
	v_mfma_f32_16x16x32_bf16 v[92:95], v[154:157], v[178:181], v[92:95]
	v_mfma_f32_16x16x32_bf16 v[84:87], v[146:149], v[186:189], v[84:87]
	v_mfma_f32_16x16x32_bf16 v[76:79], v[154:157], v[186:189], v[76:79]
	v_mfma_f32_16x16x32_bf16 v[124:127], v[150:153], v[166:169], v[124:127]
	v_mfma_f32_16x16x32_bf16 v[120:123], v[158:161], v[166:169], v[120:123]
	v_mfma_f32_16x16x32_bf16 v[116:119], v[150:153], v[174:177], v[116:119]
	v_mfma_f32_16x16x32_bf16 v[108:111], v[158:161], v[174:177], v[108:111]
	v_mfma_f32_16x16x32_bf16 v[100:103], v[150:153], v[182:185], v[100:103]
	v_mfma_f32_16x16x32_bf16 v[92:95], v[158:161], v[182:185], v[92:95]
	v_mfma_f32_16x16x32_bf16 v[84:87], v[150:153], v[204:207], v[84:87]
	v_mfma_f32_16x16x32_bf16 v[76:79], v[158:161], v[204:207], v[76:79]
	s_barrier
	s_add_i32 s20, 0, 0x1c000
	s_add_i32 s21, s43, s28
	v_add_u32_e32 v212, s20, v143
	s_add_i32 m0, s21, 0xffffff80
	ds_read_b128 v[208:211], v212
	ds_read_b128 v[214:217], v212 offset:1024
	ds_read_b128 v[218:221], v212 offset:2048
	ds_read_b128 v[222:225], v212 offset:3072
	global_load_lds_dwordx4 v192, s[18:19] offset:128
	s_add_i32 m0, s21, 0x1f80
	s_nop 0
	global_load_lds_dwordx4 v128, s[18:19] offset:128
	s_barrier
	s_waitcnt lgkmcnt(0)
	s_waitcnt lgkmcnt(0)
	v_mfma_f32_16x16x32_bf16 v[112:115], v[208:211], v[162:165], v[112:115]
	v_mfma_f32_16x16x32_bf16 v[104:107], v[218:221], v[162:165], v[104:107]
	v_mfma_f32_16x16x32_bf16 v[96:99], v[208:211], v[170:173], v[96:99]
	v_mfma_f32_16x16x32_bf16 v[88:91], v[218:221], v[170:173], v[88:91]
	v_mfma_f32_16x16x32_bf16 v[80:83], v[208:211], v[178:181], v[80:83]
	v_mfma_f32_16x16x32_bf16 v[72:75], v[218:221], v[178:181], v[72:75]
	v_mfma_f32_16x16x32_bf16 v[68:71], v[208:211], v[186:189], v[68:71]
	v_mfma_f32_16x16x32_bf16 v[64:67], v[218:221], v[186:189], v[64:67]
	v_mfma_f32_16x16x32_bf16 v[112:115], v[214:217], v[166:169], v[112:115]
	v_mfma_f32_16x16x32_bf16 v[104:107], v[222:225], v[166:169], v[104:107]
	v_mfma_f32_16x16x32_bf16 v[96:99], v[214:217], v[174:177], v[96:99]
	v_mfma_f32_16x16x32_bf16 v[88:91], v[222:225], v[174:177], v[88:91]
	v_mfma_f32_16x16x32_bf16 v[80:83], v[214:217], v[182:185], v[80:83]
	v_mfma_f32_16x16x32_bf16 v[72:75], v[222:225], v[182:185], v[72:75]
	v_mfma_f32_16x16x32_bf16 v[68:71], v[214:217], v[204:207], v[68:71]
	v_mfma_f32_16x16x32_bf16 v[64:67], v[222:225], v[204:207], v[64:67]
	s_mov_b32 m0, s35
	v_lshl_add_u64 v[140:141], v[196:197], 0, s[48:49]
	s_barrier
	ds_read_b128 v[162:165], v145 offset:49152
	ds_read_b128 v[166:169], v145 offset:50176
	ds_read_b128 v[170:173], v145 offset:51200
	ds_read_b128 v[174:177], v145 offset:52224
	ds_read_b128 v[178:181], v145 offset:53248
	ds_read_b128 v[182:185], v145 offset:54272
	ds_read_b128 v[186:189], v145 offset:55296
	ds_read_b128 v[204:207], v145 offset:56320
	global_load_lds_dwordx4 v[140:141], off
	v_lshl_add_u64 v[140:141], v[198:199], 0, s[48:49]
	s_mov_b32 m0, s36
	s_nop 0
	global_load_lds_dwordx4 v[140:141], off
	s_barrier
	s_waitcnt lgkmcnt(0)
	s_waitcnt lgkmcnt(0)
	v_mfma_f32_16x16x32_bf16 v[60:63], v[146:149], v[162:165], v[60:63]
	v_mfma_f32_16x16x32_bf16 v[56:59], v[154:157], v[162:165], v[56:59]
	v_mfma_f32_16x16x32_bf16 v[52:55], v[146:149], v[170:173], v[52:55]
	v_mfma_f32_16x16x32_bf16 v[44:47], v[154:157], v[170:173], v[44:47]
	v_mfma_f32_16x16x32_bf16 v[36:39], v[146:149], v[178:181], v[36:39]
	v_mfma_f32_16x16x32_bf16 v[28:31], v[154:157], v[178:181], v[28:31]
	v_mfma_f32_16x16x32_bf16 v[20:23], v[146:149], v[186:189], v[20:23]
	v_mfma_f32_16x16x32_bf16 v[12:15], v[154:157], v[186:189], v[12:15]
	v_mfma_f32_16x16x32_bf16 v[60:63], v[150:153], v[166:169], v[60:63]
	v_mfma_f32_16x16x32_bf16 v[56:59], v[158:161], v[166:169], v[56:59]
	v_mfma_f32_16x16x32_bf16 v[52:55], v[150:153], v[174:177], v[52:55]
	v_mfma_f32_16x16x32_bf16 v[44:47], v[158:161], v[174:177], v[44:47]
	v_mfma_f32_16x16x32_bf16 v[36:39], v[150:153], v[182:185], v[36:39]
	v_mfma_f32_16x16x32_bf16 v[28:31], v[158:161], v[182:185], v[28:31]
	v_mfma_f32_16x16x32_bf16 v[20:23], v[150:153], v[204:207], v[20:23]
	v_mfma_f32_16x16x32_bf16 v[12:15], v[158:161], v[204:207], v[12:15]
	s_barrier
	s_add_u32 s18, s18, 0x80080
	s_addc_u32 s19, s19, 0
	s_add_i32 s20, s20, s28
	s_mov_b32 m0, s20
	s_nop 0
	global_load_lds_dwordx4 v192, s[18:19]
	s_add_i32 m0, s20, 0x2000
	s_nop 0
	global_load_lds_dwordx4 v128, s[18:19]
	s_waitcnt vmcnt(6)
	s_barrier
	v_mfma_f32_16x16x32_bf16 v[48:51], v[208:211], v[162:165], v[48:51]
	v_mfma_f32_16x16x32_bf16 v[40:43], v[218:221], v[162:165], v[40:43]
	v_mfma_f32_16x16x32_bf16 v[32:35], v[208:211], v[170:173], v[32:35]
	v_mfma_f32_16x16x32_bf16 v[24:27], v[218:221], v[170:173], v[24:27]
	v_mfma_f32_16x16x32_bf16 v[16:19], v[208:211], v[178:181], v[16:19]
	v_mfma_f32_16x16x32_bf16 v[8:11], v[218:221], v[178:181], v[8:11]
	v_mfma_f32_16x16x32_bf16 v[4:7], v[208:211], v[186:189], v[4:7]
	v_mfma_f32_16x16x32_bf16 v[0:3], v[218:221], v[186:189], v[0:3]
	v_mfma_f32_16x16x32_bf16 v[48:51], v[214:217], v[166:169], v[48:51]
	v_mfma_f32_16x16x32_bf16 v[40:43], v[222:225], v[166:169], v[40:43]
	v_mfma_f32_16x16x32_bf16 v[32:35], v[214:217], v[174:177], v[32:35]
	v_mfma_f32_16x16x32_bf16 v[24:27], v[222:225], v[174:177], v[24:27]
	v_mfma_f32_16x16x32_bf16 v[16:19], v[214:217], v[182:185], v[16:19]
	v_mfma_f32_16x16x32_bf16 v[8:11], v[222:225], v[182:185], v[8:11]
	v_mfma_f32_16x16x32_bf16 v[4:7], v[214:217], v[204:207], v[4:7]
	v_mfma_f32_16x16x32_bf16 v[0:3], v[222:225], v[204:207], v[0:3]
	s_add_i32 s42, s42, 2
	s_add_u32 s16, s16, 0x100
	s_addc_u32 s17, s17, 0
	s_add_u32 s40, s40, 0x100
	s_addc_u32 s41, s41, 0
	s_cmp_gt_u32 s42, 29
	s_barrier
	s_cbranch_scc0 .LBB0_415
	s_mul_hi_i32 s9, s15, 0x2aaaaaab
	v_lshl_add_u32 v153, s14, 8, v142
	s_lshr_b32 s14, s9, 31
	s_lshr_b32 s9, s9, 2
	s_add_i32 s9, s9, s14
	s_lshl_b32 s7, s15, 8
	s_mul_i32 s16, s9, 0x1800
	v_readlane_b32 s40, v254, 14
	v_readlane_b32 s41, v254, 15
	s_sub_i32 s40, s7, s16
	s_mov_b64 s[20:21], s[40:41]
	v_readlane_b32 s42, v254, 16
	v_readlane_b32 s43, v254, 17
	v_writelane_b32 v254, s20, 14
	s_mov_b64 s[14:15], -1
	s_cmpk_gt_i32 s40, 0xfff
	v_writelane_b32 v254, s21, 15
	v_writelane_b32 v254, s22, 16
	v_writelane_b32 v254, s23, 17
	v_or_b32_e32 v152, 16, v153
	v_or_b32_e32 v151, 32, v153
	v_or_b32_e32 v150, 48, v153
	v_add_u32_e32 v149, 0x80, v153
	v_add_u32_e32 v148, 0x90, v153
	v_add_u32_e32 v147, 0xa0, v153
	v_add_u32_e32 v146, 0xb0, v153
	s_cbranch_scc0 .LBB0_418
	v_mov_b32_e32 v156, v193
	v_mov_b32_e32 v157, v193
	s_ashr_i32 s17, s16, 31
	v_mov_b64_e32 v[140:141], s[2:3]
	s_mov_b32 s9, 0x9000
	v_cvt_pk_fp8_f32 v156, v124, v125
	v_cvt_pk_fp8_f32 v157, v120, v121
	s_lshl_b64 s[14:15], s[16:17], 1
	v_mad_i64_i32 v[154:155], s[16:17], v153, s9, v[140:141]
	s_add_u32 s14, s14, 0x2000
	v_readlane_b32 s16, v254, 14
	s_addc_u32 s15, s15, 0
	v_readlane_b32 s17, v254, 15
	v_lshl_add_u64 v[154:155], v[154:155], 0, s[14:15]
	s_mov_b64 s[20:21], s[16:17]
	v_cvt_pk_fp8_f32 v156, v126, v127 op_sel:[0,0,1]
	v_cvt_pk_fp8_f32 v157, v122, v123 op_sel:[0,0,1]
	v_lshl_add_u64 v[154:155], v[154:155], 0, s[20:21]
	v_lshl_add_u64 v[154:155], v[154:155], 0, s[4:5]
	v_lshl_add_u64 v[154:155], v[154:155], 0, v[134:135]
	global_store_dwordx2 v[154:155], v[156:157], off offset:-4096
	v_mov_b32_e32 v156, v193
	v_mov_b32_e32 v157, v193
	v_cvt_pk_fp8_f32 v156, v112, v113
	v_cvt_pk_fp8_f32 v157, v104, v105
	v_readlane_b32 s18, v254, 16
	v_readlane_b32 s19, v254, 17
	v_cvt_pk_fp8_f32 v156, v114, v115 op_sel:[0,0,1]
	v_cvt_pk_fp8_f32 v157, v106, v107 op_sel:[0,0,1]
	global_store_dwordx2 v[154:155], v[156:157], off offset:-3968
	v_mov_b32_e32 v156, v193
	v_mov_b32_e32 v157, v193
	v_cvt_pk_fp8_f32 v156, v116, v117
	v_cvt_pk_fp8_f32 v157, v108, v109
	v_mad_i64_i32 v[154:155], s[16:17], v152, s9, v[140:141]
	v_lshl_add_u64 v[154:155], v[154:155], 0, s[14:15]
	v_cvt_pk_fp8_f32 v156, v118, v119 op_sel:[0,0,1]
	v_cvt_pk_fp8_f32 v157, v110, v111 op_sel:[0,0,1]
	v_lshl_add_u64 v[154:155], v[154:155], 0, s[20:21]
	v_lshl_add_u64 v[154:155], v[154:155], 0, s[4:5]
	v_lshl_add_u64 v[154:155], v[154:155], 0, v[134:135]
	global_store_dwordx2 v[154:155], v[156:157], off offset:-4096
	v_mov_b32_e32 v156, v193
	v_mov_b32_e32 v157, v193
	v_cvt_pk_fp8_f32 v156, v96, v97
	v_cvt_pk_fp8_f32 v157, v88, v89
	v_cvt_pk_fp8_f32 v156, v98, v99 op_sel:[0,0,1]
	v_cvt_pk_fp8_f32 v157, v90, v91 op_sel:[0,0,1]
	global_store_dwordx2 v[154:155], v[156:157], off offset:-3968
	v_mov_b32_e32 v156, v193
	v_mov_b32_e32 v157, v193
	v_cvt_pk_fp8_f32 v156, v100, v101
	v_cvt_pk_fp8_f32 v157, v92, v93
	v_mad_i64_i32 v[154:155], s[16:17], v151, s9, v[140:141]
	v_lshl_add_u64 v[154:155], v[154:155], 0, s[14:15]
	v_cvt_pk_fp8_f32 v156, v102, v103 op_sel:[0,0,1]
	v_cvt_pk_fp8_f32 v157, v94, v95 op_sel:[0,0,1]
	v_lshl_add_u64 v[154:155], v[154:155], 0, s[20:21]
	v_lshl_add_u64 v[154:155], v[154:155], 0, s[4:5]
	v_lshl_add_u64 v[154:155], v[154:155], 0, v[134:135]
	global_store_dwordx2 v[154:155], v[156:157], off offset:-4096
	v_mov_b32_e32 v156, v193
	v_mov_b32_e32 v157, v193
	v_cvt_pk_fp8_f32 v156, v80, v81
	v_cvt_pk_fp8_f32 v157, v72, v73
	v_cvt_pk_fp8_f32 v156, v82, v83 op_sel:[0,0,1]
	v_cvt_pk_fp8_f32 v157, v74, v75 op_sel:[0,0,1]
	global_store_dwordx2 v[154:155], v[156:157], off offset:-3968
	v_mov_b32_e32 v156, v193
	v_mov_b32_e32 v157, v193
	v_cvt_pk_fp8_f32 v156, v84, v85
	v_cvt_pk_fp8_f32 v157, v76, v77
	v_mad_i64_i32 v[154:155], s[16:17], v150, s9, v[140:141]
	v_lshl_add_u64 v[154:155], v[154:155], 0, s[14:15]
	v_cvt_pk_fp8_f32 v156, v86, v87 op_sel:[0,0,1]
	v_cvt_pk_fp8_f32 v157, v78, v79 op_sel:[0,0,1]
	v_lshl_add_u64 v[154:155], v[154:155], 0, s[20:21]
	v_lshl_add_u64 v[154:155], v[154:155], 0, s[4:5]
	v_lshl_add_u64 v[154:155], v[154:155], 0, v[134:135]
	global_store_dwordx2 v[154:155], v[156:157], off offset:-4096
	v_mov_b32_e32 v156, v193
	v_mov_b32_e32 v157, v193
	v_cvt_pk_fp8_f32 v156, v68, v69
	v_cvt_pk_fp8_f32 v157, v64, v65
	v_cvt_pk_fp8_f32 v156, v70, v71 op_sel:[0,0,1]
	v_cvt_pk_fp8_f32 v157, v66, v67 op_sel:[0,0,1]
	global_store_dwordx2 v[154:155], v[156:157], off offset:-3968
	v_mov_b32_e32 v156, v193
	v_mov_b32_e32 v157, v193
	v_cvt_pk_fp8_f32 v156, v60, v61
	v_cvt_pk_fp8_f32 v157, v56, v57
	v_mad_i64_i32 v[154:155], s[16:17], v149, s9, v[140:141]
	v_lshl_add_u64 v[154:155], v[154:155], 0, s[14:15]
	v_cvt_pk_fp8_f32 v156, v62, v63 op_sel:[0,0,1]
	v_cvt_pk_fp8_f32 v157, v58, v59 op_sel:[0,0,1]
	v_lshl_add_u64 v[154:155], v[154:155], 0, s[20:21]
	v_lshl_add_u64 v[154:155], v[154:155], 0, s[4:5]
	v_lshl_add_u64 v[154:155], v[154:155], 0, v[134:135]
	global_store_dwordx2 v[154:155], v[156:157], off offset:-4096
	v_mov_b32_e32 v156, v193
	v_mov_b32_e32 v157, v193
	v_cvt_pk_fp8_f32 v156, v48, v49
	v_cvt_pk_fp8_f32 v157, v40, v41
	v_cvt_pk_fp8_f32 v156, v50, v51 op_sel:[0,0,1]
	v_cvt_pk_fp8_f32 v157, v42, v43 op_sel:[0,0,1]
	global_store_dwordx2 v[154:155], v[156:157], off offset:-3968
	v_mov_b32_e32 v156, v193
	v_mov_b32_e32 v157, v193
	v_cvt_pk_fp8_f32 v156, v52, v53
	v_cvt_pk_fp8_f32 v157, v44, v45
	v_mad_i64_i32 v[154:155], s[16:17], v148, s9, v[140:141]
	v_lshl_add_u64 v[154:155], v[154:155], 0, s[14:15]
	v_cvt_pk_fp8_f32 v156, v54, v55 op_sel:[0,0,1]
	v_cvt_pk_fp8_f32 v157, v46, v47 op_sel:[0,0,1]
	v_lshl_add_u64 v[154:155], v[154:155], 0, s[20:21]
	v_lshl_add_u64 v[154:155], v[154:155], 0, s[4:5]
	v_lshl_add_u64 v[154:155], v[154:155], 0, v[134:135]
	global_store_dwordx2 v[154:155], v[156:157], off offset:-4096
	v_mov_b32_e32 v156, v193
	v_mov_b32_e32 v157, v193
	v_cvt_pk_fp8_f32 v156, v32, v33
	v_cvt_pk_fp8_f32 v157, v24, v25
	v_cvt_pk_fp8_f32 v156, v34, v35 op_sel:[0,0,1]
	v_cvt_pk_fp8_f32 v157, v26, v27 op_sel:[0,0,1]
	global_store_dwordx2 v[154:155], v[156:157], off offset:-3968
	v_mov_b32_e32 v156, v193
	v_mov_b32_e32 v157, v193
	v_cvt_pk_fp8_f32 v156, v36, v37
	v_cvt_pk_fp8_f32 v157, v28, v29
	v_mad_i64_i32 v[154:155], s[16:17], v147, s9, v[140:141]
	v_lshl_add_u64 v[154:155], v[154:155], 0, s[14:15]
	v_cvt_pk_fp8_f32 v156, v38, v39 op_sel:[0,0,1]
	v_cvt_pk_fp8_f32 v157, v30, v31 op_sel:[0,0,1]
	v_lshl_add_u64 v[154:155], v[154:155], 0, s[20:21]
	v_lshl_add_u64 v[154:155], v[154:155], 0, s[4:5]
	v_lshl_add_u64 v[154:155], v[154:155], 0, v[134:135]
	global_store_dwordx2 v[154:155], v[156:157], off offset:-4096
	v_mov_b32_e32 v156, v193
	v_mov_b32_e32 v157, v193
	v_cvt_pk_fp8_f32 v156, v16, v17
	v_cvt_pk_fp8_f32 v157, v8, v9
	v_mad_i64_i32 v[140:141], s[16:17], v146, s9, v[140:141]
	v_cvt_pk_fp8_f32 v156, v18, v19 op_sel:[0,0,1]
	v_cvt_pk_fp8_f32 v157, v10, v11 op_sel:[0,0,1]
	v_lshl_add_u64 v[140:141], v[140:141], 0, s[14:15]
	v_lshl_add_u64 v[140:141], v[140:141], 0, s[20:21]
	v_lshl_add_u64 v[140:141], v[140:141], 0, s[4:5]
	global_store_dwordx2 v[154:155], v[156:157], off offset:-3968
	v_mov_b32_e32 v154, v193
	v_mov_b32_e32 v155, v193
	v_cvt_pk_fp8_f32 v154, v20, v21
	v_cvt_pk_fp8_f32 v155, v12, v13
	v_lshl_add_u64 v[140:141], v[140:141], 0, v[134:135]
	s_mov_b64 s[14:15], 0
	v_cvt_pk_fp8_f32 v154, v22, v23 op_sel:[0,0,1]
	v_cvt_pk_fp8_f32 v155, v14, v15 op_sel:[0,0,1]
	global_store_dwordx2 v[140:141], v[154:155], off offset:-4096
	v_mov_b32_e32 v154, v193
	v_mov_b32_e32 v155, v193
	v_cvt_pk_fp8_f32 v154, v4, v5
	v_cvt_pk_fp8_f32 v155, v0, v1
	v_cvt_pk_fp8_f32 v154, v6, v7 op_sel:[0,0,1]
	v_cvt_pk_fp8_f32 v155, v2, v3 op_sel:[0,0,1]
	global_store_dwordx2 v[140:141], v[154:155], off offset:-3968
